# GEMM K-loop LDS-DMA loads to SGPR-base form (drops 64-bit VALU address adds); attention vmcnt(4) wait moved next to the tile barrier
# baseline (speedup 1.0000x reference)
; #define PG8_STAGE(bufoff, gbase, voff) do { _Pragma("unroll") for (int _i = 0; _i < 2; ++_i) \
;         __builtin_amdgcn_global_load_lds((const unsigned*)((const char*)(gbase) + (voff)[_i]), (PG8_LAS unsigned*)(lds + (bufoff) + ldsw + _i * 8192), 16, 0, 0); } while (0)
; #define PG8_WAIT_V(n) asm volatile("s_waitcnt vmcnt(" #n ")" ::: "memory")
; #define PG8_BAR __builtin_amdgcn_s_barrier()
; template <class Epi, class Sched, bool ALIGN_EPI = false, bool SP2 = false>
; __device__ __forceinline__ void gemm_phase(PG8_LAS unsigned char* lds, const Gemm g, const Sched& S, const Epi& E, const int tid) {
;     const int wid = __builtin_amdgcn_readfirstlane(tid >> 6), lane = tid & 63, wr = wid >> 2, wc = wid & 3, fr = lane & 15, fq = lane >> 4;
;     const int K = g.K, nt = K / BK;
;     unsigned voffA[2], voffB[2];
; #pragma unroll
;     for (int i = 0; i < 2; ++i) { int R, C; stage_rc(tid * 16 + i * 8192, R, C); const int Rb = Epi::PERM ? ((R & ~31) + perm32(R & 31)) : R;
;         voffA[i] = (unsigned)(R * K + C) * 2u; voffB[i] = (unsigned)(Rb * K + C) * 2u; }
;     const size_t kstep = (size_t)(BK * 2);
;     const size_t hstep = (size_t)HALF * K * 2;
;     const size_t tstep = 2 * hstep;
;     const unsigned ldsw = (unsigned)wid * 1024u;
;     const int aoff = lds_byte(wr * 64 + fr, fq * 8), boff = lds_byte(wc * 32 + fr, fq * 8);
;     ...
;         PG8_STAGE(PG8_SB(0, 0), cB, voffB); PG8_STAGE(PG8_SB(0, 1), cB + hstep, voffB); PG8_STAGE(PG8_SA(0, 0), cA, voffA); PG8_STAGE(PG8_SA(0, 1), cA + hstep, voffA);
;         if (wr == 1) PG8_BAR;
;         PG8_WAIT_V(2); PG8_BAR;
;         PG8_STAGE(PG8_SB(1, 0), cB + kstep, voffB); PG8_STAGE(PG8_SA(1, 0), cA + kstep, voffA); PG8_STAGE(PG8_SB(1, 1), cB + hstep + kstep, voffB);
;         PG8_WAIT_V(6); PG8_BAR;
;     } else {
;         PG8_STAGE(PG8_SB(0, 0), cB, voffB); PG8_STAGE(PG8_SA(0, 0), cA, voffA); PG8_STAGE(PG8_SB(0, 1), cB + hstep, voffB); PG8_STAGE(PG8_SA(0, 1), cA + hstep, voffA);
;         if (wr == 1) PG8_BAR;
;         PG8_WAIT_V(4); PG8_BAR;
;         PG8_STAGE(PG8_SB(1, 0), cB + kstep, voffB); PG8_STAGE(PG8_SA(1, 0), cA + kstep, voffA); PG8_STAGE(PG8_SB(1, 1), cB + hstep + kstep, voffB);
;         PG8_WAIT_V(6); PG8_BAR;
;     }
.LBB0_216:
	s_add_u32 s8, s53, 0x10a00000
	s_addc_u32 s9, s52, 0
	s_add_u32 s10, s53, 0x3200000
	s_mov_b64 s[12:13], 0x80
	s_addc_u32 s11, s52, 0
	s_and_b32 s16, s1, 3
	s_add_i32 m0, s58, 0x18000
	v_lshl_add_u64 v[6:7], v[6:7], 0, s[12:13]
	s_lshl_b32 s17, s3, 13
	s_lshl_b32 s18, s16, 12
	s_waitcnt vmcnt(2)
	s_barrier
	global_load_lds_dwordx4 v[6:7], off
	v_lshl_add_u64 v[4:5], v[4:5], 0, s[12:13]
	s_add_i32 m0, s58, 0x1a000
	s_add_i32 s63, s58, 0x8000
	s_add_i32 s64, s58, 0xa000
	global_load_lds_dwordx4 v[4:5], off
	v_lshl_add_u64 v[0:1], v[0:1], 0, s[12:13]
	s_mov_b32 m0, s63
	s_add_u32 s14, s48, 0x40080
	global_load_lds_dwordx4 v[0:1], off
	v_lshl_add_u64 v[0:1], v[2:3], 0, s[12:13]
	s_mov_b32 m0, s64
	s_addc_u32 s15, s49, 0
	global_load_lds_dwordx4 v[0:1], off
	s_add_i32 m0, s58, 0x1c000
	global_load_lds_dwordx4 v130, s[14:15]
	s_add_i32 m0, s58, 0x1e000
	v_bfe_u32 v2, v8, 4, 2
	global_load_lds_dwordx4 v134, s[14:15]
	v_lshrrev_b32_e32 v0, 4, v8
	v_and_b32_e32 v1, 15, v8
	v_lshlrev_b32_e32 v3, 3, v2
	v_lshlrev_b32_e32 v2, 4, v2
	v_bitop3_b32 v0, s1, v0, 3 bitop3:0xa8
	s_sext_i32_i8 s76, s0
	v_lshl_or_b32 v148, s3, 6, v1
	v_lshl_or_b32 v1, v1, 6, v2
	v_lshlrev_b32_e32 v2, 2, v8
	v_cmp_eq_u32_e64 s[0:1], 0, v0
	v_lshlrev_b32_e32 v0, 14, v9
	v_and_b32_e32 v2, 32, v2
	v_and_b32_e32 v0, 0xffff8000, v0
	v_bitop3_b32 v4, v1, s17, v2 bitop3:0xde
	v_bitop3_b32 v149, s18, v1, v2 bitop3:0xf6
	v_lshl_add_u32 v0, v10, 11, v0
	v_and_b32_e32 v1, 1, v9
	v_lshl_or_b32 v0, v1, 6, v0
	v_lshl_add_u32 v136, v11, 1, v0
	v_lshlrev_b32_e32 v0, 14, v12
	v_and_b32_e32 v0, 0xffff8000, v0
	s_waitcnt vmcnt(6)
	s_cmpk_lt_u32 s2, 0x100
	v_lshl_add_u32 v0, v13, 11, v0
	v_and_b32_e32 v1, 1, v12
	s_cselect_b64 s[14:15], -1, 0
	v_lshl_or_b32 v0, v1, 6, v0
	s_add_i32 s66, 0, 0x10000
	s_add_i32 s67, 0, 0x14000
	v_lshl_or_b32 v150, s16, 5, v3
	s_ashr_i32 s65, s45, 31
	v_mov_b32_e32 v137, v131
	v_lshl_add_u32 v138, v14, 1, v0
	v_mov_b32_e32 v139, v131
	v_mov_b64_e32 v[140:141], 0x492
	v_mov_b64_e32 v[142:143], 0x491
	v_add_u32_e32 v151, s66, v149
	v_add_u32_e32 v152, s67, v149
	v_add_u32_e32 v153, 0, v4
	s_mov_b64 s[16:17], 0x1000
	s_mov_b64 s[18:19], 0x1200
	s_mov_b64 s[20:21], 0x1400
	s_mov_b64 s[22:23], 0x1600
	s_mov_b64 s[24:25], 0x80000
	s_mov_b32 s72, 0x80000
	s_mov_b64 s[26:27], 0x90000
	s_mov_b32 s73, 0x90000
	s_mov_b64 s[28:29], 0xa0000
	s_mov_b32 s74, 0xa0000
	s_mov_b64 s[30:31], 0xb0000
	s_mov_b32 s75, 0xb0000
	s_barrier
	s_branch .LBB0_219

; #define PG8_STAGE(bufoff, gbase, voff) do { _Pragma("unroll") for (int _i = 0; _i < 2; ++_i) \
;         __builtin_amdgcn_global_load_lds((const unsigned*)((const char*)(gbase) + (voff)[_i]), (PG8_LAS unsigned*)(lds + (bufoff) + ldsw + _i * 8192), 16, 0, 0); } while (0)
; #define PG8_LDA(dst, b, h) do { _Pragma("unroll") for (int m = 0; m < 4; ++m) _Pragma("unroll") for (int k = 0; k < 2; ++k) dst[m][k] = *(const PG8_LAS bf16x8*)(lds + PG8_SA(b, h) + aoff + m * 2048 + k * 1024); } while (0)
; #define PG8_LDB(dst, b, h) do { _Pragma("unroll") for (int n = 0; n < 2; ++n) _Pragma("unroll") for (int k = 0; k < 2; ++k) dst[n][k] = *(const PG8_LAS bf16x8*)(lds + PG8_SB(b, h) + boff + n * 2048 + k * 1024); } while (0)
; #define PG8_MMA(ai, bj, At, Bt) do { __builtin_amdgcn_s_setprio(1); _Pragma("unroll") for (int m = 0; m < 4; ++m) _Pragma("unroll") for (int n = 0; n < 2; ++n) _Pragma("unroll") for (int k = 0; k < 2; ++k) \
;         acc[ai][bj][m][n] = __builtin_amdgcn_mfma_f32_16x16x32_bf16(Bt[n][k], At[m][k], acc[ai][bj][m][n], 0, 0, 0); __builtin_amdgcn_s_setprio(0); } while (0)
; #define PG8_WAIT_V(n) asm volatile("s_waitcnt vmcnt(" #n ")" ::: "memory")
; #define PG8_WAIT_L(n) asm volatile("s_waitcnt lgkmcnt(" #n ")" ::: "memory")
; #define PG8_BAR __builtin_amdgcn_s_barrier()
; #define PG8_SCHED __builtin_amdgcn_sched_barrier(0)
; template <class Epi, class Sched, bool ALIGN_EPI = false, bool SP2 = false>
; __device__ __forceinline__ void gemm_phase(PG8_LAS unsigned char* lds, const Gemm g, const Sched& S, const Epi& E, const int tid) {
;     ...
;             PG8_LDB(B0, 0, 0); PG8_LDB(B1, 0, 1); PG8_SCHED; PG8_LDA(At, 0, 0); PG8_STAGE(PG8_SA(1, 1), a1 + hstep, voffA);
;             PG8_WAIT_V(8); PG8_WAIT_L(0); PG8_BAR; PG8_MMA(0, 0, At, B0); PG8_MMA(0, 1, At, B1); PG8_BAR; PG8_SCHED;
;             PG8_LDA(At, 0, 1); PG8_STAGE(PG8_SB(0, 0), b2, voffB); PG8_STAGE(PG8_SB(0, 1), b2 + hstep, voffB); PG8_STAGE(PG8_SA(0, 0), a2, voffA);
;             PG8_WAIT_V(8); PG8_WAIT_L(0); PG8_BAR; PG8_MMA(1, 0, At, B0); PG8_MMA(1, 1, At, B1); PG8_BAR; PG8_SCHED;
.LBB0_226:
	ds_read_b128 v[144:147], v151
	ds_read_b128 v[154:157], v151 offset:1024
	ds_read_b128 v[158:161], v151 offset:2048
	ds_read_b128 v[162:165], v151 offset:3072
	ds_read_b128 v[166:169], v152
	ds_read_b128 v[170:173], v152 offset:1024
	ds_read_b128 v[174:177], v152 offset:2048
	ds_read_b128 v[178:181], v152 offset:3072
	s_add_u32 s48, s46, 0xfffc0080
	s_addc_u32 s49, s47, -1
	s_cmp_eq_u32 s79, 12
	s_cselect_b32 s51, s33, s49
	s_cselect_b32 s50, s37, s48
	s_cselect_b32 s49, s35, s78
	s_cselect_b32 s48, s43, s77
	s_add_i32 m0, s58, 0xc000
	ds_read_b128 v[182:185], v153
	ds_read_b128 v[186:189], v153 offset:1024
	ds_read_b128 v[190:193], v153 offset:2048
	ds_read_b128 v[194:197], v153 offset:3072
	ds_read_b128 v[198:201], v153 offset:4096
	ds_read_b128 v[202:205], v153 offset:5120
	ds_read_b128 v[206:209], v153 offset:6144
	ds_read_b128 v[210:213], v153 offset:7168
	global_load_lds_dwordx4 v136, s[46:47]
	s_add_i32 m0, s58, 0xe000
	s_nop 0
	global_load_lds_dwordx4 v138, s[46:47]
	s_waitcnt vmcnt(8)
	s_waitcnt lgkmcnt(0)
	s_barrier
	s_setprio 1
	s_waitcnt lgkmcnt(0)
	v_mfma_f32_16x16x32_bf16 v[124:127], v[144:147], v[182:185], v[124:127]
	v_mfma_f32_16x16x32_bf16 v[120:123], v[158:161], v[182:185], v[120:123]
	v_mfma_f32_16x16x32_bf16 v[116:119], v[144:147], v[190:193], v[116:119]
	v_mfma_f32_16x16x32_bf16 v[108:111], v[158:161], v[190:193], v[108:111]
	v_mfma_f32_16x16x32_bf16 v[100:103], v[144:147], v[198:201], v[100:103]
	v_mfma_f32_16x16x32_bf16 v[92:95], v[158:161], v[198:201], v[92:95]
	v_mfma_f32_16x16x32_bf16 v[84:87], v[144:147], v[206:209], v[84:87]
	v_mfma_f32_16x16x32_bf16 v[76:79], v[158:161], v[206:209], v[76:79]
	v_mfma_f32_16x16x32_bf16 v[124:127], v[154:157], v[186:189], v[124:127]
	v_mfma_f32_16x16x32_bf16 v[120:123], v[162:165], v[186:189], v[120:123]
	v_mfma_f32_16x16x32_bf16 v[116:119], v[154:157], v[194:197], v[116:119]
	v_mfma_f32_16x16x32_bf16 v[108:111], v[162:165], v[194:197], v[108:111]
	v_mfma_f32_16x16x32_bf16 v[100:103], v[154:157], v[202:205], v[100:103]
	v_mfma_f32_16x16x32_bf16 v[92:95], v[162:165], v[202:205], v[92:95]
	v_mfma_f32_16x16x32_bf16 v[84:87], v[154:157], v[210:213], v[84:87]
	v_mfma_f32_16x16x32_bf16 v[76:79], v[162:165], v[210:213], v[76:79]
	s_setprio 0
	s_setprio 1
	v_mfma_f32_16x16x32_bf16 v[112:115], v[166:169], v[182:185], v[112:115]
	v_mfma_f32_16x16x32_bf16 v[104:107], v[174:177], v[182:185], v[104:107]
	v_mfma_f32_16x16x32_bf16 v[96:99], v[166:169], v[190:193], v[96:99]
	v_mfma_f32_16x16x32_bf16 v[88:91], v[174:177], v[190:193], v[88:91]
	v_mfma_f32_16x16x32_bf16 v[80:83], v[166:169], v[198:201], v[80:83]
	v_mfma_f32_16x16x32_bf16 v[72:75], v[174:177], v[198:201], v[72:75]
	v_mfma_f32_16x16x32_bf16 v[68:71], v[166:169], v[206:209], v[68:71]
	v_mfma_f32_16x16x32_bf16 v[64:67], v[174:177], v[206:209], v[64:67]
	v_mfma_f32_16x16x32_bf16 v[112:115], v[170:173], v[186:189], v[112:115]
	v_mfma_f32_16x16x32_bf16 v[104:107], v[178:181], v[186:189], v[104:107]
	v_mfma_f32_16x16x32_bf16 v[96:99], v[170:173], v[194:197], v[96:99]
	v_mfma_f32_16x16x32_bf16 v[88:91], v[178:181], v[194:197], v[88:91]
	v_mfma_f32_16x16x32_bf16 v[80:83], v[170:173], v[202:205], v[80:83]
	v_mfma_f32_16x16x32_bf16 v[72:75], v[178:181], v[202:205], v[72:75]
	v_mfma_f32_16x16x32_bf16 v[68:71], v[170:173], v[210:213], v[68:71]
	v_mfma_f32_16x16x32_bf16 v[64:67], v[178:181], v[210:213], v[64:67]
	s_setprio 0
	s_barrier
	s_add_i32 s80, s66, s57
	v_lshl_add_u64 v[214:215], s[48:49], 0, v[130:131]
	s_mov_b32 m0, s80
	ds_read_b128 v[182:185], v153 offset:16384
	ds_read_b128 v[186:189], v153 offset:17408
	ds_read_b128 v[190:193], v153 offset:18432
	ds_read_b128 v[194:197], v153 offset:19456
	ds_read_b128 v[198:201], v153 offset:20480
	ds_read_b128 v[202:205], v153 offset:21504
	ds_read_b128 v[206:209], v153 offset:22528
	ds_read_b128 v[210:213], v153 offset:23552
	global_load_lds_dwordx4 v[214:215], off
	s_add_i32 m0, s80, 0x2000
	s_add_u32 s80, s48, 0x40000
	v_lshl_add_u64 v[216:217], s[48:49], 0, v[134:135]
	s_addc_u32 s81, s49, 0
	s_add_i32 s82, s67, s57
	global_load_lds_dwordx4 v[216:217], off
	s_mov_b32 m0, s82
	v_lshl_add_u64 v[220:221], s[50:51], 0, v[132:133]
	global_load_lds_dwordx4 v130, s[80:81]
	s_add_i32 m0, s82, 0x2000
	s_nop 0
	global_load_lds_dwordx4 v134, s[80:81]
	v_lshl_add_u64 v[218:219], s[50:51], 0, v[128:129]
	s_mov_b32 m0, s58
	s_nop 0
	global_load_lds_dwordx4 v[218:219], off
	s_mov_b32 m0, s59
	s_nop 0
	global_load_lds_dwordx4 v[220:221], off
	s_waitcnt vmcnt(8)
	s_waitcnt lgkmcnt(0)
	s_barrier
; #define PG8_STAGE(bufoff, gbase, voff) do { _Pragma("unroll") for (int _i = 0; _i < 2; ++_i) \
;         __builtin_amdgcn_global_load_lds((const unsigned*)((const char*)(gbase) + (voff)[_i]), (PG8_LAS unsigned*)(lds + (bufoff) + ldsw + _i * 8192), 16, 0, 0); } while (0)
; #define PG8_LDA(dst, b, h) do { _Pragma("unroll") for (int m = 0; m < 4; ++m) _Pragma("unroll") for (int k = 0; k < 2; ++k) dst[m][k] = *(const PG8_LAS bf16x8*)(lds + PG8_SA(b, h) + aoff + m * 2048 + k * 1024); } while (0)
; #define PG8_LDB(dst, b, h) do { _Pragma("unroll") for (int n = 0; n < 2; ++n) _Pragma("unroll") for (int k = 0; k < 2; ++k) dst[n][k] = *(const PG8_LAS bf16x8*)(lds + PG8_SB(b, h) + boff + n * 2048 + k * 1024); } while (0)
; #define PG8_MMA(ai, bj, At, Bt) do { __builtin_amdgcn_s_setprio(1); _Pragma("unroll") for (int m = 0; m < 4; ++m) _Pragma("unroll") for (int n = 0; n < 2; ++n) _Pragma("unroll") for (int k = 0; k < 2; ++k) \
;         acc[ai][bj][m][n] = __builtin_amdgcn_mfma_f32_16x16x32_bf16(Bt[n][k], At[m][k], acc[ai][bj][m][n], 0, 0, 0); __builtin_amdgcn_s_setprio(0); } while (0)
; #define PG8_WAIT_V(n) asm volatile("s_waitcnt vmcnt(" #n ")" ::: "memory")
; #define PG8_WAIT_L(n) asm volatile("s_waitcnt lgkmcnt(" #n ")" ::: "memory")
; #define PG8_BAR __builtin_amdgcn_s_barrier()
; #define PG8_SCHED __builtin_amdgcn_sched_barrier(0)
; template <class Epi, class Sched, bool ALIGN_EPI = false, bool SP2 = false>
; __device__ __forceinline__ void gemm_phase(PG8_LAS unsigned char* lds, const Gemm g, const Sched& S, const Epi& E, const int tid) {
;     ...
;             PG8_WAIT_V(8); PG8_WAIT_L(0); PG8_BAR; PG8_MMA(1, 0, At, B0); PG8_MMA(1, 1, At, B1); PG8_BAR; PG8_SCHED;
;             PG8_LDB(B0, 1, 0); PG8_LDB(B1, 1, 1); PG8_SCHED; PG8_LDA(At, 1, 0); PG8_STAGE(PG8_SA(0, 1), a2 + hstep, voffA);
;             PG8_WAIT_V(8); PG8_WAIT_L(0); PG8_BAR; PG8_MMA(0, 0, At, B0); PG8_MMA(0, 1, At, B1); PG8_BAR; PG8_SCHED;
	s_setprio 1
	s_waitcnt lgkmcnt(0)
	v_mfma_f32_16x16x32_bf16 v[60:63], v[144:147], v[182:185], v[60:63]
	v_mfma_f32_16x16x32_bf16 v[56:59], v[158:161], v[182:185], v[56:59]
	v_mfma_f32_16x16x32_bf16 v[52:55], v[144:147], v[190:193], v[52:55]
	v_mfma_f32_16x16x32_bf16 v[44:47], v[158:161], v[190:193], v[44:47]
	v_mfma_f32_16x16x32_bf16 v[36:39], v[144:147], v[198:201], v[36:39]
	v_mfma_f32_16x16x32_bf16 v[28:31], v[158:161], v[198:201], v[28:31]
	v_mfma_f32_16x16x32_bf16 v[20:23], v[144:147], v[206:209], v[20:23]
	v_mfma_f32_16x16x32_bf16 v[12:15], v[158:161], v[206:209], v[12:15]
	v_mfma_f32_16x16x32_bf16 v[60:63], v[154:157], v[186:189], v[60:63]
	v_mfma_f32_16x16x32_bf16 v[56:59], v[162:165], v[186:189], v[56:59]
	v_mfma_f32_16x16x32_bf16 v[52:55], v[154:157], v[194:197], v[52:55]
	v_mfma_f32_16x16x32_bf16 v[44:47], v[162:165], v[194:197], v[44:47]
	v_mfma_f32_16x16x32_bf16 v[36:39], v[154:157], v[202:205], v[36:39]
	v_mfma_f32_16x16x32_bf16 v[28:31], v[162:165], v[202:205], v[28:31]
	v_mfma_f32_16x16x32_bf16 v[20:23], v[154:157], v[210:213], v[20:23]
	v_mfma_f32_16x16x32_bf16 v[12:15], v[162:165], v[210:213], v[12:15]
	s_setprio 0
	s_setprio 1
	v_mfma_f32_16x16x32_bf16 v[48:51], v[166:169], v[182:185], v[48:51]
	v_mfma_f32_16x16x32_bf16 v[40:43], v[174:177], v[182:185], v[40:43]
	v_mfma_f32_16x16x32_bf16 v[32:35], v[166:169], v[190:193], v[32:35]
	v_mfma_f32_16x16x32_bf16 v[24:27], v[174:177], v[190:193], v[24:27]
	v_mfma_f32_16x16x32_bf16 v[16:19], v[166:169], v[198:201], v[16:19]
	v_mfma_f32_16x16x32_bf16 v[8:11], v[174:177], v[198:201], v[8:11]
	v_mfma_f32_16x16x32_bf16 v[4:7], v[166:169], v[206:209], v[4:7]
	v_mfma_f32_16x16x32_bf16 v[0:3], v[174:177], v[206:209], v[0:3]
	v_mfma_f32_16x16x32_bf16 v[48:51], v[170:173], v[186:189], v[48:51]
	v_mfma_f32_16x16x32_bf16 v[40:43], v[178:181], v[186:189], v[40:43]
	v_mfma_f32_16x16x32_bf16 v[32:35], v[170:173], v[194:197], v[32:35]
	v_mfma_f32_16x16x32_bf16 v[24:27], v[178:181], v[194:197], v[24:27]
	v_mfma_f32_16x16x32_bf16 v[16:19], v[170:173], v[202:205], v[16:19]
	v_mfma_f32_16x16x32_bf16 v[8:11], v[178:181], v[202:205], v[8:11]
	v_mfma_f32_16x16x32_bf16 v[4:7], v[170:173], v[210:213], v[4:7]
	v_mfma_f32_16x16x32_bf16 v[0:3], v[178:181], v[210:213], v[0:3]
	s_setprio 0
	s_barrier
	s_add_i32 s80, 0, 0x18000
	s_add_i32 s81, 0, 0x1c000
	v_add_u32_e32 v162, s80, v149
	v_add_u32_e32 v178, s81, v149
	ds_read_b128 v[144:147], v162
	ds_read_b128 v[154:157], v162 offset:1024
	ds_read_b128 v[158:161], v162 offset:2048
	ds_read_b128 v[162:165], v162 offset:3072
	ds_read_b128 v[166:169], v178
	ds_read_b128 v[170:173], v178 offset:1024
	ds_read_b128 v[174:177], v178 offset:2048
	ds_read_b128 v[178:181], v178 offset:3072
	s_add_u32 s50, s50, 0x40000
	s_addc_u32 s51, s51, 0
	s_mov_b32 m0, s60
	ds_read_b128 v[182:185], v153 offset:32768
	ds_read_b128 v[186:189], v153 offset:33792
	ds_read_b128 v[190:193], v153 offset:34816
	ds_read_b128 v[194:197], v153 offset:35840
	ds_read_b128 v[198:201], v153 offset:36864
	ds_read_b128 v[202:205], v153 offset:37888
	ds_read_b128 v[206:209], v153 offset:38912
	ds_read_b128 v[210:213], v153 offset:39936
	global_load_lds_dwordx4 v128, s[50:51]
	v_lshl_add_u64 v[222:223], s[50:51], 0, v[132:133]
	s_mov_b32 m0, s61
	s_nop 0
	global_load_lds_dwordx4 v[222:223], off
	s_waitcnt vmcnt(8)
	s_waitcnt lgkmcnt(0)
	s_barrier
	s_setprio 1
	s_waitcnt lgkmcnt(0)
	v_mfma_f32_16x16x32_bf16 v[124:127], v[144:147], v[182:185], v[124:127]
	v_mfma_f32_16x16x32_bf16 v[120:123], v[158:161], v[182:185], v[120:123]
	v_mfma_f32_16x16x32_bf16 v[116:119], v[144:147], v[190:193], v[116:119]
	v_mfma_f32_16x16x32_bf16 v[108:111], v[158:161], v[190:193], v[108:111]
	v_mfma_f32_16x16x32_bf16 v[100:103], v[144:147], v[198:201], v[100:103]
	v_mfma_f32_16x16x32_bf16 v[92:95], v[158:161], v[198:201], v[92:95]
	v_mfma_f32_16x16x32_bf16 v[84:87], v[144:147], v[206:209], v[84:87]
	v_mfma_f32_16x16x32_bf16 v[76:79], v[158:161], v[206:209], v[76:79]
	v_mfma_f32_16x16x32_bf16 v[124:127], v[154:157], v[186:189], v[124:127]
	v_mfma_f32_16x16x32_bf16 v[120:123], v[162:165], v[186:189], v[120:123]
	v_mfma_f32_16x16x32_bf16 v[116:119], v[154:157], v[194:197], v[116:119]
	v_mfma_f32_16x16x32_bf16 v[108:111], v[162:165], v[194:197], v[108:111]
	v_mfma_f32_16x16x32_bf16 v[100:103], v[154:157], v[202:205], v[100:103]
	v_mfma_f32_16x16x32_bf16 v[92:95], v[162:165], v[202:205], v[92:95]
	v_mfma_f32_16x16x32_bf16 v[84:87], v[154:157], v[210:213], v[84:87]
	v_mfma_f32_16x16x32_bf16 v[76:79], v[162:165], v[210:213], v[76:79]
	s_setprio 0
	s_setprio 1
	v_mfma_f32_16x16x32_bf16 v[112:115], v[166:169], v[182:185], v[112:115]
	v_mfma_f32_16x16x32_bf16 v[104:107], v[174:177], v[182:185], v[104:107]
	v_mfma_f32_16x16x32_bf16 v[96:99], v[166:169], v[190:193], v[96:99]
	v_mfma_f32_16x16x32_bf16 v[88:91], v[174:177], v[190:193], v[88:91]
	v_mfma_f32_16x16x32_bf16 v[80:83], v[166:169], v[198:201], v[80:83]
	v_mfma_f32_16x16x32_bf16 v[72:75], v[174:177], v[198:201], v[72:75]
	v_mfma_f32_16x16x32_bf16 v[68:71], v[166:169], v[206:209], v[68:71]
	v_mfma_f32_16x16x32_bf16 v[64:67], v[174:177], v[206:209], v[64:67]
	v_mfma_f32_16x16x32_bf16 v[112:115], v[170:173], v[186:189], v[112:115]
	v_mfma_f32_16x16x32_bf16 v[104:107], v[178:181], v[186:189], v[104:107]
	v_mfma_f32_16x16x32_bf16 v[96:99], v[170:173], v[194:197], v[96:99]
	v_mfma_f32_16x16x32_bf16 v[88:91], v[178:181], v[194:197], v[88:91]
	v_mfma_f32_16x16x32_bf16 v[80:83], v[170:173], v[202:205], v[80:83]
	v_mfma_f32_16x16x32_bf16 v[72:75], v[178:181], v[202:205], v[72:75]
	v_mfma_f32_16x16x32_bf16 v[68:71], v[170:173], v[210:213], v[68:71]
	v_mfma_f32_16x16x32_bf16 v[64:67], v[178:181], v[210:213], v[64:67]
	s_setprio 0
	s_barrier
; #define PG8_STAGE(bufoff, gbase, voff) do { _Pragma("unroll") for (int _i = 0; _i < 2; ++_i) \
;         __builtin_amdgcn_global_load_lds((const unsigned*)((const char*)(gbase) + (voff)[_i]), (PG8_LAS unsigned*)(lds + (bufoff) + ldsw + _i * 8192), 16, 0, 0); } while (0)
; #define PG8_LDA(dst, b, h) do { _Pragma("unroll") for (int m = 0; m < 4; ++m) _Pragma("unroll") for (int k = 0; k < 2; ++k) dst[m][k] = *(const PG8_LAS bf16x8*)(lds + PG8_SA(b, h) + aoff + m * 2048 + k * 1024); } while (0)
; #define PG8_MMA(ai, bj, At, Bt) do { __builtin_amdgcn_s_setprio(1); _Pragma("unroll") for (int m = 0; m < 4; ++m) _Pragma("unroll") for (int n = 0; n < 2; ++n) _Pragma("unroll") for (int k = 0; k < 2; ++k) \
;         acc[ai][bj][m][n] = __builtin_amdgcn_mfma_f32_16x16x32_bf16(Bt[n][k], At[m][k], acc[ai][bj][m][n], 0, 0, 0); __builtin_amdgcn_s_setprio(0); } while (0)
; #define PG8_WAIT_V(n) asm volatile("s_waitcnt vmcnt(" #n ")" ::: "memory")
; #define PG8_WAIT_L(n) asm volatile("s_waitcnt lgkmcnt(" #n ")" ::: "memory")
; #define PG8_BAR __builtin_amdgcn_s_barrier()
; #define PG8_SCHED __builtin_amdgcn_sched_barrier(0)
; template <class Epi, class Sched, bool ALIGN_EPI = false, bool SP2 = false>
; __device__ __forceinline__ void gemm_phase(PG8_LAS unsigned char* lds, const Gemm g, const Sched& S, const Epi& E, const int tid) {
;     ...
;         for (int t = 0; t < nt; t += 2) {
;             const bool last = (t == nt - 2);
;     ...
;             PG8_LDA(At, 1, 1); PG8_STAGE(PG8_SB(1, 0), b3, voffB); PG8_STAGE(PG8_SB(1, 1), b3 + hstep, voffB); PG8_STAGE(PG8_SA(1, 0), a3, voffA);
;             PG8_WAIT_V(8); PG8_WAIT_L(0); PG8_BAR; PG8_MMA(1, 0, At, B0); PG8_MMA(1, 1, At, B1); PG8_BAR; PG8_SCHED;
	s_add_i32 s50, s80, s57
	v_lshl_add_u64 v[214:215], v[214:215], 0, s[12:13]
	s_mov_b32 m0, s50
	ds_read_b128 v[182:185], v153 offset:49152
	ds_read_b128 v[186:189], v153 offset:50176
	ds_read_b128 v[190:193], v153 offset:51200
	ds_read_b128 v[194:197], v153 offset:52224
	ds_read_b128 v[198:201], v153 offset:53248
	ds_read_b128 v[202:205], v153 offset:54272
	ds_read_b128 v[206:209], v153 offset:55296
	ds_read_b128 v[210:213], v153 offset:56320
	global_load_lds_dwordx4 v[214:215], off
	s_add_i32 m0, s50, 0x2000
	s_add_u32 s48, s48, 0x40080
	v_lshl_add_u64 v[214:215], v[216:217], 0, s[12:13]
	s_addc_u32 s49, s49, 0
	s_add_i32 s50, s81, s57
	global_load_lds_dwordx4 v[214:215], off
	s_mov_b32 m0, s50
	s_nop 0
	global_load_lds_dwordx4 v130, s[48:49]
	s_add_i32 m0, s50, 0x2000
	s_nop 0
	global_load_lds_dwordx4 v134, s[48:49]
	v_lshl_add_u64 v[214:215], v[218:219], 0, s[12:13]
	s_mov_b32 m0, s63
	s_nop 0
	global_load_lds_dwordx4 v[214:215], off
	v_lshl_add_u64 v[214:215], v[220:221], 0, s[12:13]
	s_mov_b32 m0, s64
	s_nop 0
	global_load_lds_dwordx4 v[214:215], off
	s_waitcnt vmcnt(8)
	s_waitcnt lgkmcnt(0)
	s_barrier
	s_setprio 1
	s_waitcnt lgkmcnt(0)
	v_mfma_f32_16x16x32_bf16 v[60:63], v[144:147], v[182:185], v[60:63]
	v_mfma_f32_16x16x32_bf16 v[56:59], v[158:161], v[182:185], v[56:59]
	v_mfma_f32_16x16x32_bf16 v[52:55], v[144:147], v[190:193], v[52:55]
	v_mfma_f32_16x16x32_bf16 v[44:47], v[158:161], v[190:193], v[44:47]
	v_mfma_f32_16x16x32_bf16 v[36:39], v[144:147], v[198:201], v[36:39]
	v_mfma_f32_16x16x32_bf16 v[28:31], v[158:161], v[198:201], v[28:31]
	v_mfma_f32_16x16x32_bf16 v[20:23], v[144:147], v[206:209], v[20:23]
	v_mfma_f32_16x16x32_bf16 v[12:15], v[158:161], v[206:209], v[12:15]
	v_mfma_f32_16x16x32_bf16 v[60:63], v[154:157], v[186:189], v[60:63]
	v_mfma_f32_16x16x32_bf16 v[56:59], v[162:165], v[186:189], v[56:59]
	v_mfma_f32_16x16x32_bf16 v[52:55], v[154:157], v[194:197], v[52:55]
	v_mfma_f32_16x16x32_bf16 v[44:47], v[162:165], v[194:197], v[44:47]
	v_mfma_f32_16x16x32_bf16 v[36:39], v[154:157], v[202:205], v[36:39]
	v_mfma_f32_16x16x32_bf16 v[28:31], v[162:165], v[202:205], v[28:31]
	v_mfma_f32_16x16x32_bf16 v[20:23], v[154:157], v[210:213], v[20:23]
	v_mfma_f32_16x16x32_bf16 v[12:15], v[162:165], v[210:213], v[12:15]
	s_setprio 0
	s_setprio 1
	v_mfma_f32_16x16x32_bf16 v[48:51], v[166:169], v[182:185], v[48:51]
	v_mfma_f32_16x16x32_bf16 v[40:43], v[174:177], v[182:185], v[40:43]
	v_mfma_f32_16x16x32_bf16 v[32:35], v[166:169], v[190:193], v[32:35]
	v_mfma_f32_16x16x32_bf16 v[24:27], v[174:177], v[190:193], v[24:27]
	v_mfma_f32_16x16x32_bf16 v[16:19], v[166:169], v[198:201], v[16:19]
	v_mfma_f32_16x16x32_bf16 v[8:11], v[174:177], v[198:201], v[8:11]
	v_mfma_f32_16x16x32_bf16 v[4:7], v[166:169], v[206:209], v[4:7]
	v_mfma_f32_16x16x32_bf16 v[0:3], v[174:177], v[206:209], v[0:3]
	v_mfma_f32_16x16x32_bf16 v[48:51], v[170:173], v[186:189], v[48:51]
	v_mfma_f32_16x16x32_bf16 v[40:43], v[178:181], v[186:189], v[40:43]
	v_mfma_f32_16x16x32_bf16 v[32:35], v[170:173], v[194:197], v[32:35]
	v_mfma_f32_16x16x32_bf16 v[24:27], v[178:181], v[194:197], v[24:27]
	v_mfma_f32_16x16x32_bf16 v[16:19], v[170:173], v[202:205], v[16:19]
	v_mfma_f32_16x16x32_bf16 v[8:11], v[178:181], v[202:205], v[8:11]
	v_mfma_f32_16x16x32_bf16 v[4:7], v[170:173], v[210:213], v[4:7]
	v_mfma_f32_16x16x32_bf16 v[0:3], v[178:181], v[210:213], v[0:3]
	s_setprio 0
	s_barrier
	s_add_i32 s79, s79, 2
	s_add_u32 s46, s46, 0x100
	s_addc_u32 s47, s47, 0
	s_add_u32 s77, s77, 0x100
	s_addc_u32 s78, s78, 0
	s_cmp_gt_u32 s79, 13
	s_cbranch_scc0 .LBB0_226
	s_and_b64 vcc, exec, s[14:15]
	s_cbranch_vccz .LBB0_231
	s_barrier
	v_lshl_add_u32 v146, s42, 8, v148
	s_cmp_gt_i32 s76, 7
	s_mov_b64 s[42:43], -1
	s_cbranch_scc1 .LBB0_232

; #define SBAR() __builtin_amdgcn_sched_barrier(0)
; #define PK4(P, BASE, OUT) do { u32x4 w = {cvtpk(P[BASE + 0], P[BASE + 1]), cvtpk(P[BASE + 2], P[BASE + 3]), cvtpk(P[BASE + 4], P[BASE + 5]), cvtpk(P[BASE + 6], P[BASE + 7])}; \
;     OUT = *reinterpret_cast<bf16x8*>(&w); } while (0)
; __device__ __forceinline__ void finishSM(f32x16& p0, f32x16& p1, float alpha, float& l_reg, bf16x8& pa0, bf16x8& pa1, bf16x8& pa2, bf16x8& pa3) {
;   for (int r = 0; r < 16; ++r) p1[r] = __builtin_amdgcn_exp2f(p1[r]);
;   float ps = 0; for (int r = 0; r < 16; ++r) ps += p0[r]; for (int r = 0; r < 16; ++r) ps += p1[r];
;   asm volatile("" : "+v"(ps));
;   l_reg = l_reg * alpha + ps;
;     ...
;   PK4(p0, 0, pa0); PK4(p0, 8, pa1); PK4(p1, 0, pa2); PK4(p1, 8, pa3);
;     ...
; }
; __device__ __forceinline__ void qkt(f32x16& p0, f32x16& p1, const bf16* Ks, const bf16x8* qr, int r32, int hi) {
;   p0 = f32x16{}; p1 = f32x16{};
;   for (int d0 = 0; d0 < 8; ++d0) { int cb = (d0 * 16 + hi * 8) * 2;
;     bf16x8 b0 = *reinterpret_cast<const bf16x8*>((const char*)Ks + KSWZ(r32, cb));
;     bf16x8 b1 = *reinterpret_cast<const bf16x8*>((const char*)Ks + KSWZ(32 + r32, cb));
;     p0 = __builtin_amdgcn_mfma_f32_32x32x16_bf16(b0, qr[d0], p0, 0, 0, 0);
;     p1 = __builtin_amdgcn_mfma_f32_32x32x16_bf16(b1, qr[d0], p1, 0, 0, 0); }
; }
; template <typename TQ> ...
;     ...
;   for (int j = 1; j + 1 < NT; j += 2) {
;     SBAR(); qkt(pB0, pB1, (const bf16*)(K_lds + (j & 3) * (int)SHM_K), qr, r32, hi);
;     finishSM(pA0, pA1, alA, l_reg, pa0, pa1, pa2, pa3); SBAR();
;     DMA_TILE(j + 2, (j + 2) & 3); SBAR();
;     pv_d0(o, vb0 + ((j - 1) & 3) * (int)SHM_V, pa0, pa1, pa2, pa3); partialSM<true>(pB0, pB1, m_reg, mnB, alB);
.LBB0_461:
	s_mov_b32 s40, s33
	s_addk_i32 s33, 0xc000
	s_and_b32 s42, s33, 0xc000
	s_add_i32 s33, s57, s42
	v_add_u32_e32 v84, s33, v178
	ds_read_b128 v[80:83], v84
	ds_read_b128 v[84:87], v84 offset:8192
	v_add_u32_e32 v202, s33, v179
	ds_read_b128 v[198:201], v202
	ds_read_b128 v[202:205], v202 offset:8192
	v_add_u32_e32 v206, s33, v181
	s_waitcnt lgkmcnt(3)
	v_mfma_f32_32x32x16_bf16 v[96:111], v[80:83], v[136:139], 0
	v_add_u32_e32 v214, s33, v182
	v_exp_f32_e32 v238, v64
	v_add_f32_e32 v64, 0, v196
	v_add_f32_e32 v64, v197, v64
	v_add_u32_e32 v222, s33, v183
	v_add_f32_e32 v64, v193, v64
	v_add_f32_e32 v64, v195, v64
	s_waitcnt lgkmcnt(2)
	v_mfma_f32_32x32x16_bf16 v[80:95], v[84:87], v[136:139], 0
	v_add_f32_e32 v64, v191, v64
	v_add_f32_e32 v64, v194, v64
	v_add_f32_e32 v64, v190, v64
	v_add_f32_e32 v64, v192, v64
	v_add_f32_e32 v64, v169, v64
	v_add_f32_e32 v64, v171, v64
	v_add_u32_e32 v226, s33, v184
	s_waitcnt lgkmcnt(1)
	v_mfma_f32_32x32x16_bf16 v[96:111], v[198:201], v[140:143], v[96:111]
	v_add_f32_e32 v64, v167, v64
	v_add_f32_e32 v64, v170, v64
	v_add_f32_e32 v64, v165, v64
	v_add_f32_e32 v64, v168, v64
	v_add_f32_e32 v64, v164, v64
	v_add_f32_e32 v64, v166, v64
	v_exp_f32_e32 v239, v68
	s_waitcnt lgkmcnt(0)
	v_mfma_f32_32x32x16_bf16 v[80:95], v[202:205], v[140:143], v[80:95]
	v_add_u32_e32 v202, s33, v180
	ds_read_b128 v[198:201], v202
	ds_read_b128 v[202:205], v202 offset:8192
	v_add_f32_e32 v64, v238, v64
	v_exp_f32_e32 v240, v69
	v_add_u32_e32 v234, s33, v185
	v_exp_f32_e32 v241, v70
	v_exp_f32_e32 v242, v71
	s_waitcnt lgkmcnt(1)
	v_mfma_f32_32x32x16_bf16 v[96:111], v[198:201], v[132:135], v[96:111]
	ds_read_b128 v[198:201], v206
	ds_read_b128 v[206:209], v206 offset:8192
	ds_read_b128 v[210:213], v214
	ds_read_b128 v[214:217], v214 offset:8192
	ds_read_b128 v[218:221], v222
	ds_read_b128 v[222:225], v222 offset:8192
	v_exp_f32_e32 v243, v76
	v_exp_f32_e32 v244, v77
	v_exp_f32_e32 v245, v78
	v_exp_f32_e32 v79, v79
	s_waitcnt lgkmcnt(6)
	v_mfma_f32_32x32x16_bf16 v[80:95], v[202:205], v[132:135], v[80:95]
	ds_read_b128 v[202:205], v226
	ds_read_b128 v[226:229], v226 offset:8192
	ds_read_b128 v[230:233], v234
	ds_read_b128 v[234:237], v234 offset:8192
	s_waitcnt lgkmcnt(9)
	v_mfma_f32_32x32x16_bf16 v[96:111], v[198:201], v[128:131], v[96:111]
	v_exp_f32_e32 v199, v65
	v_exp_f32_e32 v200, v66
	v_exp_f32_e32 v201, v67
	v_add_f32_e32 v64, v199, v64
	v_add_f32_e32 v64, v200, v64
	v_add_f32_e32 v64, v201, v64
	s_waitcnt lgkmcnt(8)
	v_mfma_f32_32x32x16_bf16 v[80:95], v[206:209], v[128:131], v[80:95]
	v_exp_f32_e32 v206, v72
	v_add_f32_e32 v64, v239, v64
	v_exp_f32_e32 v207, v73
	v_add_f32_e32 v64, v240, v64
	v_exp_f32_e32 v208, v74
	v_add_f32_e32 v64, v241, v64
	v_exp_f32_e32 v209, v75
	s_waitcnt lgkmcnt(7)
	v_mfma_f32_32x32x16_bf16 v[96:111], v[210:213], v[124:127], v[96:111]
	v_add_f32_e32 v64, v242, v64
	v_add_f32_e32 v64, v206, v64
	v_add_f32_e32 v64, v207, v64
	v_add_f32_e32 v64, v208, v64
	v_add_f32_e32 v64, v209, v64
	v_add_f32_e32 v64, v243, v64
	v_add_f32_e32 v64, v244, v64
	s_waitcnt lgkmcnt(6)
	v_mfma_f32_32x32x16_bf16 v[80:95], v[214:217], v[124:127], v[80:95]
	v_add_f32_e32 v64, v245, v64
	v_add_f32_e32 v198, v79, v64
	v_cvt_pk_bf16_f32 v64, v196, v197
	v_cvt_pk_bf16_f32 v65, v193, v195
	v_cvt_pk_bf16_f32 v66, v191, v194
	v_cvt_pk_bf16_f32 v67, v190, v192
	s_waitcnt lgkmcnt(5)
	v_mfma_f32_32x32x16_bf16 v[96:111], v[218:221], v[120:123], v[96:111]
	v_cvt_pk_bf16_f32 v68, v169, v171
	v_cvt_pk_bf16_f32 v69, v167, v170
	v_cvt_pk_bf16_f32 v70, v165, v168
	v_cvt_pk_bf16_f32 v71, v164, v166
	v_cvt_pk_bf16_f32 v72, v238, v199
	v_cvt_pk_bf16_f32 v73, v200, v201
	v_cvt_pk_bf16_f32 v74, v239, v240
	s_waitcnt lgkmcnt(4)
	v_mfma_f32_32x32x16_bf16 v[80:95], v[222:225], v[120:123], v[80:95]
	v_cvt_pk_bf16_f32 v75, v241, v242
	v_cvt_pk_bf16_f32 v76, v206, v207
	v_cvt_pk_bf16_f32 v77, v208, v209
	v_cvt_pk_bf16_f32 v78, v243, v244
	v_cvt_pk_bf16_f32 v79, v245, v79
	s_waitcnt lgkmcnt(3)
	v_mfma_f32_32x32x16_bf16 v[96:111], v[202:205], v[116:119], v[96:111]
	s_add_i32 s33, s40, 0x8000
	s_and_b32 s43, s33, 0xc000
	v_add_u32_e32 v199, s43, v176
	ds_read_b64_tr_b16 v[190:191], v199 offset:0
	ds_read_b64_tr_b16 v[192:193], v199 offset:0x800
	ds_read_b64_tr_b16 v[194:195], v199 offset:0x1000
	ds_read_b64_tr_b16 v[196:197], v199 offset:0x1800
	s_waitcnt lgkmcnt(6)
	v_mfma_f32_32x32x16_bf16 v[80:95], v[226:229], v[116:119], v[80:95]
	ds_read_b64_tr_b16 v[200:201], v199 offset:0x2000
	ds_read_b64_tr_b16 v[202:203], v199 offset:0x2800
	ds_read_b64_tr_b16 v[204:205], v199 offset:0x3000
	ds_read_b64_tr_b16 v[206:207], v199 offset:0x3800
	s_add_i32 s74, s40, 0x4000
	s_and_b32 s74, s74, 0xc000
	s_add_u32 s98, s38, s22
	s_addc_u32 s99, s39, s23
	s_add_i32 s41, s67, s74
	s_add_u32 s100, s38, s24
	s_addc_u32 s101, s39, s25
	s_mov_b32 m0, s41
	s_add_i32 s74, s72, s74
	global_load_lds_dwordx4 v156, s[98:99]
	s_waitcnt lgkmcnt(9)
	v_mfma_f32_32x32x16_bf16 v[96:111], v[230:233], v[112:115], v[96:111]
	s_add_i32 m0, s41, 0x2000
	s_nop 0
	global_load_lds_dwordx4 v158, s[98:99]
	s_mov_b32 m0, s74
	s_nop 0
	global_load_lds_dwordx4 v162, s[100:101]
	s_waitcnt lgkmcnt(8)
	v_mfma_f32_32x32x16_bf16 v[80:95], v[234:237], v[112:115], v[80:95]
	s_add_i32 m0, s74, 0x2000
	s_nop 0
	global_load_lds_dwordx4 v160, s[100:101]
	s_nop 0
	s_waitcnt lgkmcnt(6)
; #define SBAR() __builtin_amdgcn_sched_barrier(0)
; #define PUBLISH(n) do { asm volatile("s_waitcnt vmcnt(" #n ")" ::: "memory"); asm volatile("s_waitcnt lgkmcnt(0)" ::: "memory"); __builtin_amdgcn_s_barrier(); SBAR(); } while (0)
; template <int D0> __device__ __forceinline__ void pv_one(f32x16& od, int vb, bf16x8 pa0, bf16x8 pa1, bf16x8 pa2, bf16x8 pa3) {
;   const s16x4 l0 = tr_read<v_rd_off(D0, 0, 0)>(vb), h0 = tr_read<v_rd_off(D0, 0, 1)>(vb), l1 = tr_read<v_rd_off(D0, 1, 0)>(vb), h1 = tr_read<v_rd_off(D0, 1, 1)>(vb);
;   const s16x4 l2 = tr_read<v_rd_off(D0, 2, 0)>(vb), h2 = tr_read<v_rd_off(D0, 2, 1)>(vb), l3 = tr_read<v_rd_off(D0, 3, 0)>(vb), h3 = tr_read<v_rd_off(D0, 3, 1)>(vb);
;   asm volatile("s_waitcnt lgkmcnt(0)" ::: "memory"); SBAR();
;     ...
;   od = __builtin_amdgcn_mfma_f32_32x32x16_bf16(pa0, PK(l0, h0), od, 0, 0, 0);
;   od = __builtin_amdgcn_mfma_f32_32x32x16_bf16(pa1, PK(l1, h1), od, 0, 0, 0);
;   od = __builtin_amdgcn_mfma_f32_32x32x16_bf16(pa2, PK(l2, h2), od, 0, 0, 0);
;   od = __builtin_amdgcn_mfma_f32_32x32x16_bf16(pa3, PK(l3, h3), od, 0, 0, 0);
;     ...
; }
; __device__ __forceinline__ void pv_d0(f32x16* o, int vb, bf16x8 pa0, bf16x8 pa1, bf16x8 pa2, bf16x8 pa3) {
;   pv_one<0>(o[0], vb, pa0, pa1, pa2, pa3); pv_one<1>(o[1], vb, pa0, pa1, pa2, pa3); pv_one<2>(o[2], vb, pa0, pa1, pa2, pa3); pv_one<3>(o[3], vb, pa0, pa1, pa2, pa3);
; }
; template <typename TQ> ...
;     ...
;     PUBLISH(4);
;     SBAR(); qkt(pA0, pA1, (const bf16*)(K_lds + ((j + 1) & 3) * (int)SHM_K), qr, r32, hi);
;     finishSM(pB0, pB1, alB, l_reg, pa0, pa1, pa2, pa3); SBAR();
;     if (j + 3 < NT) { DMA_TILE(j + 3, (j + 3) & 3); } SBAR();
	v_mfma_f32_32x32x16_bf16 v[48:63], v[64:67], v[190:193], v[48:63]
	v_exp_f32_e32 v232, v96
	ds_read_b64_tr_b16 v[190:191], v199 offset:0x200
	ds_read_b64_tr_b16 v[192:193], v199 offset:0xa00
	s_waitcnt lgkmcnt(6)
	v_mfma_f32_32x32x16_bf16 v[48:63], v[68:71], v[194:197], v[48:63]
	v_exp_f32_e32 v233, v97
	ds_read_b64_tr_b16 v[194:195], v199 offset:0x1200
	ds_read_b64_tr_b16 v[196:197], v199 offset:0x1a00
	s_waitcnt lgkmcnt(6)
	v_mfma_f32_32x32x16_bf16 v[48:63], v[72:75], v[200:203], v[48:63]
	v_exp_f32_e32 v234, v98
	ds_read_b64_tr_b16 v[200:201], v199 offset:0x2200
	ds_read_b64_tr_b16 v[202:203], v199 offset:0x2a00
	ds_read_b64_tr_b16 v[208:209], v199 offset:0x3200
	ds_read_b64_tr_b16 v[210:211], v199 offset:0x3a00
	s_waitcnt lgkmcnt(8)
	v_mfma_f32_32x32x16_bf16 v[48:63], v[76:79], v[204:207], v[48:63]
	v_exp_f32_e32 v235, v99
	s_waitcnt lgkmcnt(6)
	v_mfma_f32_32x32x16_bf16 v[32:47], v[64:67], v[190:193], v[32:47]
	v_exp_f32_e32 v236, v100
	ds_read_b64_tr_b16 v[190:191], v199 offset:0x400
	ds_read_b64_tr_b16 v[192:193], v199 offset:0xc00
	s_waitcnt lgkmcnt(6)
	v_mfma_f32_32x32x16_bf16 v[32:47], v[68:71], v[194:197], v[32:47]
	v_exp_f32_e32 v237, v101
	ds_read_b64_tr_b16 v[194:195], v199 offset:0x1400
	ds_read_b64_tr_b16 v[196:197], v199 offset:0x1c00
	s_waitcnt lgkmcnt(6)
	v_mfma_f32_32x32x16_bf16 v[32:47], v[72:75], v[200:203], v[32:47]
	v_exp_f32_e32 v238, v102
	ds_read_b64_tr_b16 v[200:201], v199 offset:0x2400
	ds_read_b64_tr_b16 v[202:203], v199 offset:0x2c00
	ds_read_b64_tr_b16 v[204:205], v199 offset:0x3400
	ds_read_b64_tr_b16 v[206:207], v199 offset:0x3c00
	s_waitcnt lgkmcnt(8)
	v_mfma_f32_32x32x16_bf16 v[32:47], v[76:79], v[208:211], v[32:47]
	v_exp_f32_e32 v239, v103
	v_exp_f32_e32 v240, v104
	s_waitcnt lgkmcnt(6)
	v_mfma_f32_32x32x16_bf16 v[16:31], v[64:67], v[190:193], v[16:31]
	v_exp_f32_e32 v241, v105
	ds_read_b64_tr_b16 v[190:191], v199 offset:0x600
	ds_read_b64_tr_b16 v[192:193], v199 offset:0xe00
	s_waitcnt lgkmcnt(6)
	v_mfma_f32_32x32x16_bf16 v[16:31], v[68:71], v[194:197], v[16:31]
	v_exp_f32_e32 v242, v106
	ds_read_b64_tr_b16 v[194:195], v199 offset:0x1600
	ds_read_b64_tr_b16 v[196:197], v199 offset:0x1e00
	s_waitcnt lgkmcnt(6)
	v_mfma_f32_32x32x16_bf16 v[16:31], v[72:75], v[200:203], v[16:31]
	v_exp_f32_e32 v243, v107
	ds_read_b64_tr_b16 v[200:201], v199 offset:0x2600
	ds_read_b64_tr_b16 v[202:203], v199 offset:0x2e00
	ds_read_b64_tr_b16 v[208:209], v199 offset:0x3600
	ds_read_b64_tr_b16 v[210:211], v199 offset:0x3e00
	s_waitcnt lgkmcnt(8)
	v_mfma_f32_32x32x16_bf16 v[16:31], v[76:79], v[204:207], v[16:31]
	v_exp_f32_e32 v244, v108
	s_waitcnt lgkmcnt(6)
	v_mfma_f32_32x32x16_bf16 v[0:15], v[64:67], v[190:193], v[0:15]
	v_exp_f32_e32 v245, v109
	s_waitcnt lgkmcnt(4)
	v_mfma_f32_32x32x16_bf16 v[0:15], v[68:71], v[194:197], v[0:15]
	v_exp_f32_e32 v246, v110
	s_waitcnt lgkmcnt(2)
	v_mfma_f32_32x32x16_bf16 v[0:15], v[72:75], v[200:203], v[0:15]
	v_exp_f32_e32 v247, v111
	s_waitcnt vmcnt(4)
	s_waitcnt lgkmcnt(0)
	s_barrier
	v_mfma_f32_32x32x16_bf16 v[0:15], v[76:79], v[208:211], v[0:15]
	s_and_b32 s40, s40, 0xc000
	s_add_i32 s40, s57, s40
	v_add_u32_e32 v68, s40, v178
	ds_read_b128 v[64:67], v68
	ds_read_b128 v[68:71], v68 offset:8192
	v_add_u32_e32 v194, s40, v179
	ds_read_b128 v[190:193], v194
	ds_read_b128 v[194:197], v194 offset:8192
	v_add_u32_e32 v199, s40, v181
	s_waitcnt lgkmcnt(3)
	v_mfma_f32_32x32x16_bf16 v[96:111], v[64:67], v[136:139], 0
	v_exp_f32_e32 v80, v80
	v_exp_f32_e32 v81, v81
	v_exp_f32_e32 v82, v82
	v_exp_f32_e32 v83, v83
	v_exp_f32_e32 v87, v87
	v_exp_f32_e32 v248, v93
	v_exp_f32_e32 v249, v94
	s_waitcnt lgkmcnt(2)
	v_mfma_f32_32x32x16_bf16 v[64:79], v[68:71], v[136:139], 0
	s_waitcnt lgkmcnt(1)
	v_mfma_f32_32x32x16_bf16 v[96:111], v[190:193], v[140:143], v[96:111]
	s_waitcnt lgkmcnt(0)
	v_mfma_f32_32x32x16_bf16 v[64:79], v[194:197], v[140:143], v[64:79]
	v_add_u32_e32 v194, s40, v180
	ds_read_b128 v[190:193], v194
	ds_read_b128 v[194:197], v194 offset:8192
	s_waitcnt lgkmcnt(1)
	v_mfma_f32_32x32x16_bf16 v[96:111], v[190:193], v[132:135], v[96:111]
	ds_read_b128 v[190:193], v199
	ds_read_b128 v[200:203], v199 offset:8192
	v_add_u32_e32 v199, s40, v182
	ds_read_b128 v[204:207], v199
	ds_read_b128 v[208:211], v199 offset:8192
	v_add_u32_e32 v199, s40, v183
	ds_read_b128 v[212:215], v199
	ds_read_b128 v[216:219], v199 offset:8192
	v_add_u32_e32 v199, s40, v184
	s_waitcnt lgkmcnt(6)
	v_mfma_f32_32x32x16_bf16 v[64:79], v[194:197], v[132:135], v[64:79]
	ds_read_b128 v[194:197], v199
	ds_read_b128 v[220:223], v199 offset:8192
	v_add_u32_e32 v199, s40, v185
	ds_read_b128 v[224:227], v199
	ds_read_b128 v[228:231], v199 offset:8192
	s_waitcnt lgkmcnt(9)
	v_mfma_f32_32x32x16_bf16 v[96:111], v[190:193], v[128:131], v[96:111]
	s_cmp_ge_u32 s73, s37
	s_cselect_b64 s[40:41], -1, 0
	s_and_b64 vcc, exec, s[40:41]
	s_cbranch_vccnz .LBB0_463
	s_add_i32 s74, s67, s43
	s_add_u32 s98, s38, s26
	s_addc_u32 s99, s39, s27
	s_mov_b32 m0, s74
	s_add_i32 s43, s72, s43
	global_load_lds_dwordx4 v156, s[98:99]
	s_add_u32 s100, s38, s28
	s_addc_u32 s101, s39, s29
	s_add_i32 m0, s74, 0x2000
	s_nop 0
	global_load_lds_dwordx4 v158, s[98:99]
	s_mov_b32 m0, s43
	s_nop 0
	global_load_lds_dwordx4 v162, s[100:101]
	s_add_i32 m0, s43, 0x2000
	s_nop 0
	global_load_lds_dwordx4 v160, s[100:101]

; #define PG8_STAGE(bufoff, gbase, voff) do { _Pragma("unroll") for (int _i = 0; _i < 2; ++_i) \
;         __builtin_amdgcn_global_load_lds((const unsigned*)((const char*)(gbase) + (voff)[_i]), (PG8_LAS unsigned*)(lds + (bufoff) + ldsw + _i * 8192), 16, 0, 0); } while (0)
; #define PG8_WAIT_V(n) asm volatile("s_waitcnt vmcnt(" #n ")" ::: "memory")
; #define PG8_BAR __builtin_amdgcn_s_barrier()
; template <class Epi, class Sched, bool ALIGN_EPI = false, bool SP2 = false>
; __device__ __forceinline__ void gemm_phase(PG8_LAS unsigned char* lds, const Gemm g, const Sched& S, const Epi& E, const int tid) {
;     const int wid = __builtin_amdgcn_readfirstlane(tid >> 6), lane = tid & 63, wr = wid >> 2, wc = wid & 3, fr = lane & 15, fq = lane >> 4;
;     const int K = g.K, nt = K / BK;
;     unsigned voffA[2], voffB[2];
; #pragma unroll
;     for (int i = 0; i < 2; ++i) { int R, C; stage_rc(tid * 16 + i * 8192, R, C); const int Rb = Epi::PERM ? ((R & ~31) + perm32(R & 31)) : R;
;         voffA[i] = (unsigned)(R * K + C) * 2u; voffB[i] = (unsigned)(Rb * K + C) * 2u; }
;     const size_t kstep = (size_t)(BK * 2);
;     const size_t hstep = (size_t)HALF * K * 2;
;     const size_t tstep = 2 * hstep;
;     const unsigned ldsw = (unsigned)wid * 1024u;
;     const int aoff = lds_byte(wr * 64 + fr, fq * 8), boff = lds_byte(wc * 32 + fr, fq * 8);
;     ...
;         PG8_STAGE(PG8_SB(0, 0), cB, voffB); PG8_STAGE(PG8_SB(0, 1), cB + hstep, voffB); PG8_STAGE(PG8_SA(0, 0), cA, voffA); PG8_STAGE(PG8_SA(0, 1), cA + hstep, voffA);
;         if (wr == 1) PG8_BAR;
;         PG8_WAIT_V(2); PG8_BAR;
;         PG8_STAGE(PG8_SB(1, 0), cB + kstep, voffB); PG8_STAGE(PG8_SA(1, 0), cA + kstep, voffA); PG8_STAGE(PG8_SB(1, 1), cB + hstep + kstep, voffB);
;         PG8_WAIT_V(6); PG8_BAR;
;     } else {
;         PG8_STAGE(PG8_SB(0, 0), cB, voffB); PG8_STAGE(PG8_SA(0, 0), cA, voffA); PG8_STAGE(PG8_SB(0, 1), cB + hstep, voffB); PG8_STAGE(PG8_SA(0, 1), cA + hstep, voffA);
;         if (wr == 1) PG8_BAR;
;         PG8_WAIT_V(4); PG8_BAR;
;         PG8_STAGE(PG8_SB(1, 0), cB + kstep, voffB); PG8_STAGE(PG8_SA(1, 0), cA + kstep, voffA); PG8_STAGE(PG8_SB(1, 1), cB + hstep + kstep, voffB);
;         PG8_WAIT_V(6); PG8_BAR;
;     }
.LBB0_664:
	s_lshl_b32 s15, s15, 5
	s_and_b32 s19, s15, 0x60
	s_lshl_b32 s18, s1, 13
	s_lshl_b32 s15, s19, 7
	s_add_u32 s49, s13, 0x8800000
	s_addc_u32 s50, s12, 0
	s_add_u32 s51, s13, 0x3002000
	s_addc_u32 s52, s12, 0
	s_mov_b64 s[12:13], 0x80
	s_add_i32 m0, s44, 0x18000
	v_lshl_add_u64 v[6:7], v[6:7], 0, s[12:13]
	s_waitcnt vmcnt(2)
	s_barrier
	global_load_lds_dwordx4 v[6:7], off
	v_lshl_add_u64 v[4:5], v[4:5], 0, s[12:13]
	s_add_i32 m0, s44, 0x1a000
	s_add_i32 s53, s44, 0x8000
	s_add_i32 s54, s44, 0xa000
	global_load_lds_dwordx4 v[4:5], off
	v_lshl_add_u64 v[0:1], v[0:1], 0, s[12:13]
	s_mov_b32 m0, s53
	s_add_u32 s16, s26, 0x40080
	global_load_lds_dwordx4 v[0:1], off
	v_lshl_add_u64 v[0:1], v[2:3], 0, s[12:13]
	s_mov_b32 m0, s54
	s_addc_u32 s17, s27, 0
	global_load_lds_dwordx4 v[0:1], off
	s_add_i32 m0, s44, 0x1c000
	global_load_lds_dwordx4 v146, s[16:17]
	s_add_i32 m0, s44, 0x1e000
	v_lshlrev_b32_e32 v2, 2, v9
	global_load_lds_dwordx4 v150, s[16:17]
	v_lshlrev_b32_e32 v1, 1, v8
	v_lshl_or_b32 v0, s1, 6, v9
	v_lshl_or_b32 v1, v9, 6, v1
	v_and_b32_e32 v2, 32, v2
	v_bitop3_b32 v4, v1, s18, v2 bitop3:0xde
	v_bitop3_b32 v178, s15, v1, v2 bitop3:0xf6
	v_or_b32_e32 v2, 16, v0
	v_ashrrev_i32_e32 v1, 31, v0
	v_ashrrev_i32_e32 v3, 31, v2
	v_lshlrev_b64 v[152:153], 10, v[0:1]
	v_lshlrev_b64 v[154:155], 10, v[2:3]
	v_or_b32_e32 v2, 32, v0
	v_or_b32_e32 v0, 48, v0
	v_ashrrev_i32_e32 v1, 31, v0
	v_lshlrev_b64 v[158:159], 10, v[0:1]
	v_lshlrev_b32_e32 v0, 14, v10
	v_and_b32_e32 v0, 0xffff8000, v0
	v_lshl_add_u32 v0, v11, 11, v0
	v_and_b32_e32 v1, 1, v10
	v_lshl_or_b32 v0, v1, 6, v0
	s_sext_i32_i8 s59, s0
	s_mov_b64 s[0:1], 0x20000
	v_lshl_add_u32 v168, v12, 1, v0
	v_lshlrev_b32_e32 v0, 14, v13
	v_lshl_add_u64 v[160:161], v[152:153], 0, s[0:1]
	s_mov_b64 s[0:1], 0x24000
	v_and_b32_e32 v0, 0xffff8000, v0
	s_waitcnt vmcnt(6)
	s_cmpk_lt_u32 s14, 0x100
	v_lshl_add_u64 v[162:163], v[152:153], 0, s[0:1]
	s_mov_b64 s[0:1], 0x28000
	v_lshl_add_u32 v0, v14, 11, v0
	v_and_b32_e32 v1, 1, v13
	s_cselect_b64 s[14:15], -1, 0
	v_ashrrev_i32_e32 v3, 31, v2
	v_lshl_add_u64 v[164:165], v[152:153], 0, s[0:1]
	s_mov_b64 s[0:1], 0x2c000
	v_lshl_or_b32 v0, v1, 6, v0
	s_add_i32 s56, 0, 0x10000
	s_add_i32 s57, 0, 0x14000
	v_lshlrev_b64 v[156:157], 10, v[2:3]
	v_lshl_add_u64 v[166:167], v[152:153], 0, s[0:1]
	s_ashr_i32 s55, s35, 31
	v_or_b32_e32 v179, s19, v8
	v_mov_b32_e32 v169, v147
	v_lshl_add_u32 v170, v15, 1, v0
	v_mov_b32_e32 v171, v147
	v_mov_b64_e32 v[172:173], 0x200
	v_mov_b64_e32 v[174:175], 0x1ff
	v_add_u32_e32 v180, s56, v178
	v_add_u32_e32 v181, s57, v178
	v_add_u32_e32 v182, 0, v4
	s_barrier
	s_branch .LBB0_667

; #define PG8_STAGE(bufoff, gbase, voff) do { _Pragma("unroll") for (int _i = 0; _i < 2; ++_i) \
;         __builtin_amdgcn_global_load_lds((const unsigned*)((const char*)(gbase) + (voff)[_i]), (PG8_LAS unsigned*)(lds + (bufoff) + ldsw + _i * 8192), 16, 0, 0); } while (0)
; #define PG8_LDA(dst, b, h) do { _Pragma("unroll") for (int m = 0; m < 4; ++m) _Pragma("unroll") for (int k = 0; k < 2; ++k) dst[m][k] = *(const PG8_LAS bf16x8*)(lds + PG8_SA(b, h) + aoff + m * 2048 + k * 1024); } while (0)
; #define PG8_LDB(dst, b, h) do { _Pragma("unroll") for (int n = 0; n < 2; ++n) _Pragma("unroll") for (int k = 0; k < 2; ++k) dst[n][k] = *(const PG8_LAS bf16x8*)(lds + PG8_SB(b, h) + boff + n * 2048 + k * 1024); } while (0)
; #define PG8_MMA(ai, bj, At, Bt) do { __builtin_amdgcn_s_setprio(1); _Pragma("unroll") for (int m = 0; m < 4; ++m) _Pragma("unroll") for (int n = 0; n < 2; ++n) _Pragma("unroll") for (int k = 0; k < 2; ++k) \
;         acc[ai][bj][m][n] = __builtin_amdgcn_mfma_f32_16x16x32_bf16(Bt[n][k], At[m][k], acc[ai][bj][m][n], 0, 0, 0); __builtin_amdgcn_s_setprio(0); } while (0)
; #define PG8_WAIT_V(n) asm volatile("s_waitcnt vmcnt(" #n ")" ::: "memory")
; #define PG8_WAIT_L(n) asm volatile("s_waitcnt lgkmcnt(" #n ")" ::: "memory")
; #define PG8_BAR __builtin_amdgcn_s_barrier()
; #define PG8_SCHED __builtin_amdgcn_sched_barrier(0)
; template <class Epi, class Sched, bool ALIGN_EPI = false, bool SP2 = false>
; __device__ __forceinline__ void gemm_phase(PG8_LAS unsigned char* lds, const Gemm g, const Sched& S, const Epi& E, const int tid) {
;     ...
;             PG8_LDB(B0, 0, 0); PG8_LDB(B1, 0, 1); PG8_SCHED; PG8_LDA(At, 0, 0); PG8_STAGE(PG8_SA(1, 1), a1 + hstep, voffA);
;             PG8_WAIT_V(8); PG8_WAIT_L(0); PG8_BAR; PG8_MMA(0, 0, At, B0); PG8_MMA(0, 1, At, B1); PG8_BAR; PG8_SCHED;
;             PG8_LDA(At, 0, 1); PG8_STAGE(PG8_SB(0, 0), b2, voffB); PG8_STAGE(PG8_SB(0, 1), b2 + hstep, voffB); PG8_STAGE(PG8_SA(0, 0), a2, voffA);
;             PG8_WAIT_V(8); PG8_WAIT_L(0); PG8_BAR; PG8_MMA(1, 0, At, B0); PG8_MMA(1, 1, At, B1); PG8_BAR; PG8_SCHED;
.LBB0_674:
	ds_read_b128 v[128:131], v180
	ds_read_b128 v[132:135], v180 offset:1024
	ds_read_b128 v[136:139], v180 offset:2048
	ds_read_b128 v[140:143], v180 offset:3072
	ds_read_b128 v[184:187], v181
	ds_read_b128 v[188:191], v181 offset:1024
	ds_read_b128 v[192:195], v181 offset:2048
	ds_read_b128 v[196:199], v181 offset:3072
	s_add_u32 s26, s24, 0xfffc0080
	s_addc_u32 s27, s25, -1
	s_cmp_eq_u32 s61, 12
	s_cselect_b32 s29, s23, s27
	s_cselect_b32 s28, s30, s26
	s_cselect_b32 s27, s17, s60
	s_cselect_b32 s26, s31, s33
	s_add_i32 m0, s44, 0xc000
	ds_read_b128 v[200:203], v182
	ds_read_b128 v[204:207], v182 offset:1024
	ds_read_b128 v[208:211], v182 offset:2048
	ds_read_b128 v[212:215], v182 offset:3072
	ds_read_b128 v[216:219], v182 offset:4096
	ds_read_b128 v[220:223], v182 offset:5120
	ds_read_b128 v[224:227], v182 offset:6144
	ds_read_b128 v[228:231], v182 offset:7168
	global_load_lds_dwordx4 v168, s[24:25]
	s_add_i32 m0, s44, 0xe000
	s_nop 0
	global_load_lds_dwordx4 v170, s[24:25]
	s_waitcnt vmcnt(8)
	s_waitcnt lgkmcnt(0)
	s_barrier
	s_setprio 1
	s_waitcnt lgkmcnt(0)
	v_mfma_f32_16x16x32_bf16 v[124:127], v[128:131], v[200:203], v[124:127]
	v_mfma_f32_16x16x32_bf16 v[120:123], v[136:139], v[200:203], v[120:123]
	v_mfma_f32_16x16x32_bf16 v[116:119], v[128:131], v[208:211], v[116:119]
	v_mfma_f32_16x16x32_bf16 v[108:111], v[136:139], v[208:211], v[108:111]
	v_mfma_f32_16x16x32_bf16 v[100:103], v[128:131], v[216:219], v[100:103]
	v_mfma_f32_16x16x32_bf16 v[92:95], v[136:139], v[216:219], v[92:95]
	v_mfma_f32_16x16x32_bf16 v[84:87], v[128:131], v[224:227], v[84:87]
	v_mfma_f32_16x16x32_bf16 v[76:79], v[136:139], v[224:227], v[76:79]
	v_mfma_f32_16x16x32_bf16 v[124:127], v[132:135], v[204:207], v[124:127]
	v_mfma_f32_16x16x32_bf16 v[120:123], v[140:143], v[204:207], v[120:123]
	v_mfma_f32_16x16x32_bf16 v[116:119], v[132:135], v[212:215], v[116:119]
	v_mfma_f32_16x16x32_bf16 v[108:111], v[140:143], v[212:215], v[108:111]
	v_mfma_f32_16x16x32_bf16 v[100:103], v[132:135], v[220:223], v[100:103]
	v_mfma_f32_16x16x32_bf16 v[92:95], v[140:143], v[220:223], v[92:95]
	v_mfma_f32_16x16x32_bf16 v[84:87], v[132:135], v[228:231], v[84:87]
	v_mfma_f32_16x16x32_bf16 v[76:79], v[140:143], v[228:231], v[76:79]
	s_setprio 0
	s_setprio 1
	v_mfma_f32_16x16x32_bf16 v[112:115], v[184:187], v[200:203], v[112:115]
	v_mfma_f32_16x16x32_bf16 v[104:107], v[192:195], v[200:203], v[104:107]
	v_mfma_f32_16x16x32_bf16 v[96:99], v[184:187], v[208:211], v[96:99]
	v_mfma_f32_16x16x32_bf16 v[88:91], v[192:195], v[208:211], v[88:91]
	v_mfma_f32_16x16x32_bf16 v[80:83], v[184:187], v[216:219], v[80:83]
	v_mfma_f32_16x16x32_bf16 v[72:75], v[192:195], v[216:219], v[72:75]
	v_mfma_f32_16x16x32_bf16 v[68:71], v[184:187], v[224:227], v[68:71]
	v_mfma_f32_16x16x32_bf16 v[64:67], v[192:195], v[224:227], v[64:67]
	v_mfma_f32_16x16x32_bf16 v[112:115], v[188:191], v[204:207], v[112:115]
	v_mfma_f32_16x16x32_bf16 v[104:107], v[196:199], v[204:207], v[104:107]
	v_mfma_f32_16x16x32_bf16 v[96:99], v[188:191], v[212:215], v[96:99]
	v_mfma_f32_16x16x32_bf16 v[88:91], v[196:199], v[212:215], v[88:91]
	v_mfma_f32_16x16x32_bf16 v[80:83], v[188:191], v[220:223], v[80:83]
	v_mfma_f32_16x16x32_bf16 v[72:75], v[196:199], v[220:223], v[72:75]
	v_mfma_f32_16x16x32_bf16 v[68:71], v[188:191], v[228:231], v[68:71]
	v_mfma_f32_16x16x32_bf16 v[64:67], v[196:199], v[228:231], v[64:67]
	s_setprio 0
	s_barrier
	s_add_i32 s62, s56, s43
	v_lshl_add_u64 v[176:177], s[26:27], 0, v[146:147]
	s_mov_b32 m0, s62
	ds_read_b128 v[200:203], v182 offset:16384
	ds_read_b128 v[204:207], v182 offset:17408
	ds_read_b128 v[208:211], v182 offset:18432
	ds_read_b128 v[212:215], v182 offset:19456
	ds_read_b128 v[216:219], v182 offset:20480
	ds_read_b128 v[220:223], v182 offset:21504
	ds_read_b128 v[224:227], v182 offset:22528
	ds_read_b128 v[228:231], v182 offset:23552
	global_load_lds_dwordx4 v[176:177], off
	s_add_i32 m0, s62, 0x2000
	s_add_u32 s62, s26, 0x40000
	v_lshl_add_u64 v[232:233], s[26:27], 0, v[150:151]
	s_addc_u32 s63, s27, 0
	s_add_i32 s64, s57, s43
	global_load_lds_dwordx4 v[232:233], off
	s_mov_b32 m0, s64
	v_lshl_add_u64 v[236:237], s[28:29], 0, v[148:149]
	global_load_lds_dwordx4 v146, s[62:63]
	s_add_i32 m0, s64, 0x2000
	s_nop 0
	global_load_lds_dwordx4 v150, s[62:63]
	v_lshl_add_u64 v[234:235], s[28:29], 0, v[144:145]
	s_mov_b32 m0, s44
	s_nop 0
	global_load_lds_dwordx4 v[234:235], off
	s_mov_b32 m0, s45
	s_nop 0
	global_load_lds_dwordx4 v[236:237], off
	s_waitcnt vmcnt(8)
	s_waitcnt lgkmcnt(0)
	s_barrier
; #define PG8_STAGE(bufoff, gbase, voff) do { _Pragma("unroll") for (int _i = 0; _i < 2; ++_i) \
;         __builtin_amdgcn_global_load_lds((const unsigned*)((const char*)(gbase) + (voff)[_i]), (PG8_LAS unsigned*)(lds + (bufoff) + ldsw + _i * 8192), 16, 0, 0); } while (0)
; #define PG8_LDA(dst, b, h) do { _Pragma("unroll") for (int m = 0; m < 4; ++m) _Pragma("unroll") for (int k = 0; k < 2; ++k) dst[m][k] = *(const PG8_LAS bf16x8*)(lds + PG8_SA(b, h) + aoff + m * 2048 + k * 1024); } while (0)
; #define PG8_LDB(dst, b, h) do { _Pragma("unroll") for (int n = 0; n < 2; ++n) _Pragma("unroll") for (int k = 0; k < 2; ++k) dst[n][k] = *(const PG8_LAS bf16x8*)(lds + PG8_SB(b, h) + boff + n * 2048 + k * 1024); } while (0)
; #define PG8_MMA(ai, bj, At, Bt) do { __builtin_amdgcn_s_setprio(1); _Pragma("unroll") for (int m = 0; m < 4; ++m) _Pragma("unroll") for (int n = 0; n < 2; ++n) _Pragma("unroll") for (int k = 0; k < 2; ++k) \
;         acc[ai][bj][m][n] = __builtin_amdgcn_mfma_f32_16x16x32_bf16(Bt[n][k], At[m][k], acc[ai][bj][m][n], 0, 0, 0); __builtin_amdgcn_s_setprio(0); } while (0)
; #define PG8_WAIT_V(n) asm volatile("s_waitcnt vmcnt(" #n ")" ::: "memory")
; #define PG8_WAIT_L(n) asm volatile("s_waitcnt lgkmcnt(" #n ")" ::: "memory")
; #define PG8_BAR __builtin_amdgcn_s_barrier()
; #define PG8_SCHED __builtin_amdgcn_sched_barrier(0)
; template <class Epi, class Sched, bool ALIGN_EPI = false, bool SP2 = false>
; __device__ __forceinline__ void gemm_phase(PG8_LAS unsigned char* lds, const Gemm g, const Sched& S, const Epi& E, const int tid) {
;     ...
;             PG8_WAIT_V(8); PG8_WAIT_L(0); PG8_BAR; PG8_MMA(1, 0, At, B0); PG8_MMA(1, 1, At, B1); PG8_BAR; PG8_SCHED;
;             PG8_LDB(B0, 1, 0); PG8_LDB(B1, 1, 1); PG8_SCHED; PG8_LDA(At, 1, 0); PG8_STAGE(PG8_SA(0, 1), a2 + hstep, voffA);
;             PG8_WAIT_V(8); PG8_WAIT_L(0); PG8_BAR; PG8_MMA(0, 0, At, B0); PG8_MMA(0, 1, At, B1); PG8_BAR; PG8_SCHED;
	s_setprio 1
	s_waitcnt lgkmcnt(0)
	v_mfma_f32_16x16x32_bf16 v[60:63], v[128:131], v[200:203], v[60:63]
	v_mfma_f32_16x16x32_bf16 v[56:59], v[136:139], v[200:203], v[56:59]
	v_mfma_f32_16x16x32_bf16 v[52:55], v[128:131], v[208:211], v[52:55]
	v_mfma_f32_16x16x32_bf16 v[44:47], v[136:139], v[208:211], v[44:47]
	v_mfma_f32_16x16x32_bf16 v[36:39], v[128:131], v[216:219], v[36:39]
	v_mfma_f32_16x16x32_bf16 v[28:31], v[136:139], v[216:219], v[28:31]
	v_mfma_f32_16x16x32_bf16 v[20:23], v[128:131], v[224:227], v[20:23]
	v_mfma_f32_16x16x32_bf16 v[12:15], v[136:139], v[224:227], v[12:15]
	v_mfma_f32_16x16x32_bf16 v[60:63], v[132:135], v[204:207], v[60:63]
	v_mfma_f32_16x16x32_bf16 v[56:59], v[140:143], v[204:207], v[56:59]
	v_mfma_f32_16x16x32_bf16 v[52:55], v[132:135], v[212:215], v[52:55]
	v_mfma_f32_16x16x32_bf16 v[44:47], v[140:143], v[212:215], v[44:47]
	v_mfma_f32_16x16x32_bf16 v[36:39], v[132:135], v[220:223], v[36:39]
	v_mfma_f32_16x16x32_bf16 v[28:31], v[140:143], v[220:223], v[28:31]
	v_mfma_f32_16x16x32_bf16 v[20:23], v[132:135], v[228:231], v[20:23]
	v_mfma_f32_16x16x32_bf16 v[12:15], v[140:143], v[228:231], v[12:15]
	s_setprio 0
	s_setprio 1
	v_mfma_f32_16x16x32_bf16 v[48:51], v[184:187], v[200:203], v[48:51]
	v_mfma_f32_16x16x32_bf16 v[40:43], v[192:195], v[200:203], v[40:43]
	v_mfma_f32_16x16x32_bf16 v[32:35], v[184:187], v[208:211], v[32:35]
	v_mfma_f32_16x16x32_bf16 v[24:27], v[192:195], v[208:211], v[24:27]
	v_mfma_f32_16x16x32_bf16 v[16:19], v[184:187], v[216:219], v[16:19]
	v_mfma_f32_16x16x32_bf16 v[8:11], v[192:195], v[216:219], v[8:11]
	v_mfma_f32_16x16x32_bf16 v[4:7], v[184:187], v[224:227], v[4:7]
	v_mfma_f32_16x16x32_bf16 v[0:3], v[192:195], v[224:227], v[0:3]
	v_mfma_f32_16x16x32_bf16 v[48:51], v[188:191], v[204:207], v[48:51]
	v_mfma_f32_16x16x32_bf16 v[40:43], v[196:199], v[204:207], v[40:43]
	v_mfma_f32_16x16x32_bf16 v[32:35], v[188:191], v[212:215], v[32:35]
	v_mfma_f32_16x16x32_bf16 v[24:27], v[196:199], v[212:215], v[24:27]
	v_mfma_f32_16x16x32_bf16 v[16:19], v[188:191], v[220:223], v[16:19]
	v_mfma_f32_16x16x32_bf16 v[8:11], v[196:199], v[220:223], v[8:11]
	v_mfma_f32_16x16x32_bf16 v[4:7], v[188:191], v[228:231], v[4:7]
	v_mfma_f32_16x16x32_bf16 v[0:3], v[196:199], v[228:231], v[0:3]
	s_setprio 0
	s_barrier
	s_add_i32 s62, 0, 0x18000
	s_add_i32 s63, 0, 0x1c000
	v_add_u32_e32 v140, s62, v178
	v_add_u32_e32 v183, s63, v178
	ds_read_b128 v[128:131], v140
	ds_read_b128 v[132:135], v140 offset:1024
	ds_read_b128 v[136:139], v140 offset:2048
	ds_read_b128 v[140:143], v140 offset:3072
	ds_read_b128 v[184:187], v183
	ds_read_b128 v[188:191], v183 offset:1024
	ds_read_b128 v[192:195], v183 offset:2048
	ds_read_b128 v[196:199], v183 offset:3072
	s_add_u32 s28, s28, 0x40000
	s_addc_u32 s29, s29, 0
	s_mov_b32 m0, s46
	ds_read_b128 v[200:203], v182 offset:32768
	ds_read_b128 v[204:207], v182 offset:33792
	ds_read_b128 v[208:211], v182 offset:34816
	ds_read_b128 v[212:215], v182 offset:35840
	ds_read_b128 v[216:219], v182 offset:36864
	ds_read_b128 v[220:223], v182 offset:37888
	ds_read_b128 v[224:227], v182 offset:38912
	ds_read_b128 v[228:231], v182 offset:39936
	global_load_lds_dwordx4 v144, s[28:29]
	v_lshl_add_u64 v[238:239], s[28:29], 0, v[148:149]
	s_mov_b32 m0, s47
	s_nop 0
	global_load_lds_dwordx4 v[238:239], off
	s_waitcnt vmcnt(8)
	s_waitcnt lgkmcnt(0)
	s_barrier
	s_setprio 1
	s_waitcnt lgkmcnt(0)
	v_mfma_f32_16x16x32_bf16 v[124:127], v[128:131], v[200:203], v[124:127]
	v_mfma_f32_16x16x32_bf16 v[120:123], v[136:139], v[200:203], v[120:123]
	v_mfma_f32_16x16x32_bf16 v[116:119], v[128:131], v[208:211], v[116:119]
	v_mfma_f32_16x16x32_bf16 v[108:111], v[136:139], v[208:211], v[108:111]
	v_mfma_f32_16x16x32_bf16 v[100:103], v[128:131], v[216:219], v[100:103]
	v_mfma_f32_16x16x32_bf16 v[92:95], v[136:139], v[216:219], v[92:95]
	v_mfma_f32_16x16x32_bf16 v[84:87], v[128:131], v[224:227], v[84:87]
	v_mfma_f32_16x16x32_bf16 v[76:79], v[136:139], v[224:227], v[76:79]
	v_mfma_f32_16x16x32_bf16 v[124:127], v[132:135], v[204:207], v[124:127]
	v_mfma_f32_16x16x32_bf16 v[120:123], v[140:143], v[204:207], v[120:123]
	v_mfma_f32_16x16x32_bf16 v[116:119], v[132:135], v[212:215], v[116:119]
	v_mfma_f32_16x16x32_bf16 v[108:111], v[140:143], v[212:215], v[108:111]
	v_mfma_f32_16x16x32_bf16 v[100:103], v[132:135], v[220:223], v[100:103]
	v_mfma_f32_16x16x32_bf16 v[92:95], v[140:143], v[220:223], v[92:95]
	v_mfma_f32_16x16x32_bf16 v[84:87], v[132:135], v[228:231], v[84:87]
	v_mfma_f32_16x16x32_bf16 v[76:79], v[140:143], v[228:231], v[76:79]
	s_setprio 0
	s_setprio 1
	v_mfma_f32_16x16x32_bf16 v[112:115], v[184:187], v[200:203], v[112:115]
	v_mfma_f32_16x16x32_bf16 v[104:107], v[192:195], v[200:203], v[104:107]
	v_mfma_f32_16x16x32_bf16 v[96:99], v[184:187], v[208:211], v[96:99]
	v_mfma_f32_16x16x32_bf16 v[88:91], v[192:195], v[208:211], v[88:91]
	v_mfma_f32_16x16x32_bf16 v[80:83], v[184:187], v[216:219], v[80:83]
	v_mfma_f32_16x16x32_bf16 v[72:75], v[192:195], v[216:219], v[72:75]
	v_mfma_f32_16x16x32_bf16 v[68:71], v[184:187], v[224:227], v[68:71]
	v_mfma_f32_16x16x32_bf16 v[64:67], v[192:195], v[224:227], v[64:67]
	v_mfma_f32_16x16x32_bf16 v[112:115], v[188:191], v[204:207], v[112:115]
	v_mfma_f32_16x16x32_bf16 v[104:107], v[196:199], v[204:207], v[104:107]
	v_mfma_f32_16x16x32_bf16 v[96:99], v[188:191], v[212:215], v[96:99]
	v_mfma_f32_16x16x32_bf16 v[88:91], v[196:199], v[212:215], v[88:91]
	v_mfma_f32_16x16x32_bf16 v[80:83], v[188:191], v[220:223], v[80:83]
	v_mfma_f32_16x16x32_bf16 v[72:75], v[196:199], v[220:223], v[72:75]
	v_mfma_f32_16x16x32_bf16 v[68:71], v[188:191], v[228:231], v[68:71]
	v_mfma_f32_16x16x32_bf16 v[64:67], v[196:199], v[228:231], v[64:67]
	s_setprio 0
	s_barrier
; #define PG8_STAGE(bufoff, gbase, voff) do { _Pragma("unroll") for (int _i = 0; _i < 2; ++_i) \
;         __builtin_amdgcn_global_load_lds((const unsigned*)((const char*)(gbase) + (voff)[_i]), (PG8_LAS unsigned*)(lds + (bufoff) + ldsw + _i * 8192), 16, 0, 0); } while (0)
; #define PG8_LDA(dst, b, h) do { _Pragma("unroll") for (int m = 0; m < 4; ++m) _Pragma("unroll") for (int k = 0; k < 2; ++k) dst[m][k] = *(const PG8_LAS bf16x8*)(lds + PG8_SA(b, h) + aoff + m * 2048 + k * 1024); } while (0)
; #define PG8_MMA(ai, bj, At, Bt) do { __builtin_amdgcn_s_setprio(1); _Pragma("unroll") for (int m = 0; m < 4; ++m) _Pragma("unroll") for (int n = 0; n < 2; ++n) _Pragma("unroll") for (int k = 0; k < 2; ++k) \
;         acc[ai][bj][m][n] = __builtin_amdgcn_mfma_f32_16x16x32_bf16(Bt[n][k], At[m][k], acc[ai][bj][m][n], 0, 0, 0); __builtin_amdgcn_s_setprio(0); } while (0)
; #define PG8_WAIT_V(n) asm volatile("s_waitcnt vmcnt(" #n ")" ::: "memory")
; #define PG8_WAIT_L(n) asm volatile("s_waitcnt lgkmcnt(" #n ")" ::: "memory")
; #define PG8_BAR __builtin_amdgcn_s_barrier()
; #define PG8_SCHED __builtin_amdgcn_sched_barrier(0)
; template <class Epi, class Sched, bool ALIGN_EPI = false, bool SP2 = false>
; __device__ __forceinline__ void gemm_phase(PG8_LAS unsigned char* lds, const Gemm g, const Sched& S, const Epi& E, const int tid) {
;     ...
;         for (int t = 0; t < nt; t += 2) {
;             const bool last = (t == nt - 2);
;     ...
;             PG8_LDA(At, 1, 1); PG8_STAGE(PG8_SB(1, 0), b3, voffB); PG8_STAGE(PG8_SB(1, 1), b3 + hstep, voffB); PG8_STAGE(PG8_SA(1, 0), a3, voffA);
;             PG8_WAIT_V(8); PG8_WAIT_L(0); PG8_BAR; PG8_MMA(1, 0, At, B0); PG8_MMA(1, 1, At, B1); PG8_BAR; PG8_SCHED;
	s_add_i32 s28, s62, s43
	v_lshl_add_u64 v[176:177], v[176:177], 0, s[12:13]
	s_mov_b32 m0, s28
	ds_read_b128 v[200:203], v182 offset:49152
	ds_read_b128 v[204:207], v182 offset:50176
	ds_read_b128 v[208:211], v182 offset:51200
	ds_read_b128 v[212:215], v182 offset:52224
	ds_read_b128 v[216:219], v182 offset:53248
	ds_read_b128 v[220:223], v182 offset:54272
	ds_read_b128 v[224:227], v182 offset:55296
	ds_read_b128 v[228:231], v182 offset:56320
	global_load_lds_dwordx4 v[176:177], off
	s_add_i32 m0, s28, 0x2000
	s_add_u32 s26, s26, 0x40080
	v_lshl_add_u64 v[176:177], v[232:233], 0, s[12:13]
	s_addc_u32 s27, s27, 0
	s_add_i32 s28, s63, s43
	global_load_lds_dwordx4 v[176:177], off
	s_mov_b32 m0, s28
	s_nop 0
	global_load_lds_dwordx4 v146, s[26:27]
	s_add_i32 m0, s28, 0x2000
	s_nop 0
	global_load_lds_dwordx4 v150, s[26:27]
	v_lshl_add_u64 v[176:177], v[234:235], 0, s[12:13]
	s_mov_b32 m0, s53
	s_nop 0
	global_load_lds_dwordx4 v[176:177], off
	v_lshl_add_u64 v[176:177], v[236:237], 0, s[12:13]
	s_mov_b32 m0, s54
	s_nop 0
	global_load_lds_dwordx4 v[176:177], off
	s_waitcnt vmcnt(8)
	s_waitcnt lgkmcnt(0)
	s_barrier
	s_setprio 1
	s_waitcnt lgkmcnt(0)
	v_mfma_f32_16x16x32_bf16 v[60:63], v[128:131], v[200:203], v[60:63]
	v_mfma_f32_16x16x32_bf16 v[56:59], v[136:139], v[200:203], v[56:59]
	v_mfma_f32_16x16x32_bf16 v[52:55], v[128:131], v[208:211], v[52:55]
	v_mfma_f32_16x16x32_bf16 v[44:47], v[136:139], v[208:211], v[44:47]
	v_mfma_f32_16x16x32_bf16 v[36:39], v[128:131], v[216:219], v[36:39]
	v_mfma_f32_16x16x32_bf16 v[28:31], v[136:139], v[216:219], v[28:31]
	v_mfma_f32_16x16x32_bf16 v[20:23], v[128:131], v[224:227], v[20:23]
	v_mfma_f32_16x16x32_bf16 v[12:15], v[136:139], v[224:227], v[12:15]
	v_mfma_f32_16x16x32_bf16 v[60:63], v[132:135], v[204:207], v[60:63]
	v_mfma_f32_16x16x32_bf16 v[56:59], v[140:143], v[204:207], v[56:59]
	v_mfma_f32_16x16x32_bf16 v[52:55], v[132:135], v[212:215], v[52:55]
	v_mfma_f32_16x16x32_bf16 v[44:47], v[140:143], v[212:215], v[44:47]
	v_mfma_f32_16x16x32_bf16 v[36:39], v[132:135], v[220:223], v[36:39]
	v_mfma_f32_16x16x32_bf16 v[28:31], v[140:143], v[220:223], v[28:31]
	v_mfma_f32_16x16x32_bf16 v[20:23], v[132:135], v[228:231], v[20:23]
	v_mfma_f32_16x16x32_bf16 v[12:15], v[140:143], v[228:231], v[12:15]
	s_setprio 0
	s_setprio 1
	v_mfma_f32_16x16x32_bf16 v[48:51], v[184:187], v[200:203], v[48:51]
	v_mfma_f32_16x16x32_bf16 v[40:43], v[192:195], v[200:203], v[40:43]
	v_mfma_f32_16x16x32_bf16 v[32:35], v[184:187], v[208:211], v[32:35]
	v_mfma_f32_16x16x32_bf16 v[24:27], v[192:195], v[208:211], v[24:27]
	v_mfma_f32_16x16x32_bf16 v[16:19], v[184:187], v[216:219], v[16:19]
	v_mfma_f32_16x16x32_bf16 v[8:11], v[192:195], v[216:219], v[8:11]
	v_mfma_f32_16x16x32_bf16 v[4:7], v[184:187], v[224:227], v[4:7]
	v_mfma_f32_16x16x32_bf16 v[0:3], v[192:195], v[224:227], v[0:3]
	v_mfma_f32_16x16x32_bf16 v[48:51], v[188:191], v[204:207], v[48:51]
	v_mfma_f32_16x16x32_bf16 v[40:43], v[196:199], v[204:207], v[40:43]
	v_mfma_f32_16x16x32_bf16 v[32:35], v[188:191], v[212:215], v[32:35]
	v_mfma_f32_16x16x32_bf16 v[24:27], v[196:199], v[212:215], v[24:27]
	v_mfma_f32_16x16x32_bf16 v[16:19], v[188:191], v[220:223], v[16:19]
	v_mfma_f32_16x16x32_bf16 v[8:11], v[196:199], v[220:223], v[8:11]
	v_mfma_f32_16x16x32_bf16 v[4:7], v[188:191], v[228:231], v[4:7]
	v_mfma_f32_16x16x32_bf16 v[0:3], v[196:199], v[228:231], v[0:3]
	s_setprio 0
	s_barrier
	s_add_i32 s61, s61, 2
	s_add_u32 s24, s24, 0x100
	s_addc_u32 s25, s25, 0
	s_add_u32 s33, s33, 0x100
	s_addc_u32 s60, s60, 0
	s_cmp_gt_u32 s61, 13
	s_cbranch_scc0 .LBB0_674
	s_and_b64 vcc, exec, s[14:15]
	s_cbranch_vccz .LBB0_677
	s_barrier

; #define PG8_STAGE(bufoff, gbase, voff) do { _Pragma("unroll") for (int _i = 0; _i < 2; ++_i) \
;         __builtin_amdgcn_global_load_lds((const unsigned*)((const char*)(gbase) + (voff)[_i]), (PG8_LAS unsigned*)(lds + (bufoff) + ldsw + _i * 8192), 16, 0, 0); } while (0)
; #define PG8_WAIT_V(n) asm volatile("s_waitcnt vmcnt(" #n ")" ::: "memory")
; #define PG8_BAR __builtin_amdgcn_s_barrier()
; template <class Epi, class Sched, bool ALIGN_EPI = false, bool SP2 = false>
; __device__ __forceinline__ void gemm_phase(PG8_LAS unsigned char* lds, const Gemm g, const Sched& S, const Epi& E, const int tid) {
;     const int wid = __builtin_amdgcn_readfirstlane(tid >> 6), lane = tid & 63, wr = wid >> 2, wc = wid & 3, fr = lane & 15, fq = lane >> 4;
;     const int K = g.K, nt = K / BK;
;     unsigned voffA[2], voffB[2];
; #pragma unroll
;     for (int i = 0; i < 2; ++i) { int R, C; stage_rc(tid * 16 + i * 8192, R, C); const int Rb = Epi::PERM ? ((R & ~31) + perm32(R & 31)) : R;
;         voffA[i] = (unsigned)(R * K + C) * 2u; voffB[i] = (unsigned)(Rb * K + C) * 2u; }
;     const size_t kstep = (size_t)(BK * 2);
;     const size_t hstep = (size_t)HALF * K * 2;
;     const size_t tstep = 2 * hstep;
;     const unsigned ldsw = (unsigned)wid * 1024u;
;     const int aoff = lds_byte(wr * 64 + fr, fq * 8), boff = lds_byte(wc * 32 + fr, fq * 8);
;     ...
;         PG8_STAGE(PG8_SB(0, 0), cB, voffB); PG8_STAGE(PG8_SB(0, 1), cB + hstep, voffB); PG8_STAGE(PG8_SA(0, 0), cA, voffA); PG8_STAGE(PG8_SA(0, 1), cA + hstep, voffA);
;         if (wr == 1) PG8_BAR;
;         PG8_WAIT_V(2); PG8_BAR;
;         PG8_STAGE(PG8_SB(1, 0), cB + kstep, voffB); PG8_STAGE(PG8_SA(1, 0), cA + kstep, voffA); PG8_STAGE(PG8_SB(1, 1), cB + hstep + kstep, voffB);
;         PG8_WAIT_V(6); PG8_BAR;
;     } else {
;         PG8_STAGE(PG8_SB(0, 0), cB, voffB); PG8_STAGE(PG8_SA(0, 0), cA, voffA); PG8_STAGE(PG8_SB(0, 1), cB + hstep, voffB); PG8_STAGE(PG8_SA(0, 1), cA + hstep, voffA);
;         if (wr == 1) PG8_BAR;
;         PG8_WAIT_V(4); PG8_BAR;
;         PG8_STAGE(PG8_SB(1, 0), cB + kstep, voffB); PG8_STAGE(PG8_SA(1, 0), cA + kstep, voffA); PG8_STAGE(PG8_SB(1, 1), cB + hstep + kstep, voffB);
;         PG8_WAIT_V(6); PG8_BAR;
;     }
.LBB0_803:
	s_add_u32 s8, s4, 0x10a00000
	s_addc_u32 s9, s5, 0
	s_lshl_b32 s10, s43, 5
	s_and_b32 s16, s10, 0x60
	s_mov_b64 s[10:11], 0x80
	s_add_i32 m0, s23, 0x18000
	v_lshl_add_u64 v[6:7], v[6:7], 0, s[10:11]
	s_lshl_b32 s13, s1, 13
	s_lshl_b32 s17, s16, 7
	s_waitcnt vmcnt(2)
	s_barrier
	global_load_lds_dwordx4 v[6:7], off
	v_lshl_add_u64 v[4:5], v[4:5], 0, s[10:11]
	s_add_i32 m0, s23, 0x1a000
	s_add_i32 s55, s23, 0x8000
	s_add_i32 s56, s23, 0xa000
	global_load_lds_dwordx4 v[4:5], off
	v_lshl_add_u64 v[0:1], v[0:1], 0, s[10:11]
	s_mov_b32 m0, s55
	s_add_u32 s14, s26, 0x40080
	global_load_lds_dwordx4 v[0:1], off
	v_lshl_add_u64 v[0:1], v[2:3], 0, s[10:11]
	s_mov_b32 m0, s56
	s_addc_u32 s15, s27, 0
	global_load_lds_dwordx4 v[0:1], off
	s_add_i32 m0, s23, 0x1c000
	global_load_lds_dwordx4 v130, s[14:15]
	s_add_i32 m0, s23, 0x1e000
	s_cmpk_lt_u32 s12, 0x100
	global_load_lds_dwordx4 v134, s[14:15]
	v_lshrrev_b32_e32 v1, 1, v144
	v_and_b32_e32 v1, 24, v1
	v_and_b32_e32 v0, 15, v144
	v_lshlrev_b32_e32 v2, 1, v1
	v_lshl_or_b32 v145, s1, 6, v0
	v_lshl_or_b32 v0, v0, 6, v2
	v_lshlrev_b32_e32 v2, 2, v144
	v_and_b32_e32 v2, 32, v2
	v_bitop3_b32 v3, v0, s13, v2 bitop3:0xde
	v_bitop3_b32 v146, s17, v0, v2 bitop3:0xf6
	v_lshlrev_b32_e32 v0, 14, v8
	v_and_b32_e32 v0, 0xffff8000, v0
	v_or_b32_e32 v147, s16, v1
	v_lshl_add_u32 v0, v9, 11, v0
	v_and_b32_e32 v1, 1, v8
	v_lshl_or_b32 v0, v1, 6, v0
	v_lshl_add_u32 v136, v10, 1, v0
	v_lshlrev_b32_e32 v0, 14, v11
	v_and_b32_e32 v0, 0xffff8000, v0
	s_waitcnt vmcnt(6)
	v_lshl_add_u32 v0, v12, 11, v0
	v_and_b32_e32 v1, 1, v11
	s_cselect_b64 s[12:13], -1, 0
	v_lshl_or_b32 v0, v1, 6, v0
	s_add_i32 s58, 0, 0x10000
	s_add_i32 s59, 0, 0x14000
	s_sext_i32_i16 s61, s0
	s_ashr_i32 s57, s39, 31
	v_mov_b32_e32 v137, v131
	v_lshl_add_u32 v138, v13, 1, v0
	v_mov_b32_e32 v139, v131
	v_mov_b64_e32 v[140:141], 0xb2c
	v_mov_b64_e32 v[142:143], 0xb2b
	v_add_u32_e32 v148, s58, v146
	v_add_u32_e32 v149, s59, v146
	v_add_u32_e32 v150, 0, v3
	s_movk_i32 s60, 0x1600
	s_barrier
	s_branch .LBB0_806

; #define PG8_STAGE(bufoff, gbase, voff) do { _Pragma("unroll") for (int _i = 0; _i < 2; ++_i) \
;         __builtin_amdgcn_global_load_lds((const unsigned*)((const char*)(gbase) + (voff)[_i]), (PG8_LAS unsigned*)(lds + (bufoff) + ldsw + _i * 8192), 16, 0, 0); } while (0)
; #define PG8_LDA(dst, b, h) do { _Pragma("unroll") for (int m = 0; m < 4; ++m) _Pragma("unroll") for (int k = 0; k < 2; ++k) dst[m][k] = *(const PG8_LAS bf16x8*)(lds + PG8_SA(b, h) + aoff + m * 2048 + k * 1024); } while (0)
; #define PG8_LDB(dst, b, h) do { _Pragma("unroll") for (int n = 0; n < 2; ++n) _Pragma("unroll") for (int k = 0; k < 2; ++k) dst[n][k] = *(const PG8_LAS bf16x8*)(lds + PG8_SB(b, h) + boff + n * 2048 + k * 1024); } while (0)
; #define PG8_MMA(ai, bj, At, Bt) do { __builtin_amdgcn_s_setprio(1); _Pragma("unroll") for (int m = 0; m < 4; ++m) _Pragma("unroll") for (int n = 0; n < 2; ++n) _Pragma("unroll") for (int k = 0; k < 2; ++k) \
;         acc[ai][bj][m][n] = __builtin_amdgcn_mfma_f32_16x16x32_bf16(Bt[n][k], At[m][k], acc[ai][bj][m][n], 0, 0, 0); __builtin_amdgcn_s_setprio(0); } while (0)
; #define PG8_WAIT_V(n) asm volatile("s_waitcnt vmcnt(" #n ")" ::: "memory")
; #define PG8_WAIT_L(n) asm volatile("s_waitcnt lgkmcnt(" #n ")" ::: "memory")
; #define PG8_BAR __builtin_amdgcn_s_barrier()
; #define PG8_SCHED __builtin_amdgcn_sched_barrier(0)
; template <class Epi, class Sched, bool ALIGN_EPI = false, bool SP2 = false>
; __device__ __forceinline__ void gemm_phase(PG8_LAS unsigned char* lds, const Gemm g, const Sched& S, const Epi& E, const int tid) {
;     ...
;             PG8_LDB(B0, 0, 0); PG8_LDB(B1, 0, 1); PG8_SCHED; PG8_LDA(At, 0, 0); PG8_STAGE(PG8_SA(1, 1), a1 + hstep, voffA);
;             PG8_WAIT_V(8); PG8_WAIT_L(0); PG8_BAR; PG8_MMA(0, 0, At, B0); PG8_MMA(0, 1, At, B1); PG8_BAR; PG8_SCHED;
;             PG8_LDA(At, 0, 1); PG8_STAGE(PG8_SB(0, 0), b2, voffB); PG8_STAGE(PG8_SB(0, 1), b2 + hstep, voffB); PG8_STAGE(PG8_SA(0, 0), a2, voffA);
;             PG8_WAIT_V(8); PG8_WAIT_L(0); PG8_BAR; PG8_MMA(1, 0, At, B0); PG8_MMA(1, 1, At, B1); PG8_BAR; PG8_SCHED;
.LBB0_813:
	ds_read_b128 v[152:155], v148
	ds_read_b128 v[156:159], v148 offset:1024
	ds_read_b128 v[160:163], v148 offset:2048
	ds_read_b128 v[164:167], v148 offset:3072
	ds_read_b128 v[168:171], v149
	ds_read_b128 v[172:175], v149 offset:1024
	ds_read_b128 v[176:179], v149 offset:2048
	ds_read_b128 v[180:183], v149 offset:3072
	s_add_u32 s26, s24, 0xfffc0080
	s_addc_u32 s27, s25, -1
	s_cmp_eq_u32 s65, 12
	s_cselect_b32 s29, s17, s27
	s_cselect_b32 s28, s33, s26
	s_cselect_b32 s27, s15, s64
	s_cselect_b32 s26, s62, s63
	s_add_i32 m0, s23, 0xc000
	ds_read_b128 v[184:187], v150
	ds_read_b128 v[188:191], v150 offset:1024
	ds_read_b128 v[192:195], v150 offset:2048
	ds_read_b128 v[196:199], v150 offset:3072
	ds_read_b128 v[200:203], v150 offset:4096
	ds_read_b128 v[204:207], v150 offset:5120
	ds_read_b128 v[208:211], v150 offset:6144
	ds_read_b128 v[212:215], v150 offset:7168
	global_load_lds_dwordx4 v136, s[24:25]
	s_add_i32 m0, s23, 0xe000
	s_nop 0
	global_load_lds_dwordx4 v138, s[24:25]
	s_waitcnt vmcnt(8)
	s_waitcnt lgkmcnt(0)
	s_barrier
	s_setprio 1
	s_waitcnt lgkmcnt(0)
	v_mfma_f32_16x16x32_bf16 v[124:127], v[152:155], v[184:187], v[124:127]
	v_mfma_f32_16x16x32_bf16 v[116:119], v[160:163], v[184:187], v[116:119]
	v_mfma_f32_16x16x32_bf16 v[108:111], v[152:155], v[192:195], v[108:111]
	v_mfma_f32_16x16x32_bf16 v[100:103], v[160:163], v[192:195], v[100:103]
	v_mfma_f32_16x16x32_bf16 v[92:95], v[152:155], v[200:203], v[92:95]
	v_mfma_f32_16x16x32_bf16 v[84:87], v[160:163], v[200:203], v[84:87]
	v_mfma_f32_16x16x32_bf16 v[76:79], v[152:155], v[208:211], v[76:79]
	v_mfma_f32_16x16x32_bf16 v[68:71], v[160:163], v[208:211], v[68:71]
	v_mfma_f32_16x16x32_bf16 v[124:127], v[156:159], v[188:191], v[124:127]
	v_mfma_f32_16x16x32_bf16 v[116:119], v[164:167], v[188:191], v[116:119]
	v_mfma_f32_16x16x32_bf16 v[108:111], v[156:159], v[196:199], v[108:111]
	v_mfma_f32_16x16x32_bf16 v[100:103], v[164:167], v[196:199], v[100:103]
	v_mfma_f32_16x16x32_bf16 v[92:95], v[156:159], v[204:207], v[92:95]
	v_mfma_f32_16x16x32_bf16 v[84:87], v[164:167], v[204:207], v[84:87]
	v_mfma_f32_16x16x32_bf16 v[76:79], v[156:159], v[212:215], v[76:79]
	v_mfma_f32_16x16x32_bf16 v[68:71], v[164:167], v[212:215], v[68:71]
	s_setprio 0
	s_setprio 1
	v_mfma_f32_16x16x32_bf16 v[120:123], v[168:171], v[184:187], v[120:123]
	v_mfma_f32_16x16x32_bf16 v[112:115], v[176:179], v[184:187], v[112:115]
	v_mfma_f32_16x16x32_bf16 v[104:107], v[168:171], v[192:195], v[104:107]
	v_mfma_f32_16x16x32_bf16 v[96:99], v[176:179], v[192:195], v[96:99]
	v_mfma_f32_16x16x32_bf16 v[88:91], v[168:171], v[200:203], v[88:91]
	v_mfma_f32_16x16x32_bf16 v[80:83], v[176:179], v[200:203], v[80:83]
	v_mfma_f32_16x16x32_bf16 v[72:75], v[168:171], v[208:211], v[72:75]
	v_mfma_f32_16x16x32_bf16 v[64:67], v[176:179], v[208:211], v[64:67]
	v_mfma_f32_16x16x32_bf16 v[120:123], v[172:175], v[188:191], v[120:123]
	v_mfma_f32_16x16x32_bf16 v[112:115], v[180:183], v[188:191], v[112:115]
	v_mfma_f32_16x16x32_bf16 v[104:107], v[172:175], v[196:199], v[104:107]
	v_mfma_f32_16x16x32_bf16 v[96:99], v[180:183], v[196:199], v[96:99]
	v_mfma_f32_16x16x32_bf16 v[88:91], v[172:175], v[204:207], v[88:91]
	v_mfma_f32_16x16x32_bf16 v[80:83], v[180:183], v[204:207], v[80:83]
	v_mfma_f32_16x16x32_bf16 v[72:75], v[172:175], v[212:215], v[72:75]
	v_mfma_f32_16x16x32_bf16 v[64:67], v[180:183], v[212:215], v[64:67]
	s_setprio 0
	s_barrier
	s_add_i32 s66, s58, s50
	v_lshl_add_u64 v[216:217], s[26:27], 0, v[130:131]
	s_mov_b32 m0, s66
	ds_read_b128 v[184:187], v150 offset:16384
	ds_read_b128 v[188:191], v150 offset:17408
	ds_read_b128 v[192:195], v150 offset:18432
	ds_read_b128 v[196:199], v150 offset:19456
	ds_read_b128 v[200:203], v150 offset:20480
	ds_read_b128 v[204:207], v150 offset:21504
	ds_read_b128 v[208:211], v150 offset:22528
	ds_read_b128 v[212:215], v150 offset:23552
	global_load_lds_dwordx4 v[216:217], off
	s_add_i32 m0, s66, 0x2000
	s_add_u32 s66, s26, 0x40000
	v_lshl_add_u64 v[218:219], s[26:27], 0, v[134:135]
	s_addc_u32 s67, s27, 0
	s_add_i32 s72, s59, s50
	global_load_lds_dwordx4 v[218:219], off
	s_mov_b32 m0, s72
	v_lshl_add_u64 v[222:223], s[28:29], 0, v[132:133]
	global_load_lds_dwordx4 v130, s[66:67]
	s_add_i32 m0, s72, 0x2000
	s_nop 0
	global_load_lds_dwordx4 v134, s[66:67]
	v_lshl_add_u64 v[220:221], s[28:29], 0, v[128:129]
	s_mov_b32 m0, s23
	s_nop 0
	global_load_lds_dwordx4 v[220:221], off
	s_mov_b32 m0, s51
	s_nop 0
	global_load_lds_dwordx4 v[222:223], off
	s_waitcnt vmcnt(8)
	s_waitcnt lgkmcnt(0)
	s_barrier
; #define PG8_STAGE(bufoff, gbase, voff) do { _Pragma("unroll") for (int _i = 0; _i < 2; ++_i) \
;         __builtin_amdgcn_global_load_lds((const unsigned*)((const char*)(gbase) + (voff)[_i]), (PG8_LAS unsigned*)(lds + (bufoff) + ldsw + _i * 8192), 16, 0, 0); } while (0)
; #define PG8_LDA(dst, b, h) do { _Pragma("unroll") for (int m = 0; m < 4; ++m) _Pragma("unroll") for (int k = 0; k < 2; ++k) dst[m][k] = *(const PG8_LAS bf16x8*)(lds + PG8_SA(b, h) + aoff + m * 2048 + k * 1024); } while (0)
; #define PG8_LDB(dst, b, h) do { _Pragma("unroll") for (int n = 0; n < 2; ++n) _Pragma("unroll") for (int k = 0; k < 2; ++k) dst[n][k] = *(const PG8_LAS bf16x8*)(lds + PG8_SB(b, h) + boff + n * 2048 + k * 1024); } while (0)
; #define PG8_MMA(ai, bj, At, Bt) do { __builtin_amdgcn_s_setprio(1); _Pragma("unroll") for (int m = 0; m < 4; ++m) _Pragma("unroll") for (int n = 0; n < 2; ++n) _Pragma("unroll") for (int k = 0; k < 2; ++k) \
;         acc[ai][bj][m][n] = __builtin_amdgcn_mfma_f32_16x16x32_bf16(Bt[n][k], At[m][k], acc[ai][bj][m][n], 0, 0, 0); __builtin_amdgcn_s_setprio(0); } while (0)
; #define PG8_WAIT_V(n) asm volatile("s_waitcnt vmcnt(" #n ")" ::: "memory")
; #define PG8_WAIT_L(n) asm volatile("s_waitcnt lgkmcnt(" #n ")" ::: "memory")
; #define PG8_BAR __builtin_amdgcn_s_barrier()
; #define PG8_SCHED __builtin_amdgcn_sched_barrier(0)
; template <class Epi, class Sched, bool ALIGN_EPI = false, bool SP2 = false>
; __device__ __forceinline__ void gemm_phase(PG8_LAS unsigned char* lds, const Gemm g, const Sched& S, const Epi& E, const int tid) {
;     ...
;             PG8_WAIT_V(8); PG8_WAIT_L(0); PG8_BAR; PG8_MMA(1, 0, At, B0); PG8_MMA(1, 1, At, B1); PG8_BAR; PG8_SCHED;
;             PG8_LDB(B0, 1, 0); PG8_LDB(B1, 1, 1); PG8_SCHED; PG8_LDA(At, 1, 0); PG8_STAGE(PG8_SA(0, 1), a2 + hstep, voffA);
;             PG8_WAIT_V(8); PG8_WAIT_L(0); PG8_BAR; PG8_MMA(0, 0, At, B0); PG8_MMA(0, 1, At, B1); PG8_BAR; PG8_SCHED;
	s_setprio 1
	s_waitcnt lgkmcnt(0)
	v_mfma_f32_16x16x32_bf16 v[60:63], v[152:155], v[184:187], v[60:63]
	v_mfma_f32_16x16x32_bf16 v[52:55], v[160:163], v[184:187], v[52:55]
	v_mfma_f32_16x16x32_bf16 v[44:47], v[152:155], v[192:195], v[44:47]
	v_mfma_f32_16x16x32_bf16 v[36:39], v[160:163], v[192:195], v[36:39]
	v_mfma_f32_16x16x32_bf16 v[28:31], v[152:155], v[200:203], v[28:31]
	v_mfma_f32_16x16x32_bf16 v[20:23], v[160:163], v[200:203], v[20:23]
	v_mfma_f32_16x16x32_bf16 v[12:15], v[152:155], v[208:211], v[12:15]
	v_mfma_f32_16x16x32_bf16 v[4:7], v[160:163], v[208:211], v[4:7]
	v_mfma_f32_16x16x32_bf16 v[60:63], v[156:159], v[188:191], v[60:63]
	v_mfma_f32_16x16x32_bf16 v[52:55], v[164:167], v[188:191], v[52:55]
	v_mfma_f32_16x16x32_bf16 v[44:47], v[156:159], v[196:199], v[44:47]
	v_mfma_f32_16x16x32_bf16 v[36:39], v[164:167], v[196:199], v[36:39]
	v_mfma_f32_16x16x32_bf16 v[28:31], v[156:159], v[204:207], v[28:31]
	v_mfma_f32_16x16x32_bf16 v[20:23], v[164:167], v[204:207], v[20:23]
	v_mfma_f32_16x16x32_bf16 v[12:15], v[156:159], v[212:215], v[12:15]
	v_mfma_f32_16x16x32_bf16 v[4:7], v[164:167], v[212:215], v[4:7]
	s_setprio 0
	s_setprio 1
	v_mfma_f32_16x16x32_bf16 v[56:59], v[168:171], v[184:187], v[56:59]
	v_mfma_f32_16x16x32_bf16 v[48:51], v[176:179], v[184:187], v[48:51]
	v_mfma_f32_16x16x32_bf16 v[40:43], v[168:171], v[192:195], v[40:43]
	v_mfma_f32_16x16x32_bf16 v[32:35], v[176:179], v[192:195], v[32:35]
	v_mfma_f32_16x16x32_bf16 v[24:27], v[168:171], v[200:203], v[24:27]
	v_mfma_f32_16x16x32_bf16 v[16:19], v[176:179], v[200:203], v[16:19]
	v_mfma_f32_16x16x32_bf16 v[8:11], v[168:171], v[208:211], v[8:11]
	v_mfma_f32_16x16x32_bf16 v[0:3], v[176:179], v[208:211], v[0:3]
	v_mfma_f32_16x16x32_bf16 v[56:59], v[172:175], v[188:191], v[56:59]
	v_mfma_f32_16x16x32_bf16 v[48:51], v[180:183], v[188:191], v[48:51]
	v_mfma_f32_16x16x32_bf16 v[40:43], v[172:175], v[196:199], v[40:43]
	v_mfma_f32_16x16x32_bf16 v[32:35], v[180:183], v[196:199], v[32:35]
	v_mfma_f32_16x16x32_bf16 v[24:27], v[172:175], v[204:207], v[24:27]
	v_mfma_f32_16x16x32_bf16 v[16:19], v[180:183], v[204:207], v[16:19]
	v_mfma_f32_16x16x32_bf16 v[8:11], v[172:175], v[212:215], v[8:11]
	v_mfma_f32_16x16x32_bf16 v[0:3], v[180:183], v[212:215], v[0:3]
	s_setprio 0
	s_barrier
	s_add_i32 s66, 0, 0x18000
	v_add_u32_e32 v151, s66, v146
	s_add_i32 s67, 0, 0x1c000
	ds_read_b128 v[152:155], v151
	ds_read_b128 v[156:159], v151 offset:1024
	ds_read_b128 v[160:163], v151 offset:2048
	ds_read_b128 v[164:167], v151 offset:3072
	v_add_u32_e32 v151, s67, v146
	ds_read_b128 v[168:171], v151
	ds_read_b128 v[172:175], v151 offset:1024
	ds_read_b128 v[176:179], v151 offset:2048
	ds_read_b128 v[180:183], v151 offset:3072
	s_add_u32 s28, s28, 0x40000
	s_addc_u32 s29, s29, 0
	s_mov_b32 m0, s52
	ds_read_b128 v[184:187], v150 offset:32768
	ds_read_b128 v[188:191], v150 offset:33792
	ds_read_b128 v[192:195], v150 offset:34816
	ds_read_b128 v[196:199], v150 offset:35840
	ds_read_b128 v[200:203], v150 offset:36864
	ds_read_b128 v[204:207], v150 offset:37888
	ds_read_b128 v[208:211], v150 offset:38912
	ds_read_b128 v[212:215], v150 offset:39936
	global_load_lds_dwordx4 v128, s[28:29]
	v_lshl_add_u64 v[224:225], s[28:29], 0, v[132:133]
	s_mov_b32 m0, s53
	s_nop 0
	global_load_lds_dwordx4 v[224:225], off
	s_waitcnt vmcnt(8)
	s_waitcnt lgkmcnt(0)
	s_barrier
	s_setprio 1
	s_waitcnt lgkmcnt(0)
	v_mfma_f32_16x16x32_bf16 v[124:127], v[152:155], v[184:187], v[124:127]
	v_mfma_f32_16x16x32_bf16 v[116:119], v[160:163], v[184:187], v[116:119]
	v_mfma_f32_16x16x32_bf16 v[108:111], v[152:155], v[192:195], v[108:111]
	v_mfma_f32_16x16x32_bf16 v[100:103], v[160:163], v[192:195], v[100:103]
	v_mfma_f32_16x16x32_bf16 v[92:95], v[152:155], v[200:203], v[92:95]
	v_mfma_f32_16x16x32_bf16 v[84:87], v[160:163], v[200:203], v[84:87]
	v_mfma_f32_16x16x32_bf16 v[76:79], v[152:155], v[208:211], v[76:79]
	v_mfma_f32_16x16x32_bf16 v[68:71], v[160:163], v[208:211], v[68:71]
	v_mfma_f32_16x16x32_bf16 v[124:127], v[156:159], v[188:191], v[124:127]
	v_mfma_f32_16x16x32_bf16 v[116:119], v[164:167], v[188:191], v[116:119]
	v_mfma_f32_16x16x32_bf16 v[108:111], v[156:159], v[196:199], v[108:111]
	v_mfma_f32_16x16x32_bf16 v[100:103], v[164:167], v[196:199], v[100:103]
	v_mfma_f32_16x16x32_bf16 v[92:95], v[156:159], v[204:207], v[92:95]
	v_mfma_f32_16x16x32_bf16 v[84:87], v[164:167], v[204:207], v[84:87]
	v_mfma_f32_16x16x32_bf16 v[76:79], v[156:159], v[212:215], v[76:79]
	v_mfma_f32_16x16x32_bf16 v[68:71], v[164:167], v[212:215], v[68:71]
	s_setprio 0
	s_setprio 1
	v_mfma_f32_16x16x32_bf16 v[120:123], v[168:171], v[184:187], v[120:123]
	v_mfma_f32_16x16x32_bf16 v[112:115], v[176:179], v[184:187], v[112:115]
	v_mfma_f32_16x16x32_bf16 v[104:107], v[168:171], v[192:195], v[104:107]
	v_mfma_f32_16x16x32_bf16 v[96:99], v[176:179], v[192:195], v[96:99]
	v_mfma_f32_16x16x32_bf16 v[88:91], v[168:171], v[200:203], v[88:91]
	v_mfma_f32_16x16x32_bf16 v[80:83], v[176:179], v[200:203], v[80:83]
	v_mfma_f32_16x16x32_bf16 v[72:75], v[168:171], v[208:211], v[72:75]
	v_mfma_f32_16x16x32_bf16 v[64:67], v[176:179], v[208:211], v[64:67]
	v_mfma_f32_16x16x32_bf16 v[120:123], v[172:175], v[188:191], v[120:123]
	v_mfma_f32_16x16x32_bf16 v[112:115], v[180:183], v[188:191], v[112:115]
	v_mfma_f32_16x16x32_bf16 v[104:107], v[172:175], v[196:199], v[104:107]
	v_mfma_f32_16x16x32_bf16 v[96:99], v[180:183], v[196:199], v[96:99]
	v_mfma_f32_16x16x32_bf16 v[88:91], v[172:175], v[204:207], v[88:91]
	v_mfma_f32_16x16x32_bf16 v[80:83], v[180:183], v[204:207], v[80:83]
	v_mfma_f32_16x16x32_bf16 v[72:75], v[172:175], v[212:215], v[72:75]
	v_mfma_f32_16x16x32_bf16 v[64:67], v[180:183], v[212:215], v[64:67]
	s_setprio 0
	s_barrier
; #define PG8_STAGE(bufoff, gbase, voff) do { _Pragma("unroll") for (int _i = 0; _i < 2; ++_i) \
;         __builtin_amdgcn_global_load_lds((const unsigned*)((const char*)(gbase) + (voff)[_i]), (PG8_LAS unsigned*)(lds + (bufoff) + ldsw + _i * 8192), 16, 0, 0); } while (0)
; #define PG8_LDA(dst, b, h) do { _Pragma("unroll") for (int m = 0; m < 4; ++m) _Pragma("unroll") for (int k = 0; k < 2; ++k) dst[m][k] = *(const PG8_LAS bf16x8*)(lds + PG8_SA(b, h) + aoff + m * 2048 + k * 1024); } while (0)
; #define PG8_MMA(ai, bj, At, Bt) do { __builtin_amdgcn_s_setprio(1); _Pragma("unroll") for (int m = 0; m < 4; ++m) _Pragma("unroll") for (int n = 0; n < 2; ++n) _Pragma("unroll") for (int k = 0; k < 2; ++k) \
;         acc[ai][bj][m][n] = __builtin_amdgcn_mfma_f32_16x16x32_bf16(Bt[n][k], At[m][k], acc[ai][bj][m][n], 0, 0, 0); __builtin_amdgcn_s_setprio(0); } while (0)
; #define PG8_WAIT_V(n) asm volatile("s_waitcnt vmcnt(" #n ")" ::: "memory")
; #define PG8_WAIT_L(n) asm volatile("s_waitcnt lgkmcnt(" #n ")" ::: "memory")
; #define PG8_BAR __builtin_amdgcn_s_barrier()
; #define PG8_SCHED __builtin_amdgcn_sched_barrier(0)
; template <class Epi, class Sched, bool ALIGN_EPI = false, bool SP2 = false>
; __device__ __forceinline__ void gemm_phase(PG8_LAS unsigned char* lds, const Gemm g, const Sched& S, const Epi& E, const int tid) {
;     ...
;         for (int t = 0; t < nt; t += 2) {
;             const bool last = (t == nt - 2);
;             const char* a1 = cA + (size_t)(t + 1) * kstep;
;             const char* a2 = last ? nA : cA + (size_t)(t + 2) * kstep; const char* b2 = last ? nB : cB + (size_t)(t + 2) * kstep;
;     ...
;             PG8_LDA(At, 1, 1); PG8_STAGE(PG8_SB(1, 0), b3, voffB); PG8_STAGE(PG8_SB(1, 1), b3 + hstep, voffB); PG8_STAGE(PG8_SA(1, 0), a3, voffA);
;             PG8_WAIT_V(8); PG8_WAIT_L(0); PG8_BAR; PG8_MMA(1, 0, At, B0); PG8_MMA(1, 1, At, B1); PG8_BAR; PG8_SCHED;
	s_add_i32 s28, s66, s50
	v_lshl_add_u64 v[216:217], v[216:217], 0, s[10:11]
	s_mov_b32 m0, s28
	ds_read_b128 v[184:187], v150 offset:49152
	ds_read_b128 v[188:191], v150 offset:50176
	ds_read_b128 v[192:195], v150 offset:51200
	ds_read_b128 v[196:199], v150 offset:52224
	ds_read_b128 v[200:203], v150 offset:53248
	ds_read_b128 v[204:207], v150 offset:54272
	ds_read_b128 v[208:211], v150 offset:55296
	ds_read_b128 v[212:215], v150 offset:56320
	global_load_lds_dwordx4 v[216:217], off
	s_add_i32 m0, s28, 0x2000
	s_add_u32 s26, s26, 0x40080
	v_lshl_add_u64 v[216:217], v[218:219], 0, s[10:11]
	s_addc_u32 s27, s27, 0
	s_add_i32 s28, s67, s50
	global_load_lds_dwordx4 v[216:217], off
	s_mov_b32 m0, s28
	s_nop 0
	global_load_lds_dwordx4 v130, s[26:27]
	s_add_i32 m0, s28, 0x2000
	s_nop 0
	global_load_lds_dwordx4 v134, s[26:27]
	v_lshl_add_u64 v[216:217], v[220:221], 0, s[10:11]
	s_mov_b32 m0, s55
	s_nop 0
	global_load_lds_dwordx4 v[216:217], off
	v_lshl_add_u64 v[216:217], v[222:223], 0, s[10:11]
	s_mov_b32 m0, s56
	s_nop 0
	global_load_lds_dwordx4 v[216:217], off
	s_waitcnt vmcnt(8)
	s_waitcnt lgkmcnt(0)
	s_barrier
	s_setprio 1
	s_waitcnt lgkmcnt(0)
	v_mfma_f32_16x16x32_bf16 v[60:63], v[152:155], v[184:187], v[60:63]
	v_mfma_f32_16x16x32_bf16 v[52:55], v[160:163], v[184:187], v[52:55]
	v_mfma_f32_16x16x32_bf16 v[44:47], v[152:155], v[192:195], v[44:47]
	v_mfma_f32_16x16x32_bf16 v[36:39], v[160:163], v[192:195], v[36:39]
	v_mfma_f32_16x16x32_bf16 v[28:31], v[152:155], v[200:203], v[28:31]
	v_mfma_f32_16x16x32_bf16 v[20:23], v[160:163], v[200:203], v[20:23]
	v_mfma_f32_16x16x32_bf16 v[12:15], v[152:155], v[208:211], v[12:15]
	v_mfma_f32_16x16x32_bf16 v[4:7], v[160:163], v[208:211], v[4:7]
	v_mfma_f32_16x16x32_bf16 v[60:63], v[156:159], v[188:191], v[60:63]
	v_mfma_f32_16x16x32_bf16 v[52:55], v[164:167], v[188:191], v[52:55]
	v_mfma_f32_16x16x32_bf16 v[44:47], v[156:159], v[196:199], v[44:47]
	v_mfma_f32_16x16x32_bf16 v[36:39], v[164:167], v[196:199], v[36:39]
	v_mfma_f32_16x16x32_bf16 v[28:31], v[156:159], v[204:207], v[28:31]
	v_mfma_f32_16x16x32_bf16 v[20:23], v[164:167], v[204:207], v[20:23]
	v_mfma_f32_16x16x32_bf16 v[12:15], v[156:159], v[212:215], v[12:15]
	v_mfma_f32_16x16x32_bf16 v[4:7], v[164:167], v[212:215], v[4:7]
	s_setprio 0
	s_setprio 1
	v_mfma_f32_16x16x32_bf16 v[56:59], v[168:171], v[184:187], v[56:59]
	v_mfma_f32_16x16x32_bf16 v[48:51], v[176:179], v[184:187], v[48:51]
	v_mfma_f32_16x16x32_bf16 v[40:43], v[168:171], v[192:195], v[40:43]
	v_mfma_f32_16x16x32_bf16 v[32:35], v[176:179], v[192:195], v[32:35]
	v_mfma_f32_16x16x32_bf16 v[24:27], v[168:171], v[200:203], v[24:27]
	v_mfma_f32_16x16x32_bf16 v[16:19], v[176:179], v[200:203], v[16:19]
	v_mfma_f32_16x16x32_bf16 v[8:11], v[168:171], v[208:211], v[8:11]
	v_mfma_f32_16x16x32_bf16 v[0:3], v[176:179], v[208:211], v[0:3]
	v_mfma_f32_16x16x32_bf16 v[56:59], v[172:175], v[188:191], v[56:59]
	v_mfma_f32_16x16x32_bf16 v[48:51], v[180:183], v[188:191], v[48:51]
	v_mfma_f32_16x16x32_bf16 v[40:43], v[172:175], v[196:199], v[40:43]
	v_mfma_f32_16x16x32_bf16 v[32:35], v[180:183], v[196:199], v[32:35]
	v_mfma_f32_16x16x32_bf16 v[24:27], v[172:175], v[204:207], v[24:27]
	v_mfma_f32_16x16x32_bf16 v[16:19], v[180:183], v[204:207], v[16:19]
	v_mfma_f32_16x16x32_bf16 v[8:11], v[172:175], v[212:215], v[8:11]
	v_mfma_f32_16x16x32_bf16 v[0:3], v[180:183], v[212:215], v[0:3]
	s_setprio 0
	s_barrier
	s_add_i32 s65, s65, 2
	s_add_u32 s24, s24, 0x100
	s_addc_u32 s25, s25, 0
	s_add_u32 s63, s63, 0x100
	s_addc_u32 s64, s64, 0
	s_cmp_gt_u32 s65, 13
	s_cbranch_scc0 .LBB0_813
	s_and_b64 vcc, exec, s[12:13]
	s_cbranch_vccz .LBB0_816
	s_barrier

; #define PG8_STAGE(bufoff, gbase, voff) do { _Pragma("unroll") for (int _i = 0; _i < 2; ++_i) \
;         __builtin_amdgcn_global_load_lds((const unsigned*)((const char*)(gbase) + (voff)[_i]), (PG8_LAS unsigned*)(lds + (bufoff) + ldsw + _i * 8192), 16, 0, 0); } while (0)
; #define PG8_WAIT_V(n) asm volatile("s_waitcnt vmcnt(" #n ")" ::: "memory")
; #define PG8_BAR __builtin_amdgcn_s_barrier()
; template <class Epi, class Sched, bool ALIGN_EPI = false, bool SP2 = false>
; __device__ __forceinline__ void gemm_phase(PG8_LAS unsigned char* lds, const Gemm g, const Sched& S, const Epi& E, const int tid) {
;     const int wid = __builtin_amdgcn_readfirstlane(tid >> 6), lane = tid & 63, wr = wid >> 2, wc = wid & 3, fr = lane & 15, fq = lane >> 4;
;     const int K = g.K, nt = K / BK;
;     unsigned voffA[2], voffB[2];
; #pragma unroll
;     for (int i = 0; i < 2; ++i) { int R, C; stage_rc(tid * 16 + i * 8192, R, C); const int Rb = Epi::PERM ? ((R & ~31) + perm32(R & 31)) : R;
;         voffA[i] = (unsigned)(R * K + C) * 2u; voffB[i] = (unsigned)(Rb * K + C) * 2u; }
;     const size_t kstep = (size_t)(BK * 2);
;     const size_t hstep = (size_t)HALF * K * 2;
;     const size_t tstep = 2 * hstep;
;     const unsigned ldsw = (unsigned)wid * 1024u;
;     const int aoff = lds_byte(wr * 64 + fr, fq * 8), boff = lds_byte(wc * 32 + fr, fq * 8);
;     ...
;         PG8_WAIT_V(2); PG8_BAR;
;         PG8_STAGE(PG8_SB(1, 0), cB + kstep, voffB); PG8_STAGE(PG8_SA(1, 0), cA + kstep, voffA); PG8_STAGE(PG8_SB(1, 1), cB + hstep + kstep, voffB);
;         PG8_WAIT_V(6); PG8_BAR;
.LBB0_975:
	s_lshl_b32 s1, s1, 5
	s_and_b32 s1, s1, 0x60
	s_lshl_b32 s17, s15, 13
	s_lshl_b32 s22, s1, 7
	s_add_u32 s41, s3, 0x8800000
	s_addc_u32 s42, s2, 0
	s_add_u32 s43, s3, 0x3005000
	s_mov_b64 s[12:13], 0x80
	s_addc_u32 s44, s2, 0
	s_add_i32 m0, s36, 0x18000
	v_lshl_add_u64 v[6:7], v[6:7], 0, s[12:13]
	s_waitcnt vmcnt(2)
	s_barrier
	global_load_lds_dwordx4 v[6:7], off
	v_lshl_add_u64 v[4:5], v[4:5], 0, s[12:13]
	s_add_i32 m0, s36, 0x1a000
	s_add_i32 s45, s36, 0x8000
	s_add_i32 s46, s36, 0xa000
	global_load_lds_dwordx4 v[4:5], off
	v_lshl_add_u64 v[0:1], v[0:1], 0, s[12:13]
	s_mov_b32 m0, s45
	s_add_u32 s2, s20, 0xb0080
	global_load_lds_dwordx4 v[0:1], off
	v_lshl_add_u64 v[0:1], v[2:3], 0, s[12:13]
	s_mov_b32 m0, s46
	s_addc_u32 s3, s21, 0
	global_load_lds_dwordx4 v[0:1], off
	s_add_i32 m0, s36, 0x1c000
	global_load_lds_dwordx4 v146, s[2:3]
	s_add_i32 m0, s36, 0x1e000
	v_lshlrev_b32_e32 v2, 2, v43
	global_load_lds_dwordx4 v150, s[2:3]
	v_lshlrev_b32_e32 v1, 1, v42
	v_lshl_or_b32 v0, s15, 6, v43
	v_lshl_or_b32 v1, v43, 6, v1
	v_and_b32_e32 v2, 32, v2
	v_bitop3_b32 v16, v1, s17, v2 bitop3:0xde
	v_bitop3_b32 v178, s22, v1, v2 bitop3:0xf6
	v_ashrrev_i32_e32 v1, 31, v0
	s_sext_i32_i8 s53, s16
	v_lshlrev_b64 v[152:153], 11, v[0:1]
	s_mov_b64 s[16:17], 0x40000
	v_lshl_add_u64 v[154:155], v[152:153], 0, s[16:17]
	s_mov_b64 s[16:17], 0x48000
	v_lshl_add_u64 v[156:157], v[152:153], 0, s[16:17]
	s_mov_b64 s[16:17], 0x50000
	v_or_b32_e32 v2, 16, v0
	v_or_b32_e32 v4, 32, v0
	v_or_b32_e32 v6, 48, v0
	v_lshl_add_u64 v[158:159], v[152:153], 0, s[16:17]
	s_mov_b64 s[16:17], 0x58000
	v_or_b32_e32 v179, s1, v42
	v_lshrrev_b32_e32 v1, 1, v8
	v_mul_lo_u32 v0, v10, s0
	s_mov_b32 s1, 0xb000
	v_lshl_add_u64 v[160:161], v[152:153], 0, s[16:17]
	v_mad_u64_u32 v[0:1], s[16:17], v1, s1, v[0:1]
	v_or_b32_e32 v0, v0, v9
	s_mov_b64 s[2:3], 0xb0080
	v_add_lshl_u32 v0, v0, v11, 1
	v_mov_b32_e32 v1, v147
	v_lshl_add_u64 v[168:169], v[0:1], 0, s[2:3]
	v_lshrrev_b32_e32 v1, 1, v12
	v_mul_lo_u32 v0, v13, s0
	v_mad_u64_u32 v[0:1], s[0:1], v1, s1, v[0:1]
	s_waitcnt vmcnt(6)
	s_cmpk_lt_u32 s14, 0x100
	v_or_b32_e32 v0, v0, v14
	s_cselect_b64 s[14:15], -1, 0
	v_ashrrev_i32_e32 v3, 31, v2
	v_ashrrev_i32_e32 v5, 31, v4
	v_ashrrev_i32_e32 v7, 31, v6
	v_add_lshl_u32 v0, v0, v15, 1
	v_mov_b32_e32 v1, v147
	s_add_i32 s48, 0, 0x10000
	s_add_i32 s49, 0, 0x14000
	s_ashr_i32 s47, s27, 31
	v_lshlrev_b64 v[162:163], 11, v[2:3]
	v_lshlrev_b64 v[164:165], 11, v[4:5]
	v_lshlrev_b64 v[166:167], 11, v[6:7]
	v_lshl_add_u64 v[170:171], v[0:1], 0, s[2:3]
	v_mov_b64_e32 v[172:173], 0x200
	v_mov_b64_e32 v[174:175], 0x1ff
	v_add_u32_e32 v180, s48, v178
	v_add_u32_e32 v181, s49, v178
	v_add_u32_e32 v182, 0, v16
	s_barrier
	s_branch .LBB0_978

; #define PG8_STAGE(bufoff, gbase, voff) do { _Pragma("unroll") for (int _i = 0; _i < 2; ++_i) \
;         __builtin_amdgcn_global_load_lds((const unsigned*)((const char*)(gbase) + (voff)[_i]), (PG8_LAS unsigned*)(lds + (bufoff) + ldsw + _i * 8192), 16, 0, 0); } while (0)
; #define PG8_LDA(dst, b, h) do { _Pragma("unroll") for (int m = 0; m < 4; ++m) _Pragma("unroll") for (int k = 0; k < 2; ++k) dst[m][k] = *(const PG8_LAS bf16x8*)(lds + PG8_SA(b, h) + aoff + m * 2048 + k * 1024); } while (0)
; #define PG8_LDB(dst, b, h) do { _Pragma("unroll") for (int n = 0; n < 2; ++n) _Pragma("unroll") for (int k = 0; k < 2; ++k) dst[n][k] = *(const PG8_LAS bf16x8*)(lds + PG8_SB(b, h) + boff + n * 2048 + k * 1024); } while (0)
; #define PG8_MMA(ai, bj, At, Bt) do { __builtin_amdgcn_s_setprio(1); _Pragma("unroll") for (int m = 0; m < 4; ++m) _Pragma("unroll") for (int n = 0; n < 2; ++n) _Pragma("unroll") for (int k = 0; k < 2; ++k) \
;         acc[ai][bj][m][n] = __builtin_amdgcn_mfma_f32_16x16x32_bf16(Bt[n][k], At[m][k], acc[ai][bj][m][n], 0, 0, 0); __builtin_amdgcn_s_setprio(0); } while (0)
; #define PG8_WAIT_V(n) asm volatile("s_waitcnt vmcnt(" #n ")" ::: "memory")
; #define PG8_WAIT_L(n) asm volatile("s_waitcnt lgkmcnt(" #n ")" ::: "memory")
; #define PG8_BAR __builtin_amdgcn_s_barrier()
; #define PG8_SCHED __builtin_amdgcn_sched_barrier(0)
; template <class Epi, class Sched, bool ALIGN_EPI = false, bool SP2 = false>
; __device__ __forceinline__ void gemm_phase(PG8_LAS unsigned char* lds, const Gemm g, const Sched& S, const Epi& E, const int tid) {
;     ...
;             const bool last = (t == nt - 2);
;             const char* a1 = cA + (size_t)(t + 1) * kstep;
;             const char* a2 = last ? nA : cA + (size_t)(t + 2) * kstep; const char* b2 = last ? nB : cB + (size_t)(t + 2) * kstep;
;             const char* a3 = a2 + kstep; const char* b3 = b2 + kstep;
;             if (last && has_next) S.a_ready(nxt);
;             if constexpr (SP2) {
;             PG8_LDB(B0, 0, 0); PG8_LDB(B1, 0, 1); PG8_SCHED; PG8_LDA(At, 0, 0); PG8_STAGE(PG8_SA(1, 1), a1 + hstep, voffA);
;             PG8_WAIT_V(8); PG8_WAIT_L(0); PG8_BAR; PG8_MMA(0, 0, At, B0); PG8_MMA(0, 1, At, B1); PG8_BAR; PG8_SCHED;
;             PG8_LDA(At, 0, 1); PG8_STAGE(PG8_SB(0, 0), b2, voffB); PG8_STAGE(PG8_SB(0, 1), b2 + hstep, voffB); PG8_STAGE(PG8_SA(0, 0), a2, voffA);
.LBB0_989:
	ds_read_b128 v[120:123], v180
	ds_read_b128 v[124:127], v180 offset:1024
	ds_read_b128 v[136:139], v180 offset:2048
	ds_read_b128 v[140:143], v180 offset:3072
	ds_read_b128 v[184:187], v181
	ds_read_b128 v[188:191], v181 offset:1024
	ds_read_b128 v[192:195], v181 offset:2048
	ds_read_b128 v[196:199], v181 offset:3072
	s_add_u32 s20, s18, 0x100
	s_addc_u32 s21, s19, 0
	s_cmp_eq_u32 s55, 40
	s_cselect_b32 s25, s3, s21
	s_cselect_b32 s24, s2, s20
	s_cselect_b32 s23, s17, s54
	s_cselect_b32 s22, s16, s33
	s_add_i32 m0, s36, 0xc000
	ds_read_b128 v[200:203], v182
	ds_read_b128 v[204:207], v182 offset:1024
	ds_read_b128 v[208:211], v182 offset:2048
	ds_read_b128 v[212:215], v182 offset:3072
	ds_read_b128 v[216:219], v182 offset:4096
	ds_read_b128 v[220:223], v182 offset:5120
	ds_read_b128 v[224:227], v182 offset:6144
	ds_read_b128 v[228:231], v182 offset:7168
	global_load_lds_dwordx4 v168, s[18:19]
	s_add_i32 m0, s36, 0xe000
	s_nop 0
	global_load_lds_dwordx4 v170, s[18:19]
	s_waitcnt vmcnt(8)
	s_waitcnt lgkmcnt(0)
	s_barrier
	s_setprio 1
	s_waitcnt lgkmcnt(0)
	v_mfma_f32_16x16x32_bf16 v[132:135], v[120:123], v[200:203], v[132:135]
	v_mfma_f32_16x16x32_bf16 v[128:131], v[136:139], v[200:203], v[128:131]
	v_mfma_f32_16x16x32_bf16 v[116:119], v[120:123], v[208:211], v[116:119]
	v_mfma_f32_16x16x32_bf16 v[104:107], v[136:139], v[208:211], v[104:107]
	v_mfma_f32_16x16x32_bf16 v[100:103], v[120:123], v[216:219], v[100:103]
	v_mfma_f32_16x16x32_bf16 v[88:91], v[136:139], v[216:219], v[88:91]
	v_mfma_f32_16x16x32_bf16 v[84:87], v[120:123], v[224:227], v[84:87]
	v_mfma_f32_16x16x32_bf16 v[72:75], v[136:139], v[224:227], v[72:75]
	v_mfma_f32_16x16x32_bf16 v[132:135], v[124:127], v[204:207], v[132:135]
	v_mfma_f32_16x16x32_bf16 v[128:131], v[140:143], v[204:207], v[128:131]
	v_mfma_f32_16x16x32_bf16 v[116:119], v[124:127], v[212:215], v[116:119]
	v_mfma_f32_16x16x32_bf16 v[104:107], v[140:143], v[212:215], v[104:107]
	v_mfma_f32_16x16x32_bf16 v[100:103], v[124:127], v[220:223], v[100:103]
	v_mfma_f32_16x16x32_bf16 v[88:91], v[140:143], v[220:223], v[88:91]
	v_mfma_f32_16x16x32_bf16 v[84:87], v[124:127], v[228:231], v[84:87]
	v_mfma_f32_16x16x32_bf16 v[72:75], v[140:143], v[228:231], v[72:75]
	s_setprio 0
	s_setprio 1
	v_mfma_f32_16x16x32_bf16 v[112:115], v[184:187], v[200:203], v[112:115]
	v_mfma_f32_16x16x32_bf16 v[108:111], v[192:195], v[200:203], v[108:111]
	v_mfma_f32_16x16x32_bf16 v[96:99], v[184:187], v[208:211], v[96:99]
	v_mfma_f32_16x16x32_bf16 v[92:95], v[192:195], v[208:211], v[92:95]
	v_mfma_f32_16x16x32_bf16 v[80:83], v[184:187], v[216:219], v[80:83]
	v_mfma_f32_16x16x32_bf16 v[76:79], v[192:195], v[216:219], v[76:79]
	v_mfma_f32_16x16x32_bf16 v[68:71], v[184:187], v[224:227], v[68:71]
	v_mfma_f32_16x16x32_bf16 v[64:67], v[192:195], v[224:227], v[64:67]
	v_mfma_f32_16x16x32_bf16 v[112:115], v[188:191], v[204:207], v[112:115]
	v_mfma_f32_16x16x32_bf16 v[108:111], v[196:199], v[204:207], v[108:111]
	v_mfma_f32_16x16x32_bf16 v[96:99], v[188:191], v[212:215], v[96:99]
	v_mfma_f32_16x16x32_bf16 v[92:95], v[196:199], v[212:215], v[92:95]
	v_mfma_f32_16x16x32_bf16 v[80:83], v[188:191], v[220:223], v[80:83]
	v_mfma_f32_16x16x32_bf16 v[76:79], v[196:199], v[220:223], v[76:79]
	v_mfma_f32_16x16x32_bf16 v[68:71], v[188:191], v[228:231], v[68:71]
	v_mfma_f32_16x16x32_bf16 v[64:67], v[196:199], v[228:231], v[64:67]
	s_setprio 0
	s_barrier
	s_add_i32 s18, s48, s35
	v_lshl_add_u64 v[176:177], s[22:23], 0, v[146:147]
	s_mov_b32 m0, s18
	ds_read_b128 v[200:203], v182 offset:16384
	ds_read_b128 v[204:207], v182 offset:17408
	ds_read_b128 v[208:211], v182 offset:18432
	ds_read_b128 v[212:215], v182 offset:19456
	ds_read_b128 v[216:219], v182 offset:20480
	ds_read_b128 v[220:223], v182 offset:21504
	ds_read_b128 v[224:227], v182 offset:22528
	ds_read_b128 v[228:231], v182 offset:23552
	global_load_lds_dwordx4 v[176:177], off
	s_add_i32 m0, s18, 0x2000
	s_add_u32 s18, s22, 0xb0000
	v_lshl_add_u64 v[232:233], s[22:23], 0, v[150:151]
	s_addc_u32 s19, s23, 0
	s_add_i32 s56, s49, s35
	global_load_lds_dwordx4 v[232:233], off
	s_mov_b32 m0, s56
	v_lshl_add_u64 v[236:237], s[24:25], 0, v[148:149]
	global_load_lds_dwordx4 v146, s[18:19]
	s_add_i32 m0, s56, 0x2000
	s_nop 0
	global_load_lds_dwordx4 v150, s[18:19]
	v_lshl_add_u64 v[234:235], s[24:25], 0, v[144:145]
	s_mov_b32 m0, s36
	s_nop 0
	global_load_lds_dwordx4 v[234:235], off
	s_mov_b32 m0, s37
	s_nop 0
	global_load_lds_dwordx4 v[236:237], off
	s_waitcnt vmcnt(8)
	s_waitcnt lgkmcnt(0)
	s_barrier
; #define PG8_STAGE(bufoff, gbase, voff) do { _Pragma("unroll") for (int _i = 0; _i < 2; ++_i) \
;         __builtin_amdgcn_global_load_lds((const unsigned*)((const char*)(gbase) + (voff)[_i]), (PG8_LAS unsigned*)(lds + (bufoff) + ldsw + _i * 8192), 16, 0, 0); } while (0)
; #define PG8_LDA(dst, b, h) do { _Pragma("unroll") for (int m = 0; m < 4; ++m) _Pragma("unroll") for (int k = 0; k < 2; ++k) dst[m][k] = *(const PG8_LAS bf16x8*)(lds + PG8_SA(b, h) + aoff + m * 2048 + k * 1024); } while (0)
; #define PG8_LDB(dst, b, h) do { _Pragma("unroll") for (int n = 0; n < 2; ++n) _Pragma("unroll") for (int k = 0; k < 2; ++k) dst[n][k] = *(const PG8_LAS bf16x8*)(lds + PG8_SB(b, h) + boff + n * 2048 + k * 1024); } while (0)
; #define PG8_MMA(ai, bj, At, Bt) do { __builtin_amdgcn_s_setprio(1); _Pragma("unroll") for (int m = 0; m < 4; ++m) _Pragma("unroll") for (int n = 0; n < 2; ++n) _Pragma("unroll") for (int k = 0; k < 2; ++k) \
;         acc[ai][bj][m][n] = __builtin_amdgcn_mfma_f32_16x16x32_bf16(Bt[n][k], At[m][k], acc[ai][bj][m][n], 0, 0, 0); __builtin_amdgcn_s_setprio(0); } while (0)
; #define PG8_WAIT_V(n) asm volatile("s_waitcnt vmcnt(" #n ")" ::: "memory")
; #define PG8_WAIT_L(n) asm volatile("s_waitcnt lgkmcnt(" #n ")" ::: "memory")
; #define PG8_BAR __builtin_amdgcn_s_barrier()
; #define PG8_SCHED __builtin_amdgcn_sched_barrier(0)
; template <class Epi, class Sched, bool ALIGN_EPI = false, bool SP2 = false>
; __device__ __forceinline__ void gemm_phase(PG8_LAS unsigned char* lds, const Gemm g, const Sched& S, const Epi& E, const int tid) {
;     ...
;             PG8_WAIT_V(8); PG8_WAIT_L(0); PG8_BAR; PG8_MMA(1, 0, At, B0); PG8_MMA(1, 1, At, B1); PG8_BAR; PG8_SCHED;
;             PG8_LDB(B0, 1, 0); PG8_LDB(B1, 1, 1); PG8_SCHED; PG8_LDA(At, 1, 0); PG8_STAGE(PG8_SA(0, 1), a2 + hstep, voffA);
;             PG8_WAIT_V(8); PG8_WAIT_L(0); PG8_BAR; PG8_MMA(0, 0, At, B0); PG8_MMA(0, 1, At, B1); PG8_BAR; PG8_SCHED;
	s_setprio 1
	s_waitcnt lgkmcnt(0)
	v_mfma_f32_16x16x32_bf16 v[60:63], v[120:123], v[200:203], v[60:63]
	v_mfma_f32_16x16x32_bf16 v[56:59], v[136:139], v[200:203], v[56:59]
	v_mfma_f32_16x16x32_bf16 v[52:55], v[120:123], v[208:211], v[52:55]
	v_mfma_f32_16x16x32_bf16 v[40:43], v[136:139], v[208:211], v[40:43]
	v_mfma_f32_16x16x32_bf16 v[36:39], v[120:123], v[216:219], v[36:39]
	v_mfma_f32_16x16x32_bf16 v[24:27], v[136:139], v[216:219], v[24:27]
	v_mfma_f32_16x16x32_bf16 v[20:23], v[120:123], v[224:227], v[20:23]
	v_mfma_f32_16x16x32_bf16 v[8:11], v[136:139], v[224:227], v[8:11]
	v_mfma_f32_16x16x32_bf16 v[60:63], v[124:127], v[204:207], v[60:63]
	v_mfma_f32_16x16x32_bf16 v[56:59], v[140:143], v[204:207], v[56:59]
	v_mfma_f32_16x16x32_bf16 v[52:55], v[124:127], v[212:215], v[52:55]
	v_mfma_f32_16x16x32_bf16 v[40:43], v[140:143], v[212:215], v[40:43]
	v_mfma_f32_16x16x32_bf16 v[36:39], v[124:127], v[220:223], v[36:39]
	v_mfma_f32_16x16x32_bf16 v[24:27], v[140:143], v[220:223], v[24:27]
	v_mfma_f32_16x16x32_bf16 v[20:23], v[124:127], v[228:231], v[20:23]
	v_mfma_f32_16x16x32_bf16 v[8:11], v[140:143], v[228:231], v[8:11]
	s_setprio 0
	s_setprio 1
	v_mfma_f32_16x16x32_bf16 v[48:51], v[184:187], v[200:203], v[48:51]
	v_mfma_f32_16x16x32_bf16 v[44:47], v[192:195], v[200:203], v[44:47]
	v_mfma_f32_16x16x32_bf16 v[32:35], v[184:187], v[208:211], v[32:35]
	v_mfma_f32_16x16x32_bf16 v[28:31], v[192:195], v[208:211], v[28:31]
	v_mfma_f32_16x16x32_bf16 v[16:19], v[184:187], v[216:219], v[16:19]
	v_mfma_f32_16x16x32_bf16 v[12:15], v[192:195], v[216:219], v[12:15]
	v_mfma_f32_16x16x32_bf16 v[4:7], v[184:187], v[224:227], v[4:7]
	v_mfma_f32_16x16x32_bf16 v[0:3], v[192:195], v[224:227], v[0:3]
	v_mfma_f32_16x16x32_bf16 v[48:51], v[188:191], v[204:207], v[48:51]
	v_mfma_f32_16x16x32_bf16 v[44:47], v[196:199], v[204:207], v[44:47]
	v_mfma_f32_16x16x32_bf16 v[32:35], v[188:191], v[212:215], v[32:35]
	v_mfma_f32_16x16x32_bf16 v[28:31], v[196:199], v[212:215], v[28:31]
	v_mfma_f32_16x16x32_bf16 v[16:19], v[188:191], v[220:223], v[16:19]
	v_mfma_f32_16x16x32_bf16 v[12:15], v[196:199], v[220:223], v[12:15]
	v_mfma_f32_16x16x32_bf16 v[4:7], v[188:191], v[228:231], v[4:7]
	v_mfma_f32_16x16x32_bf16 v[0:3], v[196:199], v[228:231], v[0:3]
	s_setprio 0
	s_barrier
	s_add_i32 s56, 0, 0x18000
	s_add_i32 s57, 0, 0x1c000
	v_add_u32_e32 v140, s56, v178
	v_add_u32_e32 v183, s57, v178
	ds_read_b128 v[120:123], v140
	ds_read_b128 v[124:127], v140 offset:1024
	ds_read_b128 v[136:139], v140 offset:2048
	ds_read_b128 v[140:143], v140 offset:3072
	ds_read_b128 v[184:187], v183
	ds_read_b128 v[188:191], v183 offset:1024
	ds_read_b128 v[192:195], v183 offset:2048
	ds_read_b128 v[196:199], v183 offset:3072
	s_add_u32 s18, s24, 0xb0000
	s_addc_u32 s19, s25, 0
	s_mov_b32 m0, s38
	ds_read_b128 v[200:203], v182 offset:32768
	ds_read_b128 v[204:207], v182 offset:33792
	ds_read_b128 v[208:211], v182 offset:34816
	ds_read_b128 v[212:215], v182 offset:35840
	ds_read_b128 v[216:219], v182 offset:36864
	ds_read_b128 v[220:223], v182 offset:37888
	ds_read_b128 v[224:227], v182 offset:38912
	ds_read_b128 v[228:231], v182 offset:39936
	global_load_lds_dwordx4 v144, s[18:19]
	v_lshl_add_u64 v[238:239], s[18:19], 0, v[148:149]
	s_mov_b32 m0, s39
	s_nop 0
	global_load_lds_dwordx4 v[238:239], off
	s_waitcnt vmcnt(8)
	s_waitcnt lgkmcnt(0)
	s_barrier
	s_setprio 1
	s_waitcnt lgkmcnt(0)
	v_mfma_f32_16x16x32_bf16 v[132:135], v[120:123], v[200:203], v[132:135]
	v_mfma_f32_16x16x32_bf16 v[128:131], v[136:139], v[200:203], v[128:131]
	v_mfma_f32_16x16x32_bf16 v[116:119], v[120:123], v[208:211], v[116:119]
	v_mfma_f32_16x16x32_bf16 v[104:107], v[136:139], v[208:211], v[104:107]
	v_mfma_f32_16x16x32_bf16 v[100:103], v[120:123], v[216:219], v[100:103]
	v_mfma_f32_16x16x32_bf16 v[88:91], v[136:139], v[216:219], v[88:91]
	v_mfma_f32_16x16x32_bf16 v[84:87], v[120:123], v[224:227], v[84:87]
	v_mfma_f32_16x16x32_bf16 v[72:75], v[136:139], v[224:227], v[72:75]
	v_mfma_f32_16x16x32_bf16 v[132:135], v[124:127], v[204:207], v[132:135]
	v_mfma_f32_16x16x32_bf16 v[128:131], v[140:143], v[204:207], v[128:131]
	v_mfma_f32_16x16x32_bf16 v[116:119], v[124:127], v[212:215], v[116:119]
	v_mfma_f32_16x16x32_bf16 v[104:107], v[140:143], v[212:215], v[104:107]
	v_mfma_f32_16x16x32_bf16 v[100:103], v[124:127], v[220:223], v[100:103]
	v_mfma_f32_16x16x32_bf16 v[88:91], v[140:143], v[220:223], v[88:91]
	v_mfma_f32_16x16x32_bf16 v[84:87], v[124:127], v[228:231], v[84:87]
	v_mfma_f32_16x16x32_bf16 v[72:75], v[140:143], v[228:231], v[72:75]
	s_setprio 0
	s_setprio 1
	v_mfma_f32_16x16x32_bf16 v[112:115], v[184:187], v[200:203], v[112:115]
	v_mfma_f32_16x16x32_bf16 v[108:111], v[192:195], v[200:203], v[108:111]
	v_mfma_f32_16x16x32_bf16 v[96:99], v[184:187], v[208:211], v[96:99]
	v_mfma_f32_16x16x32_bf16 v[92:95], v[192:195], v[208:211], v[92:95]
	v_mfma_f32_16x16x32_bf16 v[80:83], v[184:187], v[216:219], v[80:83]
	v_mfma_f32_16x16x32_bf16 v[76:79], v[192:195], v[216:219], v[76:79]
	v_mfma_f32_16x16x32_bf16 v[68:71], v[184:187], v[224:227], v[68:71]
	v_mfma_f32_16x16x32_bf16 v[64:67], v[192:195], v[224:227], v[64:67]
	v_mfma_f32_16x16x32_bf16 v[112:115], v[188:191], v[204:207], v[112:115]
	v_mfma_f32_16x16x32_bf16 v[108:111], v[196:199], v[204:207], v[108:111]
	v_mfma_f32_16x16x32_bf16 v[96:99], v[188:191], v[212:215], v[96:99]
	v_mfma_f32_16x16x32_bf16 v[92:95], v[196:199], v[212:215], v[92:95]
	v_mfma_f32_16x16x32_bf16 v[80:83], v[188:191], v[220:223], v[80:83]
	v_mfma_f32_16x16x32_bf16 v[76:79], v[196:199], v[220:223], v[76:79]
	v_mfma_f32_16x16x32_bf16 v[68:71], v[188:191], v[228:231], v[68:71]
	v_mfma_f32_16x16x32_bf16 v[64:67], v[196:199], v[228:231], v[64:67]
	s_setprio 0
	s_barrier
; #define PG8_STAGE(bufoff, gbase, voff) do { _Pragma("unroll") for (int _i = 0; _i < 2; ++_i) \
;         __builtin_amdgcn_global_load_lds((const unsigned*)((const char*)(gbase) + (voff)[_i]), (PG8_LAS unsigned*)(lds + (bufoff) + ldsw + _i * 8192), 16, 0, 0); } while (0)
; #define PG8_LDA(dst, b, h) do { _Pragma("unroll") for (int m = 0; m < 4; ++m) _Pragma("unroll") for (int k = 0; k < 2; ++k) dst[m][k] = *(const PG8_LAS bf16x8*)(lds + PG8_SA(b, h) + aoff + m * 2048 + k * 1024); } while (0)
; #define PG8_MMA(ai, bj, At, Bt) do { __builtin_amdgcn_s_setprio(1); _Pragma("unroll") for (int m = 0; m < 4; ++m) _Pragma("unroll") for (int n = 0; n < 2; ++n) _Pragma("unroll") for (int k = 0; k < 2; ++k) \
;         acc[ai][bj][m][n] = __builtin_amdgcn_mfma_f32_16x16x32_bf16(Bt[n][k], At[m][k], acc[ai][bj][m][n], 0, 0, 0); __builtin_amdgcn_s_setprio(0); } while (0)
; #define PG8_WAIT_V(n) asm volatile("s_waitcnt vmcnt(" #n ")" ::: "memory")
; #define PG8_WAIT_L(n) asm volatile("s_waitcnt lgkmcnt(" #n ")" ::: "memory")
; #define PG8_BAR __builtin_amdgcn_s_barrier()
; #define PG8_SCHED __builtin_amdgcn_sched_barrier(0)
; template <class Epi, class Sched, bool ALIGN_EPI = false, bool SP2 = false>
; __device__ __forceinline__ void gemm_phase(PG8_LAS unsigned char* lds, const Gemm g, const Sched& S, const Epi& E, const int tid) {
;     ...
;         for (int t = 0; t < nt; t += 2) {
;             const bool last = (t == nt - 2);
;             const char* a1 = cA + (size_t)(t + 1) * kstep;
;             const char* a2 = last ? nA : cA + (size_t)(t + 2) * kstep; const char* b2 = last ? nB : cB + (size_t)(t + 2) * kstep;
;     ...
;             PG8_LDA(At, 1, 1); PG8_STAGE(PG8_SB(1, 0), b3, voffB); PG8_STAGE(PG8_SB(1, 1), b3 + hstep, voffB); PG8_STAGE(PG8_SA(1, 0), a3, voffA);
;             PG8_WAIT_V(8); PG8_WAIT_L(0); PG8_BAR; PG8_MMA(1, 0, At, B0); PG8_MMA(1, 1, At, B1); PG8_BAR; PG8_SCHED;
	s_add_i32 s18, s56, s35
	v_lshl_add_u64 v[176:177], v[176:177], 0, s[12:13]
	s_mov_b32 m0, s18
	ds_read_b128 v[200:203], v182 offset:49152
	ds_read_b128 v[204:207], v182 offset:50176
	ds_read_b128 v[208:211], v182 offset:51200
	ds_read_b128 v[212:215], v182 offset:52224
	ds_read_b128 v[216:219], v182 offset:53248
	ds_read_b128 v[220:223], v182 offset:54272
	ds_read_b128 v[224:227], v182 offset:55296
	ds_read_b128 v[228:231], v182 offset:56320
	global_load_lds_dwordx4 v[176:177], off
	s_add_i32 m0, s18, 0x2000
	s_add_u32 s18, s22, 0xb0080
	v_lshl_add_u64 v[176:177], v[232:233], 0, s[12:13]
	s_addc_u32 s19, s23, 0
	s_add_i32 s22, s57, s35
	global_load_lds_dwordx4 v[176:177], off
	s_mov_b32 m0, s22
	s_nop 0
	global_load_lds_dwordx4 v146, s[18:19]
	s_add_i32 m0, s22, 0x2000
	s_nop 0
	global_load_lds_dwordx4 v150, s[18:19]
	v_lshl_add_u64 v[176:177], v[234:235], 0, s[12:13]
	s_mov_b32 m0, s45
	s_nop 0
	global_load_lds_dwordx4 v[176:177], off
	v_lshl_add_u64 v[176:177], v[236:237], 0, s[12:13]
	s_mov_b32 m0, s46
	s_nop 0
	global_load_lds_dwordx4 v[176:177], off
	s_waitcnt vmcnt(8)
	s_waitcnt lgkmcnt(0)
	s_barrier
	s_setprio 1
	s_waitcnt lgkmcnt(0)
	v_mfma_f32_16x16x32_bf16 v[60:63], v[120:123], v[200:203], v[60:63]
	v_mfma_f32_16x16x32_bf16 v[56:59], v[136:139], v[200:203], v[56:59]
	v_mfma_f32_16x16x32_bf16 v[52:55], v[120:123], v[208:211], v[52:55]
	v_mfma_f32_16x16x32_bf16 v[40:43], v[136:139], v[208:211], v[40:43]
	v_mfma_f32_16x16x32_bf16 v[36:39], v[120:123], v[216:219], v[36:39]
	v_mfma_f32_16x16x32_bf16 v[24:27], v[136:139], v[216:219], v[24:27]
	v_mfma_f32_16x16x32_bf16 v[20:23], v[120:123], v[224:227], v[20:23]
	v_mfma_f32_16x16x32_bf16 v[8:11], v[136:139], v[224:227], v[8:11]
	v_mfma_f32_16x16x32_bf16 v[60:63], v[124:127], v[204:207], v[60:63]
	v_mfma_f32_16x16x32_bf16 v[56:59], v[140:143], v[204:207], v[56:59]
	v_mfma_f32_16x16x32_bf16 v[52:55], v[124:127], v[212:215], v[52:55]
	v_mfma_f32_16x16x32_bf16 v[40:43], v[140:143], v[212:215], v[40:43]
	v_mfma_f32_16x16x32_bf16 v[36:39], v[124:127], v[220:223], v[36:39]
	v_mfma_f32_16x16x32_bf16 v[24:27], v[140:143], v[220:223], v[24:27]
	v_mfma_f32_16x16x32_bf16 v[20:23], v[124:127], v[228:231], v[20:23]
	v_mfma_f32_16x16x32_bf16 v[8:11], v[140:143], v[228:231], v[8:11]
	s_setprio 0
	s_setprio 1
	v_mfma_f32_16x16x32_bf16 v[48:51], v[184:187], v[200:203], v[48:51]
	v_mfma_f32_16x16x32_bf16 v[44:47], v[192:195], v[200:203], v[44:47]
	v_mfma_f32_16x16x32_bf16 v[32:35], v[184:187], v[208:211], v[32:35]
	v_mfma_f32_16x16x32_bf16 v[28:31], v[192:195], v[208:211], v[28:31]
	v_mfma_f32_16x16x32_bf16 v[16:19], v[184:187], v[216:219], v[16:19]
	v_mfma_f32_16x16x32_bf16 v[12:15], v[192:195], v[216:219], v[12:15]
	v_mfma_f32_16x16x32_bf16 v[4:7], v[184:187], v[224:227], v[4:7]
	v_mfma_f32_16x16x32_bf16 v[0:3], v[192:195], v[224:227], v[0:3]
	v_mfma_f32_16x16x32_bf16 v[48:51], v[188:191], v[204:207], v[48:51]
	v_mfma_f32_16x16x32_bf16 v[44:47], v[196:199], v[204:207], v[44:47]
	v_mfma_f32_16x16x32_bf16 v[32:35], v[188:191], v[212:215], v[32:35]
	v_mfma_f32_16x16x32_bf16 v[28:31], v[196:199], v[212:215], v[28:31]
	v_mfma_f32_16x16x32_bf16 v[16:19], v[188:191], v[220:223], v[16:19]
	v_mfma_f32_16x16x32_bf16 v[12:15], v[196:199], v[220:223], v[12:15]
	v_mfma_f32_16x16x32_bf16 v[4:7], v[188:191], v[228:231], v[4:7]
	v_mfma_f32_16x16x32_bf16 v[0:3], v[196:199], v[228:231], v[0:3]
	s_setprio 0
	s_barrier
	s_add_i32 s55, s55, 2
	s_add_u32 s33, s33, 0x100
	s_addc_u32 s54, s54, 0
	s_cmp_gt_u32 s55, 41
	s_mov_b64 s[18:19], s[20:21]
	s_cbranch_scc0 .LBB0_989
	s_and_b64 vcc, exec, s[14:15]
	s_cbranch_vccz .LBB0_992
	s_barrier

; #define PG8_STAGE(bufoff, gbase, voff) do { _Pragma("unroll") for (int _i = 0; _i < 2; ++_i) \
;         __builtin_amdgcn_global_load_lds((const unsigned*)((const char*)(gbase) + (voff)[_i]), (PG8_LAS unsigned*)(lds + (bufoff) + ldsw + _i * 8192), 16, 0, 0); } while (0)
; #define PG8_WAIT_V(n) asm volatile("s_waitcnt vmcnt(" #n ")" ::: "memory")
; #define PG8_BAR __builtin_amdgcn_s_barrier()
; template <class Epi, class Sched, bool ALIGN_EPI = false, bool SP2 = false>
; __device__ __forceinline__ void gemm_phase(PG8_LAS unsigned char* lds, const Gemm g, const Sched& S, const Epi& E, const int tid) {
;     const int wid = __builtin_amdgcn_readfirstlane(tid >> 6), lane = tid & 63, wr = wid >> 2, wc = wid & 3, fr = lane & 15, fq = lane >> 4;
;     const int K = g.K, nt = K / BK;
;     unsigned voffA[2], voffB[2];
; #pragma unroll
;     for (int i = 0; i < 2; ++i) { int R, C; stage_rc(tid * 16 + i * 8192, R, C); const int Rb = Epi::PERM ? ((R & ~31) + perm32(R & 31)) : R;
;         voffA[i] = (unsigned)(R * K + C) * 2u; voffB[i] = (unsigned)(Rb * K + C) * 2u; }
;     const size_t kstep = (size_t)(BK * 2);
;     const size_t hstep = (size_t)HALF * K * 2;
;     const size_t tstep = 2 * hstep;
;     const unsigned ldsw = (unsigned)wid * 1024u;
;     const int aoff = lds_byte(wr * 64 + fr, fq * 8), boff = lds_byte(wc * 32 + fr, fq * 8);
;     ...
;         PG8_STAGE(PG8_SB(1, 0), cB + kstep, voffB); PG8_STAGE(PG8_SA(1, 0), cA + kstep, voffA); PG8_STAGE(PG8_SB(1, 1), cB + hstep + kstep, voffB);
;         PG8_WAIT_V(6); PG8_BAR;
.LBB0_1118:
	s_add_u32 s8, s10, 0x10a00000
	s_addc_u32 s9, s3, 0
	s_add_u32 s10, s10, 0x3200000
	s_mov_b64 s[12:13], 0x80
	s_addc_u32 s11, s3, 0
	s_and_b32 s3, s1, 3
	s_add_i32 m0, s58, 0x18000
	v_lshl_add_u64 v[6:7], v[6:7], 0, s[12:13]
	s_lshl_b32 s15, s14, 13
	s_lshl_b32 s18, s3, 12
	s_waitcnt vmcnt(2)
	s_barrier
	global_load_lds_dwordx4 v[6:7], off
	v_lshl_add_u64 v[4:5], v[4:5], 0, s[12:13]
	s_add_i32 m0, s58, 0x1a000
	s_add_i32 s63, s58, 0x8000
	s_add_i32 s64, s58, 0xa000
	global_load_lds_dwordx4 v[4:5], off
	v_lshl_add_u64 v[0:1], v[0:1], 0, s[12:13]
	s_mov_b32 m0, s63
	s_add_u32 s16, s48, 0x40080
	global_load_lds_dwordx4 v[0:1], off
	v_lshl_add_u64 v[0:1], v[2:3], 0, s[12:13]
	s_mov_b32 m0, s64
	s_addc_u32 s17, s49, 0
	global_load_lds_dwordx4 v[0:1], off
	s_add_i32 m0, s58, 0x1c000
	global_load_lds_dwordx4 v130, s[16:17]
	s_add_i32 m0, s58, 0x1e000
	v_bfe_u32 v2, v8, 4, 2
	global_load_lds_dwordx4 v134, s[16:17]
	v_lshrrev_b32_e32 v0, 4, v8
	v_and_b32_e32 v1, 15, v8
	v_lshlrev_b32_e32 v3, 3, v2
	v_lshlrev_b32_e32 v2, 4, v2
	v_bitop3_b32 v0, s1, v0, 3 bitop3:0xa8
	s_sext_i32_i8 s76, s0
	v_lshl_or_b32 v148, s14, 6, v1
	v_lshl_or_b32 v1, v1, 6, v2
	v_lshlrev_b32_e32 v2, 2, v8
	v_cmp_eq_u32_e64 s[0:1], 0, v0
	v_lshlrev_b32_e32 v0, 14, v9
	v_and_b32_e32 v2, 32, v2
	v_and_b32_e32 v0, 0xffff8000, v0
	v_bitop3_b32 v4, v1, s15, v2 bitop3:0xde
	v_bitop3_b32 v149, s18, v1, v2 bitop3:0xf6
	v_lshl_add_u32 v0, v10, 11, v0
	v_and_b32_e32 v1, 1, v9
	v_lshl_or_b32 v0, v1, 6, v0
	v_lshl_add_u32 v136, v11, 1, v0
	v_lshlrev_b32_e32 v0, 14, v12
	v_and_b32_e32 v0, 0xffff8000, v0
	s_waitcnt vmcnt(6)
	s_cmpk_lt_u32 s2, 0x100
	v_lshl_add_u32 v0, v13, 11, v0
	v_and_b32_e32 v1, 1, v12
	s_cselect_b64 s[14:15], -1, 0
	v_lshl_or_b32 v0, v1, 6, v0
	s_add_i32 s66, 0, 0x10000
	s_add_i32 s67, 0, 0x14000
	v_lshl_or_b32 v150, s3, 5, v3
	s_ashr_i32 s65, s45, 31
	v_mov_b32_e32 v137, v131
	v_lshl_add_u32 v138, v14, 1, v0
	v_mov_b32_e32 v139, v131
	v_mov_b64_e32 v[140:141], 0x492
	v_mov_b64_e32 v[142:143], 0x491
	v_add_u32_e32 v151, s66, v149
	v_add_u32_e32 v152, s67, v149
	v_add_u32_e32 v153, 0, v4
	s_mov_b64 s[16:17], 0x1000
	s_mov_b64 s[18:19], 0x1200
	s_mov_b64 s[20:21], 0x1400
	s_mov_b64 s[22:23], 0x1600
	s_mov_b64 s[24:25], 0x80000
	s_mov_b32 s72, 0x80000
	s_mov_b64 s[26:27], 0x90000
	s_mov_b32 s73, 0x90000
	s_mov_b64 s[28:29], 0xa0000
	s_mov_b32 s74, 0xa0000
	s_mov_b64 s[30:31], 0xb0000
	s_mov_b32 s75, 0xb0000
	s_barrier
	s_branch .LBB0_1121

; __device__ __forceinline__ void finishSM(f32x16& p0, f32x16& p1, float alpha, float& l_reg, bf16x8& pa0, bf16x8& pa1, bf16x8& pa2, bf16x8& pa3) {
;   for (int r = 0; r < 16; ++r) p1[r] = __builtin_amdgcn_exp2f(p1[r]);
;   float ps = 0; for (int r = 0; r < 16; ++r) ps += p0[r]; for (int r = 0; r < 16; ++r) ps += p1[r];
;   asm volatile("" : "+v"(ps));
;   l_reg = l_reg * alpha + ps;
;     ...
;   PK4(p0, 0, pa0); PK4(p0, 8, pa1); PK4(p1, 0, pa2); PK4(p1, 8, pa3);
;     ...
; }
; __device__ __forceinline__ void qkt(f32x16& p0, f32x16& p1, const bf16* Ks, const bf16x8* qr, int r32, int hi) {
;   p0 = f32x16{}; p1 = f32x16{};
;   for (int d0 = 0; d0 < 8; ++d0) { int cb = (d0 * 16 + hi * 8) * 2;
;     bf16x8 b0 = *reinterpret_cast<const bf16x8*>((const char*)Ks + KSWZ(r32, cb));
;     bf16x8 b1 = *reinterpret_cast<const bf16x8*>((const char*)Ks + KSWZ(32 + r32, cb));
;     p0 = __builtin_amdgcn_mfma_f32_32x32x16_bf16(b0, qr[d0], p0, 0, 0, 0);
;     p1 = __builtin_amdgcn_mfma_f32_32x32x16_bf16(b1, qr[d0], p1, 0, 0, 0); }
; }
; __device__ __forceinline__ int v_st(int k, int c) { const int kk = k;
;   return ((kk >> 3) * 4 + (c >> 5)) * 512 + ((kk & 7) * 32 + (c & 31)) * 2; }
; __device__ __forceinline__ int v_rd_base(int lane) { return ((lane & 3) << 3) | (((lane >> 2) & 3) << 6) | (((lane >> 4) & 1) << 5) | (((lane >> 5) & 1) << 8); }
; template <int OFF> __device__ __forceinline__ s16x4 tr_read(int vb) {
;   s16x4 r; asm volatile("ds_read_b64_tr_b16 %0, %1 offset:%2" : "=&v"(r) : "v"(vb), "i"(OFF) : "memory"); return r;
; }
; template <int D0> __device__ __forceinline__ void pv_one(f32x16& od, int vb, bf16x8 pa0, bf16x8 pa1, bf16x8 pa2, bf16x8 pa3) {
;   const s16x4 l0 = tr_read<v_rd_off(D0, 0, 0)>(vb), h0 = tr_read<v_rd_off(D0, 0, 1)>(vb), l1 = tr_read<v_rd_off(D0, 1, 0)>(vb), h1 = tr_read<v_rd_off(D0, 1, 1)>(vb);
;   const s16x4 l2 = tr_read<v_rd_off(D0, 2, 0)>(vb), h2 = tr_read<v_rd_off(D0, 2, 1)>(vb), l3 = tr_read<v_rd_off(D0, 3, 0)>(vb), h3 = tr_read<v_rd_off(D0, 3, 1)>(vb);
;   asm volatile("s_waitcnt lgkmcnt(0)" ::: "memory"); SBAR();
; template <typename TQ> ...
;     ...
;   f32x16 pA0, pA1, pB0, pB1; float mnA, mnB, alA, alB; bf16x8 pa0, pa1, pa2, pa3; const int NT = seq / KVBLK;
;   DMA_TILE(0, 0); DMA_TILE(1, 1);
;   PUBLISH(4);
;   qkt(pA0, pA1, (const bf16*)K_lds, qr, r32, hi); partialSM<true>(pA0, pA1, m_reg, mnA, alA);
;   DMA_TILE(2, 2);
;   PUBLISH(4);
.LBB0_1365:
	s_mov_b32 s40, s33
	s_addk_i32 s33, 0xc000
	s_and_b32 s42, s33, 0xc000
	s_add_i32 s33, s56, s42
	v_add_u32_e32 v84, s33, v178
	ds_read_b128 v[80:83], v84
	ds_read_b128 v[84:87], v84 offset:8192
	v_add_u32_e32 v202, s33, v179
	ds_read_b128 v[198:201], v202
	ds_read_b128 v[202:205], v202 offset:8192
	v_add_u32_e32 v206, s33, v181
	s_waitcnt lgkmcnt(3)
	v_mfma_f32_32x32x16_bf16 v[96:111], v[80:83], v[136:139], 0
	v_add_u32_e32 v214, s33, v182
	v_exp_f32_e32 v238, v64
	v_add_f32_e32 v64, 0, v196
	v_add_f32_e32 v64, v197, v64
	v_add_u32_e32 v222, s33, v183
	v_add_f32_e32 v64, v193, v64
	v_add_f32_e32 v64, v195, v64
	s_waitcnt lgkmcnt(2)
	v_mfma_f32_32x32x16_bf16 v[80:95], v[84:87], v[136:139], 0
	v_add_f32_e32 v64, v191, v64
	v_add_f32_e32 v64, v194, v64
	v_add_f32_e32 v64, v190, v64
	v_add_f32_e32 v64, v192, v64
	v_add_f32_e32 v64, v169, v64
	v_add_f32_e32 v64, v171, v64
	v_add_u32_e32 v226, s33, v184
	s_waitcnt lgkmcnt(1)
	v_mfma_f32_32x32x16_bf16 v[96:111], v[198:201], v[140:143], v[96:111]
	v_add_f32_e32 v64, v167, v64
	v_add_f32_e32 v64, v170, v64
	v_add_f32_e32 v64, v165, v64
	v_add_f32_e32 v64, v168, v64
	v_add_f32_e32 v64, v164, v64
	v_add_f32_e32 v64, v166, v64
	v_exp_f32_e32 v239, v68
	s_waitcnt lgkmcnt(0)
	v_mfma_f32_32x32x16_bf16 v[80:95], v[202:205], v[140:143], v[80:95]
	v_add_u32_e32 v202, s33, v180
	ds_read_b128 v[198:201], v202
	ds_read_b128 v[202:205], v202 offset:8192
	v_add_f32_e32 v64, v238, v64
	v_exp_f32_e32 v240, v69
	v_add_u32_e32 v234, s33, v185
	v_exp_f32_e32 v241, v70
	v_exp_f32_e32 v242, v71
	s_waitcnt lgkmcnt(1)
	v_mfma_f32_32x32x16_bf16 v[96:111], v[198:201], v[132:135], v[96:111]
	ds_read_b128 v[198:201], v206
	ds_read_b128 v[206:209], v206 offset:8192
	ds_read_b128 v[210:213], v214
	ds_read_b128 v[214:217], v214 offset:8192
	ds_read_b128 v[218:221], v222
	ds_read_b128 v[222:225], v222 offset:8192
	v_exp_f32_e32 v243, v76
	v_exp_f32_e32 v244, v77
	v_exp_f32_e32 v245, v78
	v_exp_f32_e32 v79, v79
	s_waitcnt lgkmcnt(6)
	v_mfma_f32_32x32x16_bf16 v[80:95], v[202:205], v[132:135], v[80:95]
	ds_read_b128 v[202:205], v226
	ds_read_b128 v[226:229], v226 offset:8192
	ds_read_b128 v[230:233], v234
	ds_read_b128 v[234:237], v234 offset:8192
	s_waitcnt lgkmcnt(9)
	v_mfma_f32_32x32x16_bf16 v[96:111], v[198:201], v[128:131], v[96:111]
	v_exp_f32_e32 v199, v65
	v_exp_f32_e32 v200, v66
	v_exp_f32_e32 v201, v67
	v_add_f32_e32 v64, v199, v64
	v_add_f32_e32 v64, v200, v64
	v_add_f32_e32 v64, v201, v64
	s_waitcnt lgkmcnt(8)
	v_mfma_f32_32x32x16_bf16 v[80:95], v[206:209], v[128:131], v[80:95]
	v_exp_f32_e32 v206, v72
	v_add_f32_e32 v64, v239, v64
	v_exp_f32_e32 v207, v73
	v_add_f32_e32 v64, v240, v64
	v_exp_f32_e32 v208, v74
	v_add_f32_e32 v64, v241, v64
	v_exp_f32_e32 v209, v75
	s_waitcnt lgkmcnt(7)
	v_mfma_f32_32x32x16_bf16 v[96:111], v[210:213], v[124:127], v[96:111]
	v_add_f32_e32 v64, v242, v64
	v_add_f32_e32 v64, v206, v64
	v_add_f32_e32 v64, v207, v64
	v_add_f32_e32 v64, v208, v64
	v_add_f32_e32 v64, v209, v64
	v_add_f32_e32 v64, v243, v64
	v_add_f32_e32 v64, v244, v64
	s_waitcnt lgkmcnt(6)
	v_mfma_f32_32x32x16_bf16 v[80:95], v[214:217], v[124:127], v[80:95]
	v_add_f32_e32 v64, v245, v64
	v_add_f32_e32 v198, v79, v64
	v_cvt_pk_bf16_f32 v64, v196, v197
	v_cvt_pk_bf16_f32 v65, v193, v195
	v_cvt_pk_bf16_f32 v66, v191, v194
	v_cvt_pk_bf16_f32 v67, v190, v192
	s_waitcnt lgkmcnt(5)
	v_mfma_f32_32x32x16_bf16 v[96:111], v[218:221], v[120:123], v[96:111]
	v_cvt_pk_bf16_f32 v68, v169, v171
	v_cvt_pk_bf16_f32 v69, v167, v170
	v_cvt_pk_bf16_f32 v70, v165, v168
	v_cvt_pk_bf16_f32 v71, v164, v166
	v_cvt_pk_bf16_f32 v72, v238, v199
	v_cvt_pk_bf16_f32 v73, v200, v201
	v_cvt_pk_bf16_f32 v74, v239, v240
	s_waitcnt lgkmcnt(4)
	v_mfma_f32_32x32x16_bf16 v[80:95], v[222:225], v[120:123], v[80:95]
	v_cvt_pk_bf16_f32 v75, v241, v242
	v_cvt_pk_bf16_f32 v76, v206, v207
	v_cvt_pk_bf16_f32 v77, v208, v209
	v_cvt_pk_bf16_f32 v78, v243, v244
	v_cvt_pk_bf16_f32 v79, v245, v79
	s_waitcnt lgkmcnt(3)
	v_mfma_f32_32x32x16_bf16 v[96:111], v[202:205], v[116:119], v[96:111]
	s_add_i32 s33, s40, 0x8000
	s_and_b32 s43, s33, 0xc000
	v_add_u32_e32 v199, s43, v176
	ds_read_b64_tr_b16 v[190:191], v199 offset:0
	ds_read_b64_tr_b16 v[192:193], v199 offset:0x800
	ds_read_b64_tr_b16 v[194:195], v199 offset:0x1000
	ds_read_b64_tr_b16 v[196:197], v199 offset:0x1800
	s_waitcnt lgkmcnt(6)
	v_mfma_f32_32x32x16_bf16 v[80:95], v[226:229], v[116:119], v[80:95]
	ds_read_b64_tr_b16 v[200:201], v199 offset:0x2000
	ds_read_b64_tr_b16 v[202:203], v199 offset:0x2800
	ds_read_b64_tr_b16 v[204:205], v199 offset:0x3000
	ds_read_b64_tr_b16 v[206:207], v199 offset:0x3800
	s_add_i32 s73, s40, 0x4000
	s_and_b32 s73, s73, 0xc000
	s_add_u32 s98, s38, s22
	s_addc_u32 s99, s39, s23
	s_add_i32 s41, s66, s73
	s_add_u32 s100, s38, s24
	s_addc_u32 s101, s39, s25
	s_mov_b32 m0, s41
	s_add_i32 s73, s67, s73
	global_load_lds_dwordx4 v156, s[98:99]
	s_waitcnt lgkmcnt(9)
	v_mfma_f32_32x32x16_bf16 v[96:111], v[230:233], v[112:115], v[96:111]
	s_add_i32 m0, s41, 0x2000
	s_nop 0
	global_load_lds_dwordx4 v158, s[98:99]
	s_mov_b32 m0, s73
	s_nop 0
	global_load_lds_dwordx4 v162, s[100:101]
	s_waitcnt lgkmcnt(8)
	v_mfma_f32_32x32x16_bf16 v[80:95], v[234:237], v[112:115], v[80:95]
	s_add_i32 m0, s73, 0x2000
	s_nop 0
	global_load_lds_dwordx4 v160, s[100:101]
	s_nop 0
	s_waitcnt lgkmcnt(6)
; __device__ __forceinline__ void qkt(f32x16& p0, f32x16& p1, const bf16* Ks, const bf16x8* qr, int r32, int hi) {
;   p0 = f32x16{}; p1 = f32x16{};
;   for (int d0 = 0; d0 < 8; ++d0) { int cb = (d0 * 16 + hi * 8) * 2;
;     bf16x8 b0 = *reinterpret_cast<const bf16x8*>((const char*)Ks + KSWZ(r32, cb));
;     bf16x8 b1 = *reinterpret_cast<const bf16x8*>((const char*)Ks + KSWZ(32 + r32, cb));
;     p0 = __builtin_amdgcn_mfma_f32_32x32x16_bf16(b0, qr[d0], p0, 0, 0, 0);
;     p1 = __builtin_amdgcn_mfma_f32_32x32x16_bf16(b1, qr[d0], p1, 0, 0, 0); }
; }
; __device__ __forceinline__ int v_st(int k, int c) { const int kk = k;
;   return ((kk >> 3) * 4 + (c >> 5)) * 512 + ((kk & 7) * 32 + (c & 31)) * 2; }
; __device__ __forceinline__ int v_rd_base(int lane) { return ((lane & 3) << 3) | (((lane >> 2) & 3) << 6) | (((lane >> 4) & 1) << 5) | (((lane >> 5) & 1) << 8); }
; template <int OFF> __device__ __forceinline__ s16x4 tr_read(int vb) {
;   s16x4 r; asm volatile("ds_read_b64_tr_b16 %0, %1 offset:%2" : "=&v"(r) : "v"(vb), "i"(OFF) : "memory"); return r;
; }
; template <int D0> __device__ __forceinline__ void pv_one(f32x16& od, int vb, bf16x8 pa0, bf16x8 pa1, bf16x8 pa2, bf16x8 pa3) {
;   const s16x4 l0 = tr_read<v_rd_off(D0, 0, 0)>(vb), h0 = tr_read<v_rd_off(D0, 0, 1)>(vb), l1 = tr_read<v_rd_off(D0, 1, 0)>(vb), h1 = tr_read<v_rd_off(D0, 1, 1)>(vb);
;   const s16x4 l2 = tr_read<v_rd_off(D0, 2, 0)>(vb), h2 = tr_read<v_rd_off(D0, 2, 1)>(vb), l3 = tr_read<v_rd_off(D0, 3, 0)>(vb), h3 = tr_read<v_rd_off(D0, 3, 1)>(vb);
;   asm volatile("s_waitcnt lgkmcnt(0)" ::: "memory"); SBAR();
;     ...
;   od = __builtin_amdgcn_mfma_f32_32x32x16_bf16(pa0, PK(l0, h0), od, 0, 0, 0);
;   od = __builtin_amdgcn_mfma_f32_32x32x16_bf16(pa1, PK(l1, h1), od, 0, 0, 0);
;   od = __builtin_amdgcn_mfma_f32_32x32x16_bf16(pa2, PK(l2, h2), od, 0, 0, 0);
;   od = __builtin_amdgcn_mfma_f32_32x32x16_bf16(pa3, PK(l3, h3), od, 0, 0, 0);
;     ...
; }
; __device__ __forceinline__ void pv_d0(f32x16* o, int vb, bf16x8 pa0, bf16x8 pa1, bf16x8 pa2, bf16x8 pa3) {
;   pv_one<0>(o[0], vb, pa0, pa1, pa2, pa3); pv_one<1>(o[1], vb, pa0, pa1, pa2, pa3); pv_one<2>(o[2], vb, pa0, pa1, pa2, pa3); pv_one<3>(o[3], vb, pa0, pa1, pa2, pa3);
; template <typename TQ> ...
;     ...
;   f32x16 pA0, pA1, pB0, pB1; float mnA, mnB, alA, alB; bf16x8 pa0, pa1, pa2, pa3; const int NT = seq / KVBLK;
;   DMA_TILE(0, 0); DMA_TILE(1, 1);
;   PUBLISH(4);
	v_mfma_f32_32x32x16_bf16 v[48:63], v[64:67], v[190:193], v[48:63]
	v_exp_f32_e32 v232, v96
	ds_read_b64_tr_b16 v[190:191], v199 offset:0x200
	ds_read_b64_tr_b16 v[192:193], v199 offset:0xa00
	s_waitcnt lgkmcnt(6)
	v_mfma_f32_32x32x16_bf16 v[48:63], v[68:71], v[194:197], v[48:63]
	v_exp_f32_e32 v233, v97
	ds_read_b64_tr_b16 v[194:195], v199 offset:0x1200
	ds_read_b64_tr_b16 v[196:197], v199 offset:0x1a00
	s_waitcnt lgkmcnt(6)
	v_mfma_f32_32x32x16_bf16 v[48:63], v[72:75], v[200:203], v[48:63]
	v_exp_f32_e32 v234, v98
	ds_read_b64_tr_b16 v[200:201], v199 offset:0x2200
	ds_read_b64_tr_b16 v[202:203], v199 offset:0x2a00
	ds_read_b64_tr_b16 v[208:209], v199 offset:0x3200
	ds_read_b64_tr_b16 v[210:211], v199 offset:0x3a00
	s_waitcnt lgkmcnt(8)
	v_mfma_f32_32x32x16_bf16 v[48:63], v[76:79], v[204:207], v[48:63]
	v_exp_f32_e32 v235, v99
	s_waitcnt lgkmcnt(6)
	v_mfma_f32_32x32x16_bf16 v[32:47], v[64:67], v[190:193], v[32:47]
	v_exp_f32_e32 v236, v100
	ds_read_b64_tr_b16 v[190:191], v199 offset:0x400
	ds_read_b64_tr_b16 v[192:193], v199 offset:0xc00
	s_waitcnt lgkmcnt(6)
	v_mfma_f32_32x32x16_bf16 v[32:47], v[68:71], v[194:197], v[32:47]
	v_exp_f32_e32 v237, v101
	ds_read_b64_tr_b16 v[194:195], v199 offset:0x1400
	ds_read_b64_tr_b16 v[196:197], v199 offset:0x1c00
	s_waitcnt lgkmcnt(6)
	v_mfma_f32_32x32x16_bf16 v[32:47], v[72:75], v[200:203], v[32:47]
	v_exp_f32_e32 v238, v102
	ds_read_b64_tr_b16 v[200:201], v199 offset:0x2400
	ds_read_b64_tr_b16 v[202:203], v199 offset:0x2c00
	ds_read_b64_tr_b16 v[204:205], v199 offset:0x3400
	ds_read_b64_tr_b16 v[206:207], v199 offset:0x3c00
	s_waitcnt lgkmcnt(8)
	v_mfma_f32_32x32x16_bf16 v[32:47], v[76:79], v[208:211], v[32:47]
	v_exp_f32_e32 v239, v103
	v_exp_f32_e32 v240, v104
	s_waitcnt lgkmcnt(6)
	v_mfma_f32_32x32x16_bf16 v[16:31], v[64:67], v[190:193], v[16:31]
	v_exp_f32_e32 v241, v105
	ds_read_b64_tr_b16 v[190:191], v199 offset:0x600
	ds_read_b64_tr_b16 v[192:193], v199 offset:0xe00
	s_waitcnt lgkmcnt(6)
	v_mfma_f32_32x32x16_bf16 v[16:31], v[68:71], v[194:197], v[16:31]
	v_exp_f32_e32 v242, v106
	ds_read_b64_tr_b16 v[194:195], v199 offset:0x1600
	ds_read_b64_tr_b16 v[196:197], v199 offset:0x1e00
	s_waitcnt lgkmcnt(6)
	v_mfma_f32_32x32x16_bf16 v[16:31], v[72:75], v[200:203], v[16:31]
	v_exp_f32_e32 v243, v107
	ds_read_b64_tr_b16 v[200:201], v199 offset:0x2600
	ds_read_b64_tr_b16 v[202:203], v199 offset:0x2e00
	ds_read_b64_tr_b16 v[208:209], v199 offset:0x3600
	ds_read_b64_tr_b16 v[210:211], v199 offset:0x3e00
	s_waitcnt lgkmcnt(8)
	v_mfma_f32_32x32x16_bf16 v[16:31], v[76:79], v[204:207], v[16:31]
	v_exp_f32_e32 v244, v108
	s_waitcnt lgkmcnt(6)
	v_mfma_f32_32x32x16_bf16 v[0:15], v[64:67], v[190:193], v[0:15]
	v_exp_f32_e32 v245, v109
	s_waitcnt lgkmcnt(4)
	v_mfma_f32_32x32x16_bf16 v[0:15], v[68:71], v[194:197], v[0:15]
	v_exp_f32_e32 v246, v110
	s_waitcnt lgkmcnt(2)
	v_mfma_f32_32x32x16_bf16 v[0:15], v[72:75], v[200:203], v[0:15]
	v_exp_f32_e32 v247, v111
	s_waitcnt vmcnt(4)
	s_waitcnt lgkmcnt(0)
	s_barrier
	v_mfma_f32_32x32x16_bf16 v[0:15], v[76:79], v[208:211], v[0:15]
	s_and_b32 s40, s40, 0xc000
	s_add_i32 s40, s56, s40
	v_add_u32_e32 v68, s40, v178
	ds_read_b128 v[64:67], v68
	ds_read_b128 v[68:71], v68 offset:8192
	v_add_u32_e32 v194, s40, v179
	ds_read_b128 v[190:193], v194
	ds_read_b128 v[194:197], v194 offset:8192
	v_add_u32_e32 v199, s40, v181
	s_waitcnt lgkmcnt(3)
	v_mfma_f32_32x32x16_bf16 v[96:111], v[64:67], v[136:139], 0
	v_exp_f32_e32 v80, v80
	v_exp_f32_e32 v81, v81
	v_exp_f32_e32 v82, v82
	v_exp_f32_e32 v83, v83
	v_exp_f32_e32 v87, v87
	v_exp_f32_e32 v248, v93
	v_exp_f32_e32 v249, v94
	s_waitcnt lgkmcnt(2)
	v_mfma_f32_32x32x16_bf16 v[64:79], v[68:71], v[136:139], 0
	s_waitcnt lgkmcnt(1)
	v_mfma_f32_32x32x16_bf16 v[96:111], v[190:193], v[140:143], v[96:111]
	s_waitcnt lgkmcnt(0)
	v_mfma_f32_32x32x16_bf16 v[64:79], v[194:197], v[140:143], v[64:79]
	v_add_u32_e32 v194, s40, v180
	ds_read_b128 v[190:193], v194
	ds_read_b128 v[194:197], v194 offset:8192
	s_waitcnt lgkmcnt(1)
	v_mfma_f32_32x32x16_bf16 v[96:111], v[190:193], v[132:135], v[96:111]
	ds_read_b128 v[190:193], v199
	ds_read_b128 v[200:203], v199 offset:8192
	v_add_u32_e32 v199, s40, v182
	ds_read_b128 v[204:207], v199
	ds_read_b128 v[208:211], v199 offset:8192
	v_add_u32_e32 v199, s40, v183
	ds_read_b128 v[212:215], v199
	ds_read_b128 v[216:219], v199 offset:8192
	v_add_u32_e32 v199, s40, v184
	s_waitcnt lgkmcnt(6)
	v_mfma_f32_32x32x16_bf16 v[64:79], v[194:197], v[132:135], v[64:79]
	ds_read_b128 v[194:197], v199
	ds_read_b128 v[220:223], v199 offset:8192
	v_add_u32_e32 v199, s40, v185
	ds_read_b128 v[224:227], v199
	ds_read_b128 v[228:231], v199 offset:8192
	s_waitcnt lgkmcnt(9)
	v_mfma_f32_32x32x16_bf16 v[96:111], v[190:193], v[128:131], v[96:111]
	s_cmp_ge_u32 s72, s37
	s_cselect_b64 s[40:41], -1, 0
	s_and_b64 vcc, exec, s[40:41]
	s_cbranch_vccnz .LBB0_1367
	s_add_i32 s73, s66, s43
	s_add_u32 s98, s38, s26
	s_addc_u32 s99, s39, s27
	s_mov_b32 m0, s73
	s_add_i32 s43, s67, s43
	global_load_lds_dwordx4 v156, s[98:99]
	s_add_u32 s100, s38, s28
	s_addc_u32 s101, s39, s29
	s_add_i32 m0, s73, 0x2000
	s_nop 0
	global_load_lds_dwordx4 v158, s[98:99]
	s_mov_b32 m0, s43
	s_nop 0
	global_load_lds_dwordx4 v162, s[100:101]
	s_add_i32 m0, s43, 0x2000
	s_nop 0
	global_load_lds_dwordx4 v160, s[100:101]

; #define PG8_STAGE(bufoff, gbase, voff) do { _Pragma("unroll") for (int _i = 0; _i < 2; ++_i) \
;         __builtin_amdgcn_global_load_lds((const unsigned*)((const char*)(gbase) + (voff)[_i]), (PG8_LAS unsigned*)(lds + (bufoff) + ldsw + _i * 8192), 16, 0, 0); } while (0)
; #define PG8_WAIT_V(n) asm volatile("s_waitcnt vmcnt(" #n ")" ::: "memory")
; #define PG8_BAR __builtin_amdgcn_s_barrier()
; template <class Epi, class Sched, bool ALIGN_EPI = false, bool SP2 = false>
; __device__ __forceinline__ void gemm_phase(PG8_LAS unsigned char* lds, const Gemm g, const Sched& S, const Epi& E, const int tid) {
;     const int wid = __builtin_amdgcn_readfirstlane(tid >> 6), lane = tid & 63, wr = wid >> 2, wc = wid & 3, fr = lane & 15, fq = lane >> 4;
;     const int K = g.K, nt = K / BK;
;     unsigned voffA[2], voffB[2];
; #pragma unroll
;     for (int i = 0; i < 2; ++i) { int R, C; stage_rc(tid * 16 + i * 8192, R, C); const int Rb = Epi::PERM ? ((R & ~31) + perm32(R & 31)) : R;
;         voffA[i] = (unsigned)(R * K + C) * 2u; voffB[i] = (unsigned)(Rb * K + C) * 2u; }
;     const size_t kstep = (size_t)(BK * 2);
;     const size_t hstep = (size_t)HALF * K * 2;
;     const size_t tstep = 2 * hstep;
;     const unsigned ldsw = (unsigned)wid * 1024u;
;     const int aoff = lds_byte(wr * 64 + fr, fq * 8), boff = lds_byte(wc * 32 + fr, fq * 8);
;     ...
;         PG8_STAGE(PG8_SB(1, 0), cB + kstep, voffB); PG8_STAGE(PG8_SA(1, 0), cA + kstep, voffA); PG8_STAGE(PG8_SB(1, 1), cB + hstep + kstep, voffB);
;         PG8_WAIT_V(6); PG8_BAR;
.LBB0_1565:
	s_add_u32 s43, s13, 0x8800000
	s_addc_u32 s44, s12, 0
	s_add_u32 s45, s13, 0x10800000
	s_addc_u32 s46, s12, 0
	s_add_u32 s47, s13, 0x3014000
	s_addc_u32 s48, s12, 0
	s_lshl_b32 s1, s1, 5
	s_mov_b64 s[6:7], 0x80
	s_and_b32 s17, s1, 0x60
	s_add_i32 m0, s38, 0x18000
	v_lshl_add_u64 v[6:7], v[6:7], 0, s[6:7]
	s_lshl_b32 s16, s9, 13
	s_lshl_b32 s1, s17, 7
	s_waitcnt vmcnt(2)
	s_barrier
	global_load_lds_dwordx4 v[6:7], off
	v_lshl_add_u64 v[2:3], v[2:3], 0, s[6:7]
	s_add_i32 m0, s38, 0x1a000
	s_add_i32 s49, s38, 0x8000
	s_add_i32 s50, s38, 0xa000
	global_load_lds_dwordx4 v[2:3], off
	v_lshl_add_u64 v[0:1], v[0:1], 0, s[6:7]
	s_mov_b32 m0, s49
	s_add_u32 s14, s24, 0x40080
	global_load_lds_dwordx4 v[0:1], off
	v_lshl_add_u64 v[0:1], v[4:5], 0, s[6:7]
	s_mov_b32 m0, s50
	s_addc_u32 s15, s25, 0
	global_load_lds_dwordx4 v[0:1], off
	s_add_i32 m0, s38, 0x1c000
	global_load_lds_dwordx4 v146, s[14:15]
	s_add_i32 m0, s38, 0x1e000
	v_lshrrev_b32_e32 v2, 1, v8
	global_load_lds_dwordx4 v150, s[14:15]
	v_and_b32_e32 v15, 24, v2
	v_and_b32_e32 v1, 15, v8
	v_lshlrev_b32_e32 v2, 1, v15
	v_lshl_or_b32 v0, s9, 6, v1
	v_lshl_or_b32 v1, v1, 6, v2
	v_lshlrev_b32_e32 v2, 2, v8
	v_and_b32_e32 v2, 32, v2
	v_bitop3_b32 v8, v1, s16, v2 bitop3:0xde
	v_bitop3_b32 v178, s1, v1, v2 bitop3:0xf6
	v_ashrrev_i32_e32 v1, 31, v0
	v_or_b32_e32 v2, 16, v0
	v_or_b32_e32 v4, 32, v0
	v_or_b32_e32 v6, 48, v0
	v_lshlrev_b64 v[152:153], 11, v[0:1]
	v_lshlrev_b32_e32 v0, 14, v9
	v_and_b32_e32 v0, 0xffff8000, v0
	v_lshl_add_u32 v0, v10, 11, v0
	v_and_b32_e32 v1, 1, v9
	v_lshl_or_b32 v0, v1, 6, v0
	s_cmpk_lt_u32 s8, 0x100
	v_lshl_add_u32 v168, v11, 1, v0
	v_lshlrev_b32_e32 v0, 14, v12
	s_sext_i32_i8 s54, s0
	s_cselect_b64 s[8:9], -1, 0
	s_mov_b64 s[0:1], 0x48000
	s_ashr_i32 s51, s29, 31
	v_and_b32_e32 v0, 0xffff8000, v0
	s_waitcnt vmcnt(6)
	v_lshl_add_u64 v[154:155], v[152:153], 0, s[10:11]
	v_lshl_add_u64 v[156:157], v[152:153], 0, s[0:1]
	s_mov_b64 s[0:1], 0x50000
	s_add_u32 s10, s13, 0x3020000
	v_lshl_add_u32 v0, v13, 11, v0
	v_and_b32_e32 v1, 1, v12
	v_ashrrev_i32_e32 v3, 31, v2
	v_ashrrev_i32_e32 v5, 31, v4
	v_ashrrev_i32_e32 v7, 31, v6
	v_lshl_add_u64 v[158:159], v[152:153], 0, s[0:1]
	s_mov_b64 s[0:1], 0x58000
	s_addc_u32 s11, s12, 0
	v_lshl_or_b32 v0, v1, 6, v0
	s_add_i32 s52, 0, 0x10000
	s_add_i32 s53, 0, 0x14000
	v_lshl_add_u64 v[160:161], v[152:153], 0, s[0:1]
	v_lshlrev_b64 v[162:163], 11, v[2:3]
	v_lshlrev_b64 v[164:165], 11, v[4:5]
	v_lshlrev_b64 v[166:167], 11, v[6:7]
	v_or_b32_e32 v179, s17, v15
	v_mov_b32_e32 v169, v147
	v_lshl_add_u32 v170, v14, 1, v0
	v_mov_b32_e32 v171, v147
	v_mov_b64_e32 v[172:173], 0x200
	v_mov_b64_e32 v[174:175], 0x1ff
	v_add_u32_e32 v180, s52, v178
	v_add_u32_e32 v181, s53, v178
	v_add_u32_e32 v182, 0, v8
	s_barrier
	s_branch .LBB0_1568

; #define PG8_STAGE(bufoff, gbase, voff) do { _Pragma("unroll") for (int _i = 0; _i < 2; ++_i) \
;         __builtin_amdgcn_global_load_lds((const unsigned*)((const char*)(gbase) + (voff)[_i]), (PG8_LAS unsigned*)(lds + (bufoff) + ldsw + _i * 8192), 16, 0, 0); } while (0)
; #define PG8_LDA(dst, b, h) do { _Pragma("unroll") for (int m = 0; m < 4; ++m) _Pragma("unroll") for (int k = 0; k < 2; ++k) dst[m][k] = *(const PG8_LAS bf16x8*)(lds + PG8_SA(b, h) + aoff + m * 2048 + k * 1024); } while (0)
; #define PG8_LDB(dst, b, h) do { _Pragma("unroll") for (int n = 0; n < 2; ++n) _Pragma("unroll") for (int k = 0; k < 2; ++k) dst[n][k] = *(const PG8_LAS bf16x8*)(lds + PG8_SB(b, h) + boff + n * 2048 + k * 1024); } while (0)
; #define PG8_MMA(ai, bj, At, Bt) do { __builtin_amdgcn_s_setprio(1); _Pragma("unroll") for (int m = 0; m < 4; ++m) _Pragma("unroll") for (int n = 0; n < 2; ++n) _Pragma("unroll") for (int k = 0; k < 2; ++k) \
;         acc[ai][bj][m][n] = __builtin_amdgcn_mfma_f32_16x16x32_bf16(Bt[n][k], At[m][k], acc[ai][bj][m][n], 0, 0, 0); __builtin_amdgcn_s_setprio(0); } while (0)
; #define PG8_WAIT_V(n) asm volatile("s_waitcnt vmcnt(" #n ")" ::: "memory")
; #define PG8_WAIT_L(n) asm volatile("s_waitcnt lgkmcnt(" #n ")" ::: "memory")
; #define PG8_BAR __builtin_amdgcn_s_barrier()
; #define PG8_SCHED __builtin_amdgcn_sched_barrier(0)
; template <class Epi, class Sched, bool ALIGN_EPI = false, bool SP2 = false>
; __device__ __forceinline__ void gemm_phase(PG8_LAS unsigned char* lds, const Gemm g, const Sched& S, const Epi& E, const int tid) {
;     ...
;             const bool last = (t == nt - 2);
;             const char* a1 = cA + (size_t)(t + 1) * kstep;
;             const char* a2 = last ? nA : cA + (size_t)(t + 2) * kstep; const char* b2 = last ? nB : cB + (size_t)(t + 2) * kstep;
;             const char* a3 = a2 + kstep; const char* b3 = b2 + kstep;
;             if (last && has_next) S.a_ready(nxt);
;             if constexpr (SP2) {
;             PG8_LDB(B0, 0, 0); PG8_LDB(B1, 0, 1); PG8_SCHED; PG8_LDA(At, 0, 0); PG8_STAGE(PG8_SA(1, 1), a1 + hstep, voffA);
;             PG8_WAIT_V(8); PG8_WAIT_L(0); PG8_BAR; PG8_MMA(0, 0, At, B0); PG8_MMA(0, 1, At, B1); PG8_BAR; PG8_SCHED;
;             PG8_LDA(At, 0, 1); PG8_STAGE(PG8_SB(0, 0), b2, voffB); PG8_STAGE(PG8_SB(0, 1), b2 + hstep, voffB); PG8_STAGE(PG8_SA(0, 0), a2, voffA);
.LBB0_1575:
	ds_read_b128 v[120:123], v180
	ds_read_b128 v[124:127], v180 offset:1024
	ds_read_b128 v[136:139], v180 offset:2048
	ds_read_b128 v[140:143], v180 offset:3072
	ds_read_b128 v[184:187], v181
	ds_read_b128 v[188:191], v181 offset:1024
	ds_read_b128 v[192:195], v181 offset:2048
	ds_read_b128 v[196:199], v181 offset:3072
	s_add_u32 s24, s22, 0xfffc0080
	s_addc_u32 s25, s23, -1
	s_cmp_eq_u32 s57, 12
	s_cselect_b32 s27, s15, s25
	s_cselect_b32 s26, s21, s24
	s_cselect_b32 s25, s13, s56
	s_cselect_b32 s24, s33, s55
	s_add_i32 m0, s38, 0xc000
	ds_read_b128 v[200:203], v182
	ds_read_b128 v[204:207], v182 offset:1024
	ds_read_b128 v[208:211], v182 offset:2048
	ds_read_b128 v[212:215], v182 offset:3072
	ds_read_b128 v[216:219], v182 offset:4096
	ds_read_b128 v[220:223], v182 offset:5120
	ds_read_b128 v[224:227], v182 offset:6144
	ds_read_b128 v[228:231], v182 offset:7168
	global_load_lds_dwordx4 v168, s[22:23]
	s_add_i32 m0, s38, 0xe000
	s_nop 0
	global_load_lds_dwordx4 v170, s[22:23]
	s_waitcnt vmcnt(8)
	s_waitcnt lgkmcnt(0)
	s_barrier
	s_setprio 1
	s_waitcnt lgkmcnt(0)
	v_mfma_f32_16x16x32_bf16 v[132:135], v[120:123], v[200:203], v[132:135]
	v_mfma_f32_16x16x32_bf16 v[128:131], v[136:139], v[200:203], v[128:131]
	v_mfma_f32_16x16x32_bf16 v[116:119], v[120:123], v[208:211], v[116:119]
	v_mfma_f32_16x16x32_bf16 v[104:107], v[136:139], v[208:211], v[104:107]
	v_mfma_f32_16x16x32_bf16 v[100:103], v[120:123], v[216:219], v[100:103]
	v_mfma_f32_16x16x32_bf16 v[88:91], v[136:139], v[216:219], v[88:91]
	v_mfma_f32_16x16x32_bf16 v[84:87], v[120:123], v[224:227], v[84:87]
	v_mfma_f32_16x16x32_bf16 v[72:75], v[136:139], v[224:227], v[72:75]
	v_mfma_f32_16x16x32_bf16 v[132:135], v[124:127], v[204:207], v[132:135]
	v_mfma_f32_16x16x32_bf16 v[128:131], v[140:143], v[204:207], v[128:131]
	v_mfma_f32_16x16x32_bf16 v[116:119], v[124:127], v[212:215], v[116:119]
	v_mfma_f32_16x16x32_bf16 v[104:107], v[140:143], v[212:215], v[104:107]
	v_mfma_f32_16x16x32_bf16 v[100:103], v[124:127], v[220:223], v[100:103]
	v_mfma_f32_16x16x32_bf16 v[88:91], v[140:143], v[220:223], v[88:91]
	v_mfma_f32_16x16x32_bf16 v[84:87], v[124:127], v[228:231], v[84:87]
	v_mfma_f32_16x16x32_bf16 v[72:75], v[140:143], v[228:231], v[72:75]
	s_setprio 0
	s_setprio 1
	v_mfma_f32_16x16x32_bf16 v[112:115], v[184:187], v[200:203], v[112:115]
	v_mfma_f32_16x16x32_bf16 v[108:111], v[192:195], v[200:203], v[108:111]
	v_mfma_f32_16x16x32_bf16 v[96:99], v[184:187], v[208:211], v[96:99]
	v_mfma_f32_16x16x32_bf16 v[92:95], v[192:195], v[208:211], v[92:95]
	v_mfma_f32_16x16x32_bf16 v[80:83], v[184:187], v[216:219], v[80:83]
	v_mfma_f32_16x16x32_bf16 v[76:79], v[192:195], v[216:219], v[76:79]
	v_mfma_f32_16x16x32_bf16 v[68:71], v[184:187], v[224:227], v[68:71]
	v_mfma_f32_16x16x32_bf16 v[64:67], v[192:195], v[224:227], v[64:67]
	v_mfma_f32_16x16x32_bf16 v[112:115], v[188:191], v[204:207], v[112:115]
	v_mfma_f32_16x16x32_bf16 v[108:111], v[196:199], v[204:207], v[108:111]
	v_mfma_f32_16x16x32_bf16 v[96:99], v[188:191], v[212:215], v[96:99]
	v_mfma_f32_16x16x32_bf16 v[92:95], v[196:199], v[212:215], v[92:95]
	v_mfma_f32_16x16x32_bf16 v[80:83], v[188:191], v[220:223], v[80:83]
	v_mfma_f32_16x16x32_bf16 v[76:79], v[196:199], v[220:223], v[76:79]
	v_mfma_f32_16x16x32_bf16 v[68:71], v[188:191], v[228:231], v[68:71]
	v_mfma_f32_16x16x32_bf16 v[64:67], v[196:199], v[228:231], v[64:67]
	s_setprio 0
	s_barrier
	s_add_i32 s58, s52, s37
	v_lshl_add_u64 v[176:177], s[24:25], 0, v[146:147]
	s_mov_b32 m0, s58
	ds_read_b128 v[200:203], v182 offset:16384
	ds_read_b128 v[204:207], v182 offset:17408
	ds_read_b128 v[208:211], v182 offset:18432
	ds_read_b128 v[212:215], v182 offset:19456
	ds_read_b128 v[216:219], v182 offset:20480
	ds_read_b128 v[220:223], v182 offset:21504
	ds_read_b128 v[224:227], v182 offset:22528
	ds_read_b128 v[228:231], v182 offset:23552
	global_load_lds_dwordx4 v[176:177], off
	s_add_i32 m0, s58, 0x2000
	s_add_u32 s58, s24, 0x40000
	v_lshl_add_u64 v[232:233], s[24:25], 0, v[150:151]
	s_addc_u32 s59, s25, 0
	s_add_i32 s60, s53, s37
	global_load_lds_dwordx4 v[232:233], off
	s_mov_b32 m0, s60
	v_lshl_add_u64 v[236:237], s[26:27], 0, v[148:149]
	global_load_lds_dwordx4 v146, s[58:59]
	s_add_i32 m0, s60, 0x2000
	s_nop 0
	global_load_lds_dwordx4 v150, s[58:59]
	v_lshl_add_u64 v[234:235], s[26:27], 0, v[144:145]
	s_mov_b32 m0, s38
	s_nop 0
	global_load_lds_dwordx4 v[234:235], off
	s_mov_b32 m0, s39
	s_nop 0
	global_load_lds_dwordx4 v[236:237], off
	s_waitcnt vmcnt(8)
	s_waitcnt lgkmcnt(0)
	s_barrier
; #define PG8_STAGE(bufoff, gbase, voff) do { _Pragma("unroll") for (int _i = 0; _i < 2; ++_i) \
;         __builtin_amdgcn_global_load_lds((const unsigned*)((const char*)(gbase) + (voff)[_i]), (PG8_LAS unsigned*)(lds + (bufoff) + ldsw + _i * 8192), 16, 0, 0); } while (0)
; #define PG8_LDA(dst, b, h) do { _Pragma("unroll") for (int m = 0; m < 4; ++m) _Pragma("unroll") for (int k = 0; k < 2; ++k) dst[m][k] = *(const PG8_LAS bf16x8*)(lds + PG8_SA(b, h) + aoff + m * 2048 + k * 1024); } while (0)
; #define PG8_LDB(dst, b, h) do { _Pragma("unroll") for (int n = 0; n < 2; ++n) _Pragma("unroll") for (int k = 0; k < 2; ++k) dst[n][k] = *(const PG8_LAS bf16x8*)(lds + PG8_SB(b, h) + boff + n * 2048 + k * 1024); } while (0)
; #define PG8_MMA(ai, bj, At, Bt) do { __builtin_amdgcn_s_setprio(1); _Pragma("unroll") for (int m = 0; m < 4; ++m) _Pragma("unroll") for (int n = 0; n < 2; ++n) _Pragma("unroll") for (int k = 0; k < 2; ++k) \
;         acc[ai][bj][m][n] = __builtin_amdgcn_mfma_f32_16x16x32_bf16(Bt[n][k], At[m][k], acc[ai][bj][m][n], 0, 0, 0); __builtin_amdgcn_s_setprio(0); } while (0)
; #define PG8_WAIT_V(n) asm volatile("s_waitcnt vmcnt(" #n ")" ::: "memory")
; #define PG8_WAIT_L(n) asm volatile("s_waitcnt lgkmcnt(" #n ")" ::: "memory")
; #define PG8_BAR __builtin_amdgcn_s_barrier()
; #define PG8_SCHED __builtin_amdgcn_sched_barrier(0)
; template <class Epi, class Sched, bool ALIGN_EPI = false, bool SP2 = false>
; __device__ __forceinline__ void gemm_phase(PG8_LAS unsigned char* lds, const Gemm g, const Sched& S, const Epi& E, const int tid) {
;     ...
;             PG8_WAIT_V(8); PG8_WAIT_L(0); PG8_BAR; PG8_MMA(1, 0, At, B0); PG8_MMA(1, 1, At, B1); PG8_BAR; PG8_SCHED;
;             PG8_LDB(B0, 1, 0); PG8_LDB(B1, 1, 1); PG8_SCHED; PG8_LDA(At, 1, 0); PG8_STAGE(PG8_SA(0, 1), a2 + hstep, voffA);
;             PG8_WAIT_V(8); PG8_WAIT_L(0); PG8_BAR; PG8_MMA(0, 0, At, B0); PG8_MMA(0, 1, At, B1); PG8_BAR; PG8_SCHED;
	s_setprio 1
	s_waitcnt lgkmcnt(0)
	v_mfma_f32_16x16x32_bf16 v[60:63], v[120:123], v[200:203], v[60:63]
	v_mfma_f32_16x16x32_bf16 v[56:59], v[136:139], v[200:203], v[56:59]
	v_mfma_f32_16x16x32_bf16 v[52:55], v[120:123], v[208:211], v[52:55]
	v_mfma_f32_16x16x32_bf16 v[40:43], v[136:139], v[208:211], v[40:43]
	v_mfma_f32_16x16x32_bf16 v[36:39], v[120:123], v[216:219], v[36:39]
	v_mfma_f32_16x16x32_bf16 v[24:27], v[136:139], v[216:219], v[24:27]
	v_mfma_f32_16x16x32_bf16 v[20:23], v[120:123], v[224:227], v[20:23]
	v_mfma_f32_16x16x32_bf16 v[8:11], v[136:139], v[224:227], v[8:11]
	v_mfma_f32_16x16x32_bf16 v[60:63], v[124:127], v[204:207], v[60:63]
	v_mfma_f32_16x16x32_bf16 v[56:59], v[140:143], v[204:207], v[56:59]
	v_mfma_f32_16x16x32_bf16 v[52:55], v[124:127], v[212:215], v[52:55]
	v_mfma_f32_16x16x32_bf16 v[40:43], v[140:143], v[212:215], v[40:43]
	v_mfma_f32_16x16x32_bf16 v[36:39], v[124:127], v[220:223], v[36:39]
	v_mfma_f32_16x16x32_bf16 v[24:27], v[140:143], v[220:223], v[24:27]
	v_mfma_f32_16x16x32_bf16 v[20:23], v[124:127], v[228:231], v[20:23]
	v_mfma_f32_16x16x32_bf16 v[8:11], v[140:143], v[228:231], v[8:11]
	s_setprio 0
	s_setprio 1
	v_mfma_f32_16x16x32_bf16 v[48:51], v[184:187], v[200:203], v[48:51]
	v_mfma_f32_16x16x32_bf16 v[44:47], v[192:195], v[200:203], v[44:47]
	v_mfma_f32_16x16x32_bf16 v[32:35], v[184:187], v[208:211], v[32:35]
	v_mfma_f32_16x16x32_bf16 v[28:31], v[192:195], v[208:211], v[28:31]
	v_mfma_f32_16x16x32_bf16 v[16:19], v[184:187], v[216:219], v[16:19]
	v_mfma_f32_16x16x32_bf16 v[12:15], v[192:195], v[216:219], v[12:15]
	v_mfma_f32_16x16x32_bf16 v[4:7], v[184:187], v[224:227], v[4:7]
	v_mfma_f32_16x16x32_bf16 v[0:3], v[192:195], v[224:227], v[0:3]
	v_mfma_f32_16x16x32_bf16 v[48:51], v[188:191], v[204:207], v[48:51]
	v_mfma_f32_16x16x32_bf16 v[44:47], v[196:199], v[204:207], v[44:47]
	v_mfma_f32_16x16x32_bf16 v[32:35], v[188:191], v[212:215], v[32:35]
	v_mfma_f32_16x16x32_bf16 v[28:31], v[196:199], v[212:215], v[28:31]
	v_mfma_f32_16x16x32_bf16 v[16:19], v[188:191], v[220:223], v[16:19]
	v_mfma_f32_16x16x32_bf16 v[12:15], v[196:199], v[220:223], v[12:15]
	v_mfma_f32_16x16x32_bf16 v[4:7], v[188:191], v[228:231], v[4:7]
	v_mfma_f32_16x16x32_bf16 v[0:3], v[196:199], v[228:231], v[0:3]
	s_setprio 0
	s_barrier
	s_add_i32 s58, 0, 0x18000
	s_add_i32 s59, 0, 0x1c000
	v_add_u32_e32 v140, s58, v178
	v_add_u32_e32 v183, s59, v178
	ds_read_b128 v[120:123], v140
	ds_read_b128 v[124:127], v140 offset:1024
	ds_read_b128 v[136:139], v140 offset:2048
	ds_read_b128 v[140:143], v140 offset:3072
	ds_read_b128 v[184:187], v183
	ds_read_b128 v[188:191], v183 offset:1024
	ds_read_b128 v[192:195], v183 offset:2048
	ds_read_b128 v[196:199], v183 offset:3072
	s_add_u32 s26, s26, 0x40000
	s_addc_u32 s27, s27, 0
	s_mov_b32 m0, s40
	ds_read_b128 v[200:203], v182 offset:32768
	ds_read_b128 v[204:207], v182 offset:33792
	ds_read_b128 v[208:211], v182 offset:34816
	ds_read_b128 v[212:215], v182 offset:35840
	ds_read_b128 v[216:219], v182 offset:36864
	ds_read_b128 v[220:223], v182 offset:37888
	ds_read_b128 v[224:227], v182 offset:38912
	ds_read_b128 v[228:231], v182 offset:39936
	global_load_lds_dwordx4 v144, s[26:27]
	v_lshl_add_u64 v[238:239], s[26:27], 0, v[148:149]
	s_mov_b32 m0, s41
	s_nop 0
	global_load_lds_dwordx4 v[238:239], off
	s_waitcnt vmcnt(8)
	s_waitcnt lgkmcnt(0)
	s_barrier
	s_setprio 1
	s_waitcnt lgkmcnt(0)
	v_mfma_f32_16x16x32_bf16 v[132:135], v[120:123], v[200:203], v[132:135]
	v_mfma_f32_16x16x32_bf16 v[128:131], v[136:139], v[200:203], v[128:131]
	v_mfma_f32_16x16x32_bf16 v[116:119], v[120:123], v[208:211], v[116:119]
	v_mfma_f32_16x16x32_bf16 v[104:107], v[136:139], v[208:211], v[104:107]
	v_mfma_f32_16x16x32_bf16 v[100:103], v[120:123], v[216:219], v[100:103]
	v_mfma_f32_16x16x32_bf16 v[88:91], v[136:139], v[216:219], v[88:91]
	v_mfma_f32_16x16x32_bf16 v[84:87], v[120:123], v[224:227], v[84:87]
	v_mfma_f32_16x16x32_bf16 v[72:75], v[136:139], v[224:227], v[72:75]
	v_mfma_f32_16x16x32_bf16 v[132:135], v[124:127], v[204:207], v[132:135]
	v_mfma_f32_16x16x32_bf16 v[128:131], v[140:143], v[204:207], v[128:131]
	v_mfma_f32_16x16x32_bf16 v[116:119], v[124:127], v[212:215], v[116:119]
	v_mfma_f32_16x16x32_bf16 v[104:107], v[140:143], v[212:215], v[104:107]
	v_mfma_f32_16x16x32_bf16 v[100:103], v[124:127], v[220:223], v[100:103]
	v_mfma_f32_16x16x32_bf16 v[88:91], v[140:143], v[220:223], v[88:91]
	v_mfma_f32_16x16x32_bf16 v[84:87], v[124:127], v[228:231], v[84:87]
	v_mfma_f32_16x16x32_bf16 v[72:75], v[140:143], v[228:231], v[72:75]
	s_setprio 0
	s_setprio 1
	v_mfma_f32_16x16x32_bf16 v[112:115], v[184:187], v[200:203], v[112:115]
	v_mfma_f32_16x16x32_bf16 v[108:111], v[192:195], v[200:203], v[108:111]
	v_mfma_f32_16x16x32_bf16 v[96:99], v[184:187], v[208:211], v[96:99]
	v_mfma_f32_16x16x32_bf16 v[92:95], v[192:195], v[208:211], v[92:95]
	v_mfma_f32_16x16x32_bf16 v[80:83], v[184:187], v[216:219], v[80:83]
	v_mfma_f32_16x16x32_bf16 v[76:79], v[192:195], v[216:219], v[76:79]
	v_mfma_f32_16x16x32_bf16 v[68:71], v[184:187], v[224:227], v[68:71]
	v_mfma_f32_16x16x32_bf16 v[64:67], v[192:195], v[224:227], v[64:67]
	v_mfma_f32_16x16x32_bf16 v[112:115], v[188:191], v[204:207], v[112:115]
	v_mfma_f32_16x16x32_bf16 v[108:111], v[196:199], v[204:207], v[108:111]
	v_mfma_f32_16x16x32_bf16 v[96:99], v[188:191], v[212:215], v[96:99]
	v_mfma_f32_16x16x32_bf16 v[92:95], v[196:199], v[212:215], v[92:95]
	v_mfma_f32_16x16x32_bf16 v[80:83], v[188:191], v[220:223], v[80:83]
	v_mfma_f32_16x16x32_bf16 v[76:79], v[196:199], v[220:223], v[76:79]
	v_mfma_f32_16x16x32_bf16 v[68:71], v[188:191], v[228:231], v[68:71]
	v_mfma_f32_16x16x32_bf16 v[64:67], v[196:199], v[228:231], v[64:67]
	s_setprio 0
	s_barrier
; #define PG8_STAGE(bufoff, gbase, voff) do { _Pragma("unroll") for (int _i = 0; _i < 2; ++_i) \
;         __builtin_amdgcn_global_load_lds((const unsigned*)((const char*)(gbase) + (voff)[_i]), (PG8_LAS unsigned*)(lds + (bufoff) + ldsw + _i * 8192), 16, 0, 0); } while (0)
; #define PG8_LDA(dst, b, h) do { _Pragma("unroll") for (int m = 0; m < 4; ++m) _Pragma("unroll") for (int k = 0; k < 2; ++k) dst[m][k] = *(const PG8_LAS bf16x8*)(lds + PG8_SA(b, h) + aoff + m * 2048 + k * 1024); } while (0)
; #define PG8_MMA(ai, bj, At, Bt) do { __builtin_amdgcn_s_setprio(1); _Pragma("unroll") for (int m = 0; m < 4; ++m) _Pragma("unroll") for (int n = 0; n < 2; ++n) _Pragma("unroll") for (int k = 0; k < 2; ++k) \
;         acc[ai][bj][m][n] = __builtin_amdgcn_mfma_f32_16x16x32_bf16(Bt[n][k], At[m][k], acc[ai][bj][m][n], 0, 0, 0); __builtin_amdgcn_s_setprio(0); } while (0)
; #define PG8_WAIT_V(n) asm volatile("s_waitcnt vmcnt(" #n ")" ::: "memory")
; #define PG8_WAIT_L(n) asm volatile("s_waitcnt lgkmcnt(" #n ")" ::: "memory")
; #define PG8_BAR __builtin_amdgcn_s_barrier()
; #define PG8_SCHED __builtin_amdgcn_sched_barrier(0)
; template <class Epi, class Sched, bool ALIGN_EPI = false, bool SP2 = false>
; __device__ __forceinline__ void gemm_phase(PG8_LAS unsigned char* lds, const Gemm g, const Sched& S, const Epi& E, const int tid) {
;     ...
;         for (int t = 0; t < nt; t += 2) {
;             const bool last = (t == nt - 2);
;             const char* a1 = cA + (size_t)(t + 1) * kstep;
;             const char* a2 = last ? nA : cA + (size_t)(t + 2) * kstep; const char* b2 = last ? nB : cB + (size_t)(t + 2) * kstep;
;     ...
;             PG8_LDA(At, 1, 1); PG8_STAGE(PG8_SB(1, 0), b3, voffB); PG8_STAGE(PG8_SB(1, 1), b3 + hstep, voffB); PG8_STAGE(PG8_SA(1, 0), a3, voffA);
;             PG8_WAIT_V(8); PG8_WAIT_L(0); PG8_BAR; PG8_MMA(1, 0, At, B0); PG8_MMA(1, 1, At, B1); PG8_BAR; PG8_SCHED;
	s_add_i32 s26, s58, s37
	v_lshl_add_u64 v[176:177], v[176:177], 0, s[6:7]
	s_mov_b32 m0, s26
	ds_read_b128 v[200:203], v182 offset:49152
	ds_read_b128 v[204:207], v182 offset:50176
	ds_read_b128 v[208:211], v182 offset:51200
	ds_read_b128 v[212:215], v182 offset:52224
	ds_read_b128 v[216:219], v182 offset:53248
	ds_read_b128 v[220:223], v182 offset:54272
	ds_read_b128 v[224:227], v182 offset:55296
	ds_read_b128 v[228:231], v182 offset:56320
	global_load_lds_dwordx4 v[176:177], off
	s_add_i32 m0, s26, 0x2000
	s_add_u32 s24, s24, 0x40080
	v_lshl_add_u64 v[176:177], v[232:233], 0, s[6:7]
	s_addc_u32 s25, s25, 0
	s_add_i32 s26, s59, s37
	global_load_lds_dwordx4 v[176:177], off
	s_mov_b32 m0, s26
	s_nop 0
	global_load_lds_dwordx4 v146, s[24:25]
	s_add_i32 m0, s26, 0x2000
	s_nop 0
	global_load_lds_dwordx4 v150, s[24:25]
	v_lshl_add_u64 v[176:177], v[234:235], 0, s[6:7]
	s_mov_b32 m0, s49
	s_nop 0
	global_load_lds_dwordx4 v[176:177], off
	v_lshl_add_u64 v[176:177], v[236:237], 0, s[6:7]
	s_mov_b32 m0, s50
	s_nop 0
	global_load_lds_dwordx4 v[176:177], off
	s_waitcnt vmcnt(8)
	s_waitcnt lgkmcnt(0)
	s_barrier
	s_setprio 1
	s_waitcnt lgkmcnt(0)
	v_mfma_f32_16x16x32_bf16 v[60:63], v[120:123], v[200:203], v[60:63]
	v_mfma_f32_16x16x32_bf16 v[56:59], v[136:139], v[200:203], v[56:59]
	v_mfma_f32_16x16x32_bf16 v[52:55], v[120:123], v[208:211], v[52:55]
	v_mfma_f32_16x16x32_bf16 v[40:43], v[136:139], v[208:211], v[40:43]
	v_mfma_f32_16x16x32_bf16 v[36:39], v[120:123], v[216:219], v[36:39]
	v_mfma_f32_16x16x32_bf16 v[24:27], v[136:139], v[216:219], v[24:27]
	v_mfma_f32_16x16x32_bf16 v[20:23], v[120:123], v[224:227], v[20:23]
	v_mfma_f32_16x16x32_bf16 v[8:11], v[136:139], v[224:227], v[8:11]
	v_mfma_f32_16x16x32_bf16 v[60:63], v[124:127], v[204:207], v[60:63]
	v_mfma_f32_16x16x32_bf16 v[56:59], v[140:143], v[204:207], v[56:59]
	v_mfma_f32_16x16x32_bf16 v[52:55], v[124:127], v[212:215], v[52:55]
	v_mfma_f32_16x16x32_bf16 v[40:43], v[140:143], v[212:215], v[40:43]
	v_mfma_f32_16x16x32_bf16 v[36:39], v[124:127], v[220:223], v[36:39]
	v_mfma_f32_16x16x32_bf16 v[24:27], v[140:143], v[220:223], v[24:27]
	v_mfma_f32_16x16x32_bf16 v[20:23], v[124:127], v[228:231], v[20:23]
	v_mfma_f32_16x16x32_bf16 v[8:11], v[140:143], v[228:231], v[8:11]
	s_setprio 0
	s_setprio 1
	v_mfma_f32_16x16x32_bf16 v[48:51], v[184:187], v[200:203], v[48:51]
	v_mfma_f32_16x16x32_bf16 v[44:47], v[192:195], v[200:203], v[44:47]
	v_mfma_f32_16x16x32_bf16 v[32:35], v[184:187], v[208:211], v[32:35]
	v_mfma_f32_16x16x32_bf16 v[28:31], v[192:195], v[208:211], v[28:31]
	v_mfma_f32_16x16x32_bf16 v[16:19], v[184:187], v[216:219], v[16:19]
	v_mfma_f32_16x16x32_bf16 v[12:15], v[192:195], v[216:219], v[12:15]
	v_mfma_f32_16x16x32_bf16 v[4:7], v[184:187], v[224:227], v[4:7]
	v_mfma_f32_16x16x32_bf16 v[0:3], v[192:195], v[224:227], v[0:3]
	v_mfma_f32_16x16x32_bf16 v[48:51], v[188:191], v[204:207], v[48:51]
	v_mfma_f32_16x16x32_bf16 v[44:47], v[196:199], v[204:207], v[44:47]
	v_mfma_f32_16x16x32_bf16 v[32:35], v[188:191], v[212:215], v[32:35]
	v_mfma_f32_16x16x32_bf16 v[28:31], v[196:199], v[212:215], v[28:31]
	v_mfma_f32_16x16x32_bf16 v[16:19], v[188:191], v[220:223], v[16:19]
	v_mfma_f32_16x16x32_bf16 v[12:15], v[196:199], v[220:223], v[12:15]
	v_mfma_f32_16x16x32_bf16 v[4:7], v[188:191], v[228:231], v[4:7]
	v_mfma_f32_16x16x32_bf16 v[0:3], v[196:199], v[228:231], v[0:3]
	s_setprio 0
	s_barrier
	s_add_i32 s57, s57, 2
	s_add_u32 s22, s22, 0x100
	s_addc_u32 s23, s23, 0
	s_add_u32 s55, s55, 0x100
	s_addc_u32 s56, s56, 0
	s_cmp_gt_u32 s57, 13
	s_cbranch_scc0 .LBB0_1575
	s_and_b64 vcc, exec, s[8:9]
	s_cbranch_vccz .LBB0_1578
	s_barrier

; #define PG8_STAGE(bufoff, gbase, voff) do { _Pragma("unroll") for (int _i = 0; _i < 2; ++_i) \
;         __builtin_amdgcn_global_load_lds((const unsigned*)((const char*)(gbase) + (voff)[_i]), (PG8_LAS unsigned*)(lds + (bufoff) + ldsw + _i * 8192), 16, 0, 0); } while (0)
; #define PG8_WAIT_V(n) asm volatile("s_waitcnt vmcnt(" #n ")" ::: "memory")
; #define PG8_BAR __builtin_amdgcn_s_barrier()
; template <class Epi, class Sched, bool ALIGN_EPI = false, bool SP2 = false>
; __device__ __forceinline__ void gemm_phase(PG8_LAS unsigned char* lds, const Gemm g, const Sched& S, const Epi& E, const int tid) {
;     const int wid = __builtin_amdgcn_readfirstlane(tid >> 6), lane = tid & 63, wr = wid >> 2, wc = wid & 3, fr = lane & 15, fq = lane >> 4;
;     const int K = g.K, nt = K / BK;
;     unsigned voffA[2], voffB[2];
; #pragma unroll
;     for (int i = 0; i < 2; ++i) { int R, C; stage_rc(tid * 16 + i * 8192, R, C); const int Rb = Epi::PERM ? ((R & ~31) + perm32(R & 31)) : R;
;         voffA[i] = (unsigned)(R * K + C) * 2u; voffB[i] = (unsigned)(Rb * K + C) * 2u; }
;     const size_t kstep = (size_t)(BK * 2);
;     const size_t hstep = (size_t)HALF * K * 2;
;     const size_t tstep = 2 * hstep;
;     const unsigned ldsw = (unsigned)wid * 1024u;
;     const int aoff = lds_byte(wr * 64 + fr, fq * 8), boff = lds_byte(wc * 32 + fr, fq * 8);
;     ...
;         PG8_STAGE(PG8_SB(1, 0), cB + kstep, voffB); PG8_STAGE(PG8_SA(1, 0), cA + kstep, voffA); PG8_STAGE(PG8_SB(1, 1), cB + hstep + kstep, voffB);
;         PG8_WAIT_V(6); PG8_BAR;
.LBB0_1698:
	s_add_u32 s6, s6, 0x10a00000
	s_addc_u32 s7, s7, 0
	s_lshl_b32 s8, s8, 5
	s_and_b32 s14, s8, 0x60
	s_mov_b64 s[8:9], 0x80
	s_add_i32 m0, s19, 0x18000
	v_lshl_add_u64 v[6:7], v[6:7], 0, s[8:9]
	s_lshl_b32 s11, s10, 13
	s_lshl_b32 s15, s14, 7
	s_waitcnt vmcnt(2)
	s_barrier
	global_load_lds_dwordx4 v[6:7], off
	v_lshl_add_u64 v[4:5], v[4:5], 0, s[8:9]
	s_add_i32 m0, s19, 0x1a000
	s_add_i32 s40, s19, 0x8000
	s_add_i32 s41, s19, 0xa000
	global_load_lds_dwordx4 v[4:5], off
	v_lshl_add_u64 v[0:1], v[0:1], 0, s[8:9]
	s_mov_b32 m0, s40
	s_add_u32 s12, s22, 0x40080
	global_load_lds_dwordx4 v[0:1], off
	v_lshl_add_u64 v[0:1], v[2:3], 0, s[8:9]
	s_mov_b32 m0, s41
	s_addc_u32 s13, s23, 0
	global_load_lds_dwordx4 v[0:1], off
	s_add_i32 m0, s19, 0x1c000
	global_load_lds_dwordx4 v132, s[12:13]
	s_add_i32 m0, s19, 0x1e000
	s_cmpk_lt_u32 s1, 0x100
	global_load_lds_dwordx4 v128, s[12:13]
	v_lshrrev_b32_e32 v1, 1, v8
	v_and_b32_e32 v1, 24, v1
	v_and_b32_e32 v0, 15, v8
	v_lshlrev_b32_e32 v2, 1, v1
	v_lshl_or_b32 v144, s10, 6, v0
	v_lshl_or_b32 v0, v0, 6, v2
	v_lshlrev_b32_e32 v2, 2, v8
	v_and_b32_e32 v2, 32, v2
	v_bitop3_b32 v3, v0, s11, v2 bitop3:0xde
	v_bitop3_b32 v145, s15, v0, v2 bitop3:0xf6
	v_lshlrev_b32_e32 v0, 14, v13
	v_and_b32_e32 v0, 0xffff8000, v0
	v_or_b32_e32 v146, s14, v1
	v_lshl_add_u32 v0, v12, 11, v0
	v_and_b32_e32 v1, 1, v13
	v_lshl_or_b32 v0, v1, 6, v0
	v_lshl_add_u32 v136, v14, 1, v0
	v_lshlrev_b32_e32 v0, 14, v9
	v_and_b32_e32 v0, 0xffff8000, v0
	s_waitcnt vmcnt(6)
	v_lshl_add_u32 v0, v10, 11, v0
	v_and_b32_e32 v1, 1, v9
	s_cselect_b64 s[10:11], -1, 0
	v_lshl_or_b32 v0, v1, 6, v0
	s_add_i32 s44, 0, 0x10000
	s_add_i32 s45, 0, 0x14000
	s_sext_i32_i16 s48, s0
	s_mov_b32 s42, 0
	s_ashr_i32 s43, s27, 31
	v_mov_b32_e32 v137, v133
	v_lshl_add_u32 v138, v11, 1, v0
	v_mov_b32_e32 v139, v133
	v_mov_b64_e32 v[140:141], 0xb00
	v_mov_b64_e32 v[142:143], 0xaff
	v_add_u32_e32 v147, s44, v145
	v_add_u32_e32 v148, s45, v145
	v_add_u32_e32 v149, 0, v3
	s_movk_i32 s46, 0x1600
	s_barrier
	s_branch .LBB0_1701

; #define PG8_STAGE(bufoff, gbase, voff) do { _Pragma("unroll") for (int _i = 0; _i < 2; ++_i) \
;         __builtin_amdgcn_global_load_lds((const unsigned*)((const char*)(gbase) + (voff)[_i]), (PG8_LAS unsigned*)(lds + (bufoff) + ldsw + _i * 8192), 16, 0, 0); } while (0)
; #define PG8_LDA(dst, b, h) do { _Pragma("unroll") for (int m = 0; m < 4; ++m) _Pragma("unroll") for (int k = 0; k < 2; ++k) dst[m][k] = *(const PG8_LAS bf16x8*)(lds + PG8_SA(b, h) + aoff + m * 2048 + k * 1024); } while (0)
; #define PG8_LDB(dst, b, h) do { _Pragma("unroll") for (int n = 0; n < 2; ++n) _Pragma("unroll") for (int k = 0; k < 2; ++k) dst[n][k] = *(const PG8_LAS bf16x8*)(lds + PG8_SB(b, h) + boff + n * 2048 + k * 1024); } while (0)
; #define PG8_MMA(ai, bj, At, Bt) do { __builtin_amdgcn_s_setprio(1); _Pragma("unroll") for (int m = 0; m < 4; ++m) _Pragma("unroll") for (int n = 0; n < 2; ++n) _Pragma("unroll") for (int k = 0; k < 2; ++k) \
;         acc[ai][bj][m][n] = __builtin_amdgcn_mfma_f32_16x16x32_bf16(Bt[n][k], At[m][k], acc[ai][bj][m][n], 0, 0, 0); __builtin_amdgcn_s_setprio(0); } while (0)
; #define PG8_WAIT_V(n) asm volatile("s_waitcnt vmcnt(" #n ")" ::: "memory")
; #define PG8_WAIT_L(n) asm volatile("s_waitcnt lgkmcnt(" #n ")" ::: "memory")
; #define PG8_BAR __builtin_amdgcn_s_barrier()
; #define PG8_SCHED __builtin_amdgcn_sched_barrier(0)
; template <class Epi, class Sched, bool ALIGN_EPI = false, bool SP2 = false>
; __device__ __forceinline__ void gemm_phase(PG8_LAS unsigned char* lds, const Gemm g, const Sched& S, const Epi& E, const int tid) {
;     ...
;             const bool last = (t == nt - 2);
;             const char* a1 = cA + (size_t)(t + 1) * kstep;
;             const char* a2 = last ? nA : cA + (size_t)(t + 2) * kstep; const char* b2 = last ? nB : cB + (size_t)(t + 2) * kstep;
;             const char* a3 = a2 + kstep; const char* b3 = b2 + kstep;
;             if (last && has_next) S.a_ready(nxt);
;             if constexpr (SP2) {
;             PG8_LDB(B0, 0, 0); PG8_LDB(B1, 0, 1); PG8_SCHED; PG8_LDA(At, 0, 0); PG8_STAGE(PG8_SA(1, 1), a1 + hstep, voffA);
;             PG8_WAIT_V(8); PG8_WAIT_L(0); PG8_BAR; PG8_MMA(0, 0, At, B0); PG8_MMA(0, 1, At, B1); PG8_BAR; PG8_SCHED;
;             PG8_LDA(At, 0, 1); PG8_STAGE(PG8_SB(0, 0), b2, voffB); PG8_STAGE(PG8_SB(0, 1), b2 + hstep, voffB); PG8_STAGE(PG8_SA(0, 0), a2, voffA);
.LBB0_1704:
	ds_read_b128 v[150:153], v147
	ds_read_b128 v[154:157], v147 offset:1024
	ds_read_b128 v[158:161], v147 offset:2048
	ds_read_b128 v[162:165], v147 offset:3072
	ds_read_b128 v[166:169], v148
	ds_read_b128 v[170:173], v148 offset:1024
	ds_read_b128 v[174:177], v148 offset:2048
	ds_read_b128 v[178:181], v148 offset:3072
	s_add_u32 s22, s20, 0xfffc0080
	s_addc_u32 s23, s21, -1
	s_cmp_eq_u32 s53, 12
	s_cselect_b32 s25, s33, s23
	s_cselect_b32 s24, s49, s22
	s_cselect_b32 s23, s13, s52
	s_cselect_b32 s22, s50, s51
	s_add_i32 m0, s19, 0xc000
	ds_read_b128 v[182:185], v149
	ds_read_b128 v[186:189], v149 offset:1024
	ds_read_b128 v[190:193], v149 offset:2048
	ds_read_b128 v[194:197], v149 offset:3072
	ds_read_b128 v[198:201], v149 offset:4096
	ds_read_b128 v[202:205], v149 offset:5120
	ds_read_b128 v[206:209], v149 offset:6144
	ds_read_b128 v[210:213], v149 offset:7168
	global_load_lds_dwordx4 v136, s[20:21]
	s_add_i32 m0, s19, 0xe000
	s_nop 0
	global_load_lds_dwordx4 v138, s[20:21]
	s_waitcnt vmcnt(8)
	s_waitcnt lgkmcnt(0)
	s_barrier
	s_setprio 1
	s_waitcnt lgkmcnt(0)
	v_mfma_f32_16x16x32_bf16 v[124:127], v[150:153], v[182:185], v[124:127]
	v_mfma_f32_16x16x32_bf16 v[116:119], v[158:161], v[182:185], v[116:119]
	v_mfma_f32_16x16x32_bf16 v[108:111], v[150:153], v[190:193], v[108:111]
	v_mfma_f32_16x16x32_bf16 v[100:103], v[158:161], v[190:193], v[100:103]
	v_mfma_f32_16x16x32_bf16 v[92:95], v[150:153], v[198:201], v[92:95]
	v_mfma_f32_16x16x32_bf16 v[84:87], v[158:161], v[198:201], v[84:87]
	v_mfma_f32_16x16x32_bf16 v[76:79], v[150:153], v[206:209], v[76:79]
	v_mfma_f32_16x16x32_bf16 v[68:71], v[158:161], v[206:209], v[68:71]
	v_mfma_f32_16x16x32_bf16 v[124:127], v[154:157], v[186:189], v[124:127]
	v_mfma_f32_16x16x32_bf16 v[116:119], v[162:165], v[186:189], v[116:119]
	v_mfma_f32_16x16x32_bf16 v[108:111], v[154:157], v[194:197], v[108:111]
	v_mfma_f32_16x16x32_bf16 v[100:103], v[162:165], v[194:197], v[100:103]
	v_mfma_f32_16x16x32_bf16 v[92:95], v[154:157], v[202:205], v[92:95]
	v_mfma_f32_16x16x32_bf16 v[84:87], v[162:165], v[202:205], v[84:87]
	v_mfma_f32_16x16x32_bf16 v[76:79], v[154:157], v[210:213], v[76:79]
	v_mfma_f32_16x16x32_bf16 v[68:71], v[162:165], v[210:213], v[68:71]
	s_setprio 0
	s_setprio 1
	v_mfma_f32_16x16x32_bf16 v[120:123], v[166:169], v[182:185], v[120:123]
	v_mfma_f32_16x16x32_bf16 v[112:115], v[174:177], v[182:185], v[112:115]
	v_mfma_f32_16x16x32_bf16 v[104:107], v[166:169], v[190:193], v[104:107]
	v_mfma_f32_16x16x32_bf16 v[96:99], v[174:177], v[190:193], v[96:99]
	v_mfma_f32_16x16x32_bf16 v[88:91], v[166:169], v[198:201], v[88:91]
	v_mfma_f32_16x16x32_bf16 v[80:83], v[174:177], v[198:201], v[80:83]
	v_mfma_f32_16x16x32_bf16 v[72:75], v[166:169], v[206:209], v[72:75]
	v_mfma_f32_16x16x32_bf16 v[64:67], v[174:177], v[206:209], v[64:67]
	v_mfma_f32_16x16x32_bf16 v[120:123], v[170:173], v[186:189], v[120:123]
	v_mfma_f32_16x16x32_bf16 v[112:115], v[178:181], v[186:189], v[112:115]
	v_mfma_f32_16x16x32_bf16 v[104:107], v[170:173], v[194:197], v[104:107]
	v_mfma_f32_16x16x32_bf16 v[96:99], v[178:181], v[194:197], v[96:99]
	v_mfma_f32_16x16x32_bf16 v[88:91], v[170:173], v[202:205], v[88:91]
	v_mfma_f32_16x16x32_bf16 v[80:83], v[178:181], v[202:205], v[80:83]
	v_mfma_f32_16x16x32_bf16 v[72:75], v[170:173], v[210:213], v[72:75]
	v_mfma_f32_16x16x32_bf16 v[64:67], v[178:181], v[210:213], v[64:67]
	s_setprio 0
	s_barrier
	s_add_i32 s54, s44, s34
	v_lshl_add_u64 v[214:215], s[22:23], 0, v[132:133]
	s_mov_b32 m0, s54
	ds_read_b128 v[182:185], v149 offset:16384
	ds_read_b128 v[186:189], v149 offset:17408
	ds_read_b128 v[190:193], v149 offset:18432
	ds_read_b128 v[194:197], v149 offset:19456
	ds_read_b128 v[198:201], v149 offset:20480
	ds_read_b128 v[202:205], v149 offset:21504
	ds_read_b128 v[206:209], v149 offset:22528
	ds_read_b128 v[210:213], v149 offset:23552
	global_load_lds_dwordx4 v[214:215], off
	s_add_i32 m0, s54, 0x2000
	s_add_u32 s54, s22, 0x40000
	v_lshl_add_u64 v[216:217], s[22:23], 0, v[128:129]
	s_addc_u32 s55, s23, 0
	s_add_i32 s56, s45, s34
	global_load_lds_dwordx4 v[216:217], off
	s_mov_b32 m0, s56
	v_lshl_add_u64 v[220:221], s[24:25], 0, v[130:131]
	global_load_lds_dwordx4 v132, s[54:55]
	s_add_i32 m0, s56, 0x2000
	s_nop 0
	global_load_lds_dwordx4 v128, s[54:55]
	v_lshl_add_u64 v[218:219], s[24:25], 0, v[134:135]
	s_mov_b32 m0, s19
	s_nop 0
	global_load_lds_dwordx4 v[218:219], off
	s_mov_b32 m0, s37
	s_nop 0
	global_load_lds_dwordx4 v[220:221], off
	s_waitcnt vmcnt(8)
	s_waitcnt lgkmcnt(0)
	s_barrier
; #define PG8_STAGE(bufoff, gbase, voff) do { _Pragma("unroll") for (int _i = 0; _i < 2; ++_i) \
;         __builtin_amdgcn_global_load_lds((const unsigned*)((const char*)(gbase) + (voff)[_i]), (PG8_LAS unsigned*)(lds + (bufoff) + ldsw + _i * 8192), 16, 0, 0); } while (0)
; #define PG8_LDA(dst, b, h) do { _Pragma("unroll") for (int m = 0; m < 4; ++m) _Pragma("unroll") for (int k = 0; k < 2; ++k) dst[m][k] = *(const PG8_LAS bf16x8*)(lds + PG8_SA(b, h) + aoff + m * 2048 + k * 1024); } while (0)
; #define PG8_LDB(dst, b, h) do { _Pragma("unroll") for (int n = 0; n < 2; ++n) _Pragma("unroll") for (int k = 0; k < 2; ++k) dst[n][k] = *(const PG8_LAS bf16x8*)(lds + PG8_SB(b, h) + boff + n * 2048 + k * 1024); } while (0)
; #define PG8_MMA(ai, bj, At, Bt) do { __builtin_amdgcn_s_setprio(1); _Pragma("unroll") for (int m = 0; m < 4; ++m) _Pragma("unroll") for (int n = 0; n < 2; ++n) _Pragma("unroll") for (int k = 0; k < 2; ++k) \
;         acc[ai][bj][m][n] = __builtin_amdgcn_mfma_f32_16x16x32_bf16(Bt[n][k], At[m][k], acc[ai][bj][m][n], 0, 0, 0); __builtin_amdgcn_s_setprio(0); } while (0)
; #define PG8_WAIT_V(n) asm volatile("s_waitcnt vmcnt(" #n ")" ::: "memory")
; #define PG8_WAIT_L(n) asm volatile("s_waitcnt lgkmcnt(" #n ")" ::: "memory")
; #define PG8_BAR __builtin_amdgcn_s_barrier()
; #define PG8_SCHED __builtin_amdgcn_sched_barrier(0)
; template <class Epi, class Sched, bool ALIGN_EPI = false, bool SP2 = false>
; __device__ __forceinline__ void gemm_phase(PG8_LAS unsigned char* lds, const Gemm g, const Sched& S, const Epi& E, const int tid) {
;     ...
;             PG8_WAIT_V(8); PG8_WAIT_L(0); PG8_BAR; PG8_MMA(1, 0, At, B0); PG8_MMA(1, 1, At, B1); PG8_BAR; PG8_SCHED;
;             PG8_LDB(B0, 1, 0); PG8_LDB(B1, 1, 1); PG8_SCHED; PG8_LDA(At, 1, 0); PG8_STAGE(PG8_SA(0, 1), a2 + hstep, voffA);
;             PG8_WAIT_V(8); PG8_WAIT_L(0); PG8_BAR; PG8_MMA(0, 0, At, B0); PG8_MMA(0, 1, At, B1); PG8_BAR; PG8_SCHED;
	s_setprio 1
	s_waitcnt lgkmcnt(0)
	v_mfma_f32_16x16x32_bf16 v[60:63], v[150:153], v[182:185], v[60:63]
	v_mfma_f32_16x16x32_bf16 v[52:55], v[158:161], v[182:185], v[52:55]
	v_mfma_f32_16x16x32_bf16 v[44:47], v[150:153], v[190:193], v[44:47]
	v_mfma_f32_16x16x32_bf16 v[36:39], v[158:161], v[190:193], v[36:39]
	v_mfma_f32_16x16x32_bf16 v[28:31], v[150:153], v[198:201], v[28:31]
	v_mfma_f32_16x16x32_bf16 v[20:23], v[158:161], v[198:201], v[20:23]
	v_mfma_f32_16x16x32_bf16 v[12:15], v[150:153], v[206:209], v[12:15]
	v_mfma_f32_16x16x32_bf16 v[4:7], v[158:161], v[206:209], v[4:7]
	v_mfma_f32_16x16x32_bf16 v[60:63], v[154:157], v[186:189], v[60:63]
	v_mfma_f32_16x16x32_bf16 v[52:55], v[162:165], v[186:189], v[52:55]
	v_mfma_f32_16x16x32_bf16 v[44:47], v[154:157], v[194:197], v[44:47]
	v_mfma_f32_16x16x32_bf16 v[36:39], v[162:165], v[194:197], v[36:39]
	v_mfma_f32_16x16x32_bf16 v[28:31], v[154:157], v[202:205], v[28:31]
	v_mfma_f32_16x16x32_bf16 v[20:23], v[162:165], v[202:205], v[20:23]
	v_mfma_f32_16x16x32_bf16 v[12:15], v[154:157], v[210:213], v[12:15]
	v_mfma_f32_16x16x32_bf16 v[4:7], v[162:165], v[210:213], v[4:7]
	s_setprio 0
	s_setprio 1
	v_mfma_f32_16x16x32_bf16 v[56:59], v[166:169], v[182:185], v[56:59]
	v_mfma_f32_16x16x32_bf16 v[48:51], v[174:177], v[182:185], v[48:51]
	v_mfma_f32_16x16x32_bf16 v[40:43], v[166:169], v[190:193], v[40:43]
	v_mfma_f32_16x16x32_bf16 v[32:35], v[174:177], v[190:193], v[32:35]
	v_mfma_f32_16x16x32_bf16 v[24:27], v[166:169], v[198:201], v[24:27]
	v_mfma_f32_16x16x32_bf16 v[16:19], v[174:177], v[198:201], v[16:19]
	v_mfma_f32_16x16x32_bf16 v[8:11], v[166:169], v[206:209], v[8:11]
	v_mfma_f32_16x16x32_bf16 v[0:3], v[174:177], v[206:209], v[0:3]
	v_mfma_f32_16x16x32_bf16 v[56:59], v[170:173], v[186:189], v[56:59]
	v_mfma_f32_16x16x32_bf16 v[48:51], v[178:181], v[186:189], v[48:51]
	v_mfma_f32_16x16x32_bf16 v[40:43], v[170:173], v[194:197], v[40:43]
	v_mfma_f32_16x16x32_bf16 v[32:35], v[178:181], v[194:197], v[32:35]
	v_mfma_f32_16x16x32_bf16 v[24:27], v[170:173], v[202:205], v[24:27]
	v_mfma_f32_16x16x32_bf16 v[16:19], v[178:181], v[202:205], v[16:19]
	v_mfma_f32_16x16x32_bf16 v[8:11], v[170:173], v[210:213], v[8:11]
	v_mfma_f32_16x16x32_bf16 v[0:3], v[178:181], v[210:213], v[0:3]
	s_setprio 0
	s_barrier
	s_add_i32 s54, 0, 0x18000
	s_add_i32 s55, 0, 0x1c000
	v_add_u32_e32 v162, s54, v145
	v_add_u32_e32 v178, s55, v145
	ds_read_b128 v[150:153], v162
	ds_read_b128 v[154:157], v162 offset:1024
	ds_read_b128 v[158:161], v162 offset:2048
	ds_read_b128 v[162:165], v162 offset:3072
	ds_read_b128 v[166:169], v178
	ds_read_b128 v[170:173], v178 offset:1024
	ds_read_b128 v[174:177], v178 offset:2048
	ds_read_b128 v[178:181], v178 offset:3072
	s_add_u32 s24, s24, 0x40000
	s_addc_u32 s25, s25, 0
	s_mov_b32 m0, s38
	ds_read_b128 v[182:185], v149 offset:32768
	ds_read_b128 v[186:189], v149 offset:33792
	ds_read_b128 v[190:193], v149 offset:34816
	ds_read_b128 v[194:197], v149 offset:35840
	ds_read_b128 v[198:201], v149 offset:36864
	ds_read_b128 v[202:205], v149 offset:37888
	ds_read_b128 v[206:209], v149 offset:38912
	ds_read_b128 v[210:213], v149 offset:39936
	global_load_lds_dwordx4 v134, s[24:25]
	v_lshl_add_u64 v[222:223], s[24:25], 0, v[130:131]
	s_mov_b32 m0, s39
	s_nop 0
	global_load_lds_dwordx4 v[222:223], off
	s_waitcnt vmcnt(8)
	s_waitcnt lgkmcnt(0)
	s_barrier
	s_setprio 1
	s_waitcnt lgkmcnt(0)
	v_mfma_f32_16x16x32_bf16 v[124:127], v[150:153], v[182:185], v[124:127]
	v_mfma_f32_16x16x32_bf16 v[116:119], v[158:161], v[182:185], v[116:119]
	v_mfma_f32_16x16x32_bf16 v[108:111], v[150:153], v[190:193], v[108:111]
	v_mfma_f32_16x16x32_bf16 v[100:103], v[158:161], v[190:193], v[100:103]
	v_mfma_f32_16x16x32_bf16 v[92:95], v[150:153], v[198:201], v[92:95]
	v_mfma_f32_16x16x32_bf16 v[84:87], v[158:161], v[198:201], v[84:87]
	v_mfma_f32_16x16x32_bf16 v[76:79], v[150:153], v[206:209], v[76:79]
	v_mfma_f32_16x16x32_bf16 v[68:71], v[158:161], v[206:209], v[68:71]
	v_mfma_f32_16x16x32_bf16 v[124:127], v[154:157], v[186:189], v[124:127]
	v_mfma_f32_16x16x32_bf16 v[116:119], v[162:165], v[186:189], v[116:119]
	v_mfma_f32_16x16x32_bf16 v[108:111], v[154:157], v[194:197], v[108:111]
	v_mfma_f32_16x16x32_bf16 v[100:103], v[162:165], v[194:197], v[100:103]
	v_mfma_f32_16x16x32_bf16 v[92:95], v[154:157], v[202:205], v[92:95]
	v_mfma_f32_16x16x32_bf16 v[84:87], v[162:165], v[202:205], v[84:87]
	v_mfma_f32_16x16x32_bf16 v[76:79], v[154:157], v[210:213], v[76:79]
	v_mfma_f32_16x16x32_bf16 v[68:71], v[162:165], v[210:213], v[68:71]
	s_setprio 0
	s_setprio 1
	v_mfma_f32_16x16x32_bf16 v[120:123], v[166:169], v[182:185], v[120:123]
	v_mfma_f32_16x16x32_bf16 v[112:115], v[174:177], v[182:185], v[112:115]
	v_mfma_f32_16x16x32_bf16 v[104:107], v[166:169], v[190:193], v[104:107]
	v_mfma_f32_16x16x32_bf16 v[96:99], v[174:177], v[190:193], v[96:99]
	v_mfma_f32_16x16x32_bf16 v[88:91], v[166:169], v[198:201], v[88:91]
	v_mfma_f32_16x16x32_bf16 v[80:83], v[174:177], v[198:201], v[80:83]
	v_mfma_f32_16x16x32_bf16 v[72:75], v[166:169], v[206:209], v[72:75]
	v_mfma_f32_16x16x32_bf16 v[64:67], v[174:177], v[206:209], v[64:67]
	v_mfma_f32_16x16x32_bf16 v[120:123], v[170:173], v[186:189], v[120:123]
	v_mfma_f32_16x16x32_bf16 v[112:115], v[178:181], v[186:189], v[112:115]
	v_mfma_f32_16x16x32_bf16 v[104:107], v[170:173], v[194:197], v[104:107]
	v_mfma_f32_16x16x32_bf16 v[96:99], v[178:181], v[194:197], v[96:99]
	v_mfma_f32_16x16x32_bf16 v[88:91], v[170:173], v[202:205], v[88:91]
	v_mfma_f32_16x16x32_bf16 v[80:83], v[178:181], v[202:205], v[80:83]
	v_mfma_f32_16x16x32_bf16 v[72:75], v[170:173], v[210:213], v[72:75]
	v_mfma_f32_16x16x32_bf16 v[64:67], v[178:181], v[210:213], v[64:67]
	s_setprio 0
	s_barrier
; #define PG8_STAGE(bufoff, gbase, voff) do { _Pragma("unroll") for (int _i = 0; _i < 2; ++_i) \
;         __builtin_amdgcn_global_load_lds((const unsigned*)((const char*)(gbase) + (voff)[_i]), (PG8_LAS unsigned*)(lds + (bufoff) + ldsw + _i * 8192), 16, 0, 0); } while (0)
; #define PG8_LDA(dst, b, h) do { _Pragma("unroll") for (int m = 0; m < 4; ++m) _Pragma("unroll") for (int k = 0; k < 2; ++k) dst[m][k] = *(const PG8_LAS bf16x8*)(lds + PG8_SA(b, h) + aoff + m * 2048 + k * 1024); } while (0)
; #define PG8_MMA(ai, bj, At, Bt) do { __builtin_amdgcn_s_setprio(1); _Pragma("unroll") for (int m = 0; m < 4; ++m) _Pragma("unroll") for (int n = 0; n < 2; ++n) _Pragma("unroll") for (int k = 0; k < 2; ++k) \
;         acc[ai][bj][m][n] = __builtin_amdgcn_mfma_f32_16x16x32_bf16(Bt[n][k], At[m][k], acc[ai][bj][m][n], 0, 0, 0); __builtin_amdgcn_s_setprio(0); } while (0)
; #define PG8_WAIT_V(n) asm volatile("s_waitcnt vmcnt(" #n ")" ::: "memory")
; #define PG8_WAIT_L(n) asm volatile("s_waitcnt lgkmcnt(" #n ")" ::: "memory")
; #define PG8_BAR __builtin_amdgcn_s_barrier()
; #define PG8_SCHED __builtin_amdgcn_sched_barrier(0)
; template <class Epi, class Sched, bool ALIGN_EPI = false, bool SP2 = false>
; __device__ __forceinline__ void gemm_phase(PG8_LAS unsigned char* lds, const Gemm g, const Sched& S, const Epi& E, const int tid) {
;     ...
;         for (int t = 0; t < nt; t += 2) {
;             const bool last = (t == nt - 2);
;             const char* a1 = cA + (size_t)(t + 1) * kstep;
;             const char* a2 = last ? nA : cA + (size_t)(t + 2) * kstep; const char* b2 = last ? nB : cB + (size_t)(t + 2) * kstep;
;     ...
;             PG8_LDA(At, 1, 1); PG8_STAGE(PG8_SB(1, 0), b3, voffB); PG8_STAGE(PG8_SB(1, 1), b3 + hstep, voffB); PG8_STAGE(PG8_SA(1, 0), a3, voffA);
;             PG8_WAIT_V(8); PG8_WAIT_L(0); PG8_BAR; PG8_MMA(1, 0, At, B0); PG8_MMA(1, 1, At, B1); PG8_BAR; PG8_SCHED;
	s_add_i32 s24, s54, s34
	v_lshl_add_u64 v[214:215], v[214:215], 0, s[8:9]
	s_mov_b32 m0, s24
	ds_read_b128 v[182:185], v149 offset:49152
	ds_read_b128 v[186:189], v149 offset:50176
	ds_read_b128 v[190:193], v149 offset:51200
	ds_read_b128 v[194:197], v149 offset:52224
	ds_read_b128 v[198:201], v149 offset:53248
	ds_read_b128 v[202:205], v149 offset:54272
	ds_read_b128 v[206:209], v149 offset:55296
	ds_read_b128 v[210:213], v149 offset:56320
	global_load_lds_dwordx4 v[214:215], off
	s_add_i32 m0, s24, 0x2000
	s_add_u32 s22, s22, 0x40080
	v_lshl_add_u64 v[214:215], v[216:217], 0, s[8:9]
	s_addc_u32 s23, s23, 0
	s_add_i32 s24, s55, s34
	global_load_lds_dwordx4 v[214:215], off
	s_mov_b32 m0, s24
	s_nop 0
	global_load_lds_dwordx4 v132, s[22:23]
	s_add_i32 m0, s24, 0x2000
	s_nop 0
	global_load_lds_dwordx4 v128, s[22:23]
	v_lshl_add_u64 v[214:215], v[218:219], 0, s[8:9]
	s_mov_b32 m0, s40
	s_nop 0
	global_load_lds_dwordx4 v[214:215], off
	v_lshl_add_u64 v[214:215], v[220:221], 0, s[8:9]
	s_mov_b32 m0, s41
	s_nop 0
	global_load_lds_dwordx4 v[214:215], off
	s_waitcnt vmcnt(8)
	s_waitcnt lgkmcnt(0)
	s_barrier
	s_setprio 1
	s_waitcnt lgkmcnt(0)
	v_mfma_f32_16x16x32_bf16 v[60:63], v[150:153], v[182:185], v[60:63]
	v_mfma_f32_16x16x32_bf16 v[52:55], v[158:161], v[182:185], v[52:55]
	v_mfma_f32_16x16x32_bf16 v[44:47], v[150:153], v[190:193], v[44:47]
	v_mfma_f32_16x16x32_bf16 v[36:39], v[158:161], v[190:193], v[36:39]
	v_mfma_f32_16x16x32_bf16 v[28:31], v[150:153], v[198:201], v[28:31]
	v_mfma_f32_16x16x32_bf16 v[20:23], v[158:161], v[198:201], v[20:23]
	v_mfma_f32_16x16x32_bf16 v[12:15], v[150:153], v[206:209], v[12:15]
	v_mfma_f32_16x16x32_bf16 v[4:7], v[158:161], v[206:209], v[4:7]
	v_mfma_f32_16x16x32_bf16 v[60:63], v[154:157], v[186:189], v[60:63]
	v_mfma_f32_16x16x32_bf16 v[52:55], v[162:165], v[186:189], v[52:55]
	v_mfma_f32_16x16x32_bf16 v[44:47], v[154:157], v[194:197], v[44:47]
	v_mfma_f32_16x16x32_bf16 v[36:39], v[162:165], v[194:197], v[36:39]
	v_mfma_f32_16x16x32_bf16 v[28:31], v[154:157], v[202:205], v[28:31]
	v_mfma_f32_16x16x32_bf16 v[20:23], v[162:165], v[202:205], v[20:23]
	v_mfma_f32_16x16x32_bf16 v[12:15], v[154:157], v[210:213], v[12:15]
	v_mfma_f32_16x16x32_bf16 v[4:7], v[162:165], v[210:213], v[4:7]
	s_setprio 0
	s_setprio 1
	v_mfma_f32_16x16x32_bf16 v[56:59], v[166:169], v[182:185], v[56:59]
	v_mfma_f32_16x16x32_bf16 v[48:51], v[174:177], v[182:185], v[48:51]
	v_mfma_f32_16x16x32_bf16 v[40:43], v[166:169], v[190:193], v[40:43]
	v_mfma_f32_16x16x32_bf16 v[32:35], v[174:177], v[190:193], v[32:35]
	v_mfma_f32_16x16x32_bf16 v[24:27], v[166:169], v[198:201], v[24:27]
	v_mfma_f32_16x16x32_bf16 v[16:19], v[174:177], v[198:201], v[16:19]
	v_mfma_f32_16x16x32_bf16 v[8:11], v[166:169], v[206:209], v[8:11]
	v_mfma_f32_16x16x32_bf16 v[0:3], v[174:177], v[206:209], v[0:3]
	v_mfma_f32_16x16x32_bf16 v[56:59], v[170:173], v[186:189], v[56:59]
	v_mfma_f32_16x16x32_bf16 v[48:51], v[178:181], v[186:189], v[48:51]
	v_mfma_f32_16x16x32_bf16 v[40:43], v[170:173], v[194:197], v[40:43]
	v_mfma_f32_16x16x32_bf16 v[32:35], v[178:181], v[194:197], v[32:35]
	v_mfma_f32_16x16x32_bf16 v[24:27], v[170:173], v[202:205], v[24:27]
	v_mfma_f32_16x16x32_bf16 v[16:19], v[178:181], v[202:205], v[16:19]
	v_mfma_f32_16x16x32_bf16 v[8:11], v[170:173], v[210:213], v[8:11]
	v_mfma_f32_16x16x32_bf16 v[0:3], v[178:181], v[210:213], v[0:3]
	s_setprio 0
	s_barrier
	s_add_i32 s53, s53, 2
	s_add_u32 s20, s20, 0x100
	s_addc_u32 s21, s21, 0
	s_add_u32 s51, s51, 0x100
	s_addc_u32 s52, s52, 0
	s_cmp_gt_u32 s53, 13
	s_cbranch_scc0 .LBB0_1704
	s_and_b64 vcc, exec, s[10:11]
	s_cbranch_vccz .LBB0_1707
	s_barrier

; #define PG8_STAGE(bufoff, gbase, voff) do { _Pragma("unroll") for (int _i = 0; _i < 2; ++_i) \
;         __builtin_amdgcn_global_load_lds((const unsigned*)((const char*)(gbase) + (voff)[_i]), (PG8_LAS unsigned*)(lds + (bufoff) + ldsw + _i * 8192), 16, 0, 0); } while (0)
; #define PG8_WAIT_V(n) asm volatile("s_waitcnt vmcnt(" #n ")" ::: "memory")
; #define PG8_BAR __builtin_amdgcn_s_barrier()
; template <class Epi, class Sched, bool ALIGN_EPI = false, bool SP2 = false>
; __device__ __forceinline__ void gemm_phase(PG8_LAS unsigned char* lds, const Gemm g, const Sched& S, const Epi& E, const int tid) {
;     const int wid = __builtin_amdgcn_readfirstlane(tid >> 6), lane = tid & 63, wr = wid >> 2, wc = wid & 3, fr = lane & 15, fq = lane >> 4;
;     const int K = g.K, nt = K / BK;
;     unsigned voffA[2], voffB[2];
; #pragma unroll
;     for (int i = 0; i < 2; ++i) { int R, C; stage_rc(tid * 16 + i * 8192, R, C); const int Rb = Epi::PERM ? ((R & ~31) + perm32(R & 31)) : R;
;         voffA[i] = (unsigned)(R * K + C) * 2u; voffB[i] = (unsigned)(Rb * K + C) * 2u; }
;     const size_t kstep = (size_t)(BK * 2);
;     const size_t hstep = (size_t)HALF * K * 2;
;     const size_t tstep = 2 * hstep;
;     const unsigned ldsw = (unsigned)wid * 1024u;
;     const int aoff = lds_byte(wr * 64 + fr, fq * 8), boff = lds_byte(wc * 32 + fr, fq * 8);
;     ...
;         PG8_STAGE(PG8_SB(1, 0), cB + kstep, voffB); PG8_STAGE(PG8_SA(1, 0), cA + kstep, voffA); PG8_STAGE(PG8_SB(1, 1), cB + hstep + kstep, voffB);
;         PG8_WAIT_V(6); PG8_BAR;
.LBB0_1769:
	s_add_u32 s42, s3, 0x8800000
	s_addc_u32 s43, s2, 0
	s_add_u32 s44, s3, 0x10800000
	s_addc_u32 s45, s2, 0
	s_add_u32 s46, s3, 0x3017000
	s_addc_u32 s47, s2, 0
	s_lshl_b32 s8, s8, 5
	s_and_b32 s20, s8, 0x60
	s_mov_b64 s[8:9], 0x80
	s_add_i32 m0, s37, 0x18000
	v_lshl_add_u64 v[6:7], v[6:7], 0, s[8:9]
	s_lshl_b32 s14, s1, 13
	s_lshl_b32 s15, s20, 7
	s_waitcnt vmcnt(2)
	s_barrier
	global_load_lds_dwordx4 v[6:7], off
	v_lshl_add_u64 v[4:5], v[4:5], 0, s[8:9]
	s_add_i32 m0, s37, 0x1a000
	s_add_i32 s48, s37, 0x8000
	s_add_i32 s49, s37, 0xa000
	global_load_lds_dwordx4 v[4:5], off
	v_lshl_add_u64 v[0:1], v[0:1], 0, s[8:9]
	s_mov_b32 m0, s48
	s_add_u32 s12, s18, 0xb0080
	global_load_lds_dwordx4 v[0:1], off
	v_lshl_add_u64 v[0:1], v[2:3], 0, s[8:9]
	s_mov_b32 m0, s49
	s_addc_u32 s13, s19, 0
	global_load_lds_dwordx4 v[0:1], off
	s_add_i32 m0, s37, 0x1c000
	global_load_lds_dwordx4 v146, s[12:13]
	s_add_i32 m0, s37, 0x1e000
	v_lshrrev_b32_e32 v2, 1, v8
	global_load_lds_dwordx4 v150, s[12:13]
	v_and_b32_e32 v4, 24, v2
	v_and_b32_e32 v1, 15, v8
	v_lshlrev_b32_e32 v2, 1, v4
	v_lshl_or_b32 v0, s1, 6, v1
	v_lshl_or_b32 v1, v1, 6, v2
	v_lshlrev_b32_e32 v2, 2, v8
	v_and_b32_e32 v2, 32, v2
	v_bitop3_b32 v5, v1, s14, v2 bitop3:0xde
	v_bitop3_b32 v178, s15, v1, v2 bitop3:0xf6
	v_ashrrev_i32_e32 v1, 31, v0
	v_lshlrev_b64 v[152:153], 10, v[0:1]
	v_or_b32_e32 v2, 16, v0
	s_mov_b64 s[12:13], 0x20000
	v_ashrrev_i32_e32 v3, 31, v2
	v_lshl_add_u64 v[160:161], v[152:153], 0, s[12:13]
	s_mov_b64 s[12:13], 0x24000
	s_cmpk_lt_u32 s10, 0x100
	v_lshlrev_b64 v[154:155], 10, v[2:3]
	v_or_b32_e32 v2, 32, v0
	v_or_b32_e32 v0, 48, v0
	v_lshl_add_u64 v[162:163], v[152:153], 0, s[12:13]
	s_mov_b64 s[12:13], 0x28000
	s_sext_i32_i8 s55, s11
	s_cselect_b64 s[10:11], -1, 0
	v_ashrrev_i32_e32 v1, 31, v0
	v_lshl_add_u64 v[164:165], v[152:153], 0, s[12:13]
	s_mov_b64 s[12:13], 0x2c000
	s_ashr_i32 s50, s26, 31
	v_lshlrev_b64 v[158:159], 10, v[0:1]
	v_lshl_add_u64 v[166:167], v[152:153], 0, s[12:13]
	s_add_u32 s12, s3, 0x3023000
	v_lshrrev_b32_e32 v1, 1, v9
	v_mul_lo_u32 v0, v11, s0
	s_mov_b32 s1, 0xb000
	s_addc_u32 s13, s2, 0
	v_mad_u64_u32 v[0:1], s[2:3], v1, s1, v[0:1]
	v_or_b32_e32 v0, v0, v10
	s_mov_b64 s[14:15], 0xb0080
	v_add_lshl_u32 v0, v0, v12, 1
	v_mov_b32_e32 v1, v147
	v_lshl_add_u64 v[168:169], v[0:1], 0, s[14:15]
	v_lshrrev_b32_e32 v1, 1, v13
	v_mul_lo_u32 v0, v14, s0
	v_mad_u64_u32 v[0:1], s[0:1], v1, s1, v[0:1]
	s_waitcnt vmcnt(6)
	v_or_b32_e32 v0, v0, v15
	v_ashrrev_i32_e32 v3, 31, v2
	v_add_lshl_u32 v0, v0, v16, 1
	v_mov_b32_e32 v1, v147
	s_add_i32 s51, 0, 0x10000
	s_add_i32 s52, 0, 0x14000
	v_lshlrev_b64 v[156:157], 10, v[2:3]
	v_or_b32_e32 v179, s20, v4
	v_lshl_add_u64 v[170:171], v[0:1], 0, s[14:15]
	v_mov_b64_e32 v[172:173], 0x200
	v_mov_b64_e32 v[174:175], 0x1ff
	v_add_u32_e32 v180, s51, v178
	v_add_u32_e32 v181, s52, v178
	v_add_u32_e32 v182, 0, v5
	s_barrier
	s_branch .LBB0_1772

; #define PG8_STAGE(bufoff, gbase, voff) do { _Pragma("unroll") for (int _i = 0; _i < 2; ++_i) \
;         __builtin_amdgcn_global_load_lds((const unsigned*)((const char*)(gbase) + (voff)[_i]), (PG8_LAS unsigned*)(lds + (bufoff) + ldsw + _i * 8192), 16, 0, 0); } while (0)
; #define PG8_LDA(dst, b, h) do { _Pragma("unroll") for (int m = 0; m < 4; ++m) _Pragma("unroll") for (int k = 0; k < 2; ++k) dst[m][k] = *(const PG8_LAS bf16x8*)(lds + PG8_SA(b, h) + aoff + m * 2048 + k * 1024); } while (0)
; #define PG8_LDB(dst, b, h) do { _Pragma("unroll") for (int n = 0; n < 2; ++n) _Pragma("unroll") for (int k = 0; k < 2; ++k) dst[n][k] = *(const PG8_LAS bf16x8*)(lds + PG8_SB(b, h) + boff + n * 2048 + k * 1024); } while (0)
; #define PG8_MMA(ai, bj, At, Bt) do { __builtin_amdgcn_s_setprio(1); _Pragma("unroll") for (int m = 0; m < 4; ++m) _Pragma("unroll") for (int n = 0; n < 2; ++n) _Pragma("unroll") for (int k = 0; k < 2; ++k) \
;         acc[ai][bj][m][n] = __builtin_amdgcn_mfma_f32_16x16x32_bf16(Bt[n][k], At[m][k], acc[ai][bj][m][n], 0, 0, 0); __builtin_amdgcn_s_setprio(0); } while (0)
; #define PG8_WAIT_V(n) asm volatile("s_waitcnt vmcnt(" #n ")" ::: "memory")
; #define PG8_WAIT_L(n) asm volatile("s_waitcnt lgkmcnt(" #n ")" ::: "memory")
; #define PG8_BAR __builtin_amdgcn_s_barrier()
; #define PG8_SCHED __builtin_amdgcn_sched_barrier(0)
; template <class Epi, class Sched, bool ALIGN_EPI = false, bool SP2 = false>
; __device__ __forceinline__ void gemm_phase(PG8_LAS unsigned char* lds, const Gemm g, const Sched& S, const Epi& E, const int tid) {
;     ...
;             const bool last = (t == nt - 2);
;             const char* a1 = cA + (size_t)(t + 1) * kstep;
;             const char* a2 = last ? nA : cA + (size_t)(t + 2) * kstep; const char* b2 = last ? nB : cB + (size_t)(t + 2) * kstep;
;             const char* a3 = a2 + kstep; const char* b3 = b2 + kstep;
;             if (last && has_next) S.a_ready(nxt);
;             if constexpr (SP2) {
;             PG8_LDB(B0, 0, 0); PG8_LDB(B1, 0, 1); PG8_SCHED; PG8_LDA(At, 0, 0); PG8_STAGE(PG8_SA(1, 1), a1 + hstep, voffA);
;             PG8_WAIT_V(8); PG8_WAIT_L(0); PG8_BAR; PG8_MMA(0, 0, At, B0); PG8_MMA(0, 1, At, B1); PG8_BAR; PG8_SCHED;
;             PG8_LDA(At, 0, 1); PG8_STAGE(PG8_SB(0, 0), b2, voffB); PG8_STAGE(PG8_SB(0, 1), b2 + hstep, voffB); PG8_STAGE(PG8_SA(0, 0), a2, voffA);
.LBB0_1783:
	ds_read_b128 v[128:131], v180
	ds_read_b128 v[132:135], v180 offset:1024
	ds_read_b128 v[136:139], v180 offset:2048
	ds_read_b128 v[140:143], v180 offset:3072
	ds_read_b128 v[184:187], v181
	ds_read_b128 v[188:191], v181 offset:1024
	ds_read_b128 v[192:195], v181 offset:2048
	ds_read_b128 v[196:199], v181 offset:3072
	s_add_u32 s18, s16, 0x100
	s_addc_u32 s19, s17, 0
	s_cmp_eq_u32 s56, 40
	s_cselect_b32 s23, s3, s19
	s_cselect_b32 s22, s2, s18
	s_cselect_b32 s21, s15, s33
	s_cselect_b32 s20, s14, s25
	s_add_i32 m0, s37, 0xc000
	ds_read_b128 v[200:203], v182
	ds_read_b128 v[204:207], v182 offset:1024
	ds_read_b128 v[208:211], v182 offset:2048
	ds_read_b128 v[212:215], v182 offset:3072
	ds_read_b128 v[216:219], v182 offset:4096
	ds_read_b128 v[220:223], v182 offset:5120
	ds_read_b128 v[224:227], v182 offset:6144
	ds_read_b128 v[228:231], v182 offset:7168
	global_load_lds_dwordx4 v168, s[16:17]
	s_add_i32 m0, s37, 0xe000
	s_nop 0
	global_load_lds_dwordx4 v170, s[16:17]
	s_waitcnt vmcnt(8)
	s_waitcnt lgkmcnt(0)
	s_barrier
	s_setprio 1
	s_waitcnt lgkmcnt(0)
	v_mfma_f32_16x16x32_bf16 v[124:127], v[128:131], v[200:203], v[124:127]
	v_mfma_f32_16x16x32_bf16 v[120:123], v[136:139], v[200:203], v[120:123]
	v_mfma_f32_16x16x32_bf16 v[116:119], v[128:131], v[208:211], v[116:119]
	v_mfma_f32_16x16x32_bf16 v[104:107], v[136:139], v[208:211], v[104:107]
	v_mfma_f32_16x16x32_bf16 v[100:103], v[128:131], v[216:219], v[100:103]
	v_mfma_f32_16x16x32_bf16 v[88:91], v[136:139], v[216:219], v[88:91]
	v_mfma_f32_16x16x32_bf16 v[84:87], v[128:131], v[224:227], v[84:87]
	v_mfma_f32_16x16x32_bf16 v[72:75], v[136:139], v[224:227], v[72:75]
	v_mfma_f32_16x16x32_bf16 v[124:127], v[132:135], v[204:207], v[124:127]
	v_mfma_f32_16x16x32_bf16 v[120:123], v[140:143], v[204:207], v[120:123]
	v_mfma_f32_16x16x32_bf16 v[116:119], v[132:135], v[212:215], v[116:119]
	v_mfma_f32_16x16x32_bf16 v[104:107], v[140:143], v[212:215], v[104:107]
	v_mfma_f32_16x16x32_bf16 v[100:103], v[132:135], v[220:223], v[100:103]
	v_mfma_f32_16x16x32_bf16 v[88:91], v[140:143], v[220:223], v[88:91]
	v_mfma_f32_16x16x32_bf16 v[84:87], v[132:135], v[228:231], v[84:87]
	v_mfma_f32_16x16x32_bf16 v[72:75], v[140:143], v[228:231], v[72:75]
	s_setprio 0
	s_setprio 1
	v_mfma_f32_16x16x32_bf16 v[112:115], v[184:187], v[200:203], v[112:115]
	v_mfma_f32_16x16x32_bf16 v[108:111], v[192:195], v[200:203], v[108:111]
	v_mfma_f32_16x16x32_bf16 v[96:99], v[184:187], v[208:211], v[96:99]
	v_mfma_f32_16x16x32_bf16 v[92:95], v[192:195], v[208:211], v[92:95]
	v_mfma_f32_16x16x32_bf16 v[80:83], v[184:187], v[216:219], v[80:83]
	v_mfma_f32_16x16x32_bf16 v[76:79], v[192:195], v[216:219], v[76:79]
	v_mfma_f32_16x16x32_bf16 v[68:71], v[184:187], v[224:227], v[68:71]
	v_mfma_f32_16x16x32_bf16 v[64:67], v[192:195], v[224:227], v[64:67]
	v_mfma_f32_16x16x32_bf16 v[112:115], v[188:191], v[204:207], v[112:115]
	v_mfma_f32_16x16x32_bf16 v[108:111], v[196:199], v[204:207], v[108:111]
	v_mfma_f32_16x16x32_bf16 v[96:99], v[188:191], v[212:215], v[96:99]
	v_mfma_f32_16x16x32_bf16 v[92:95], v[196:199], v[212:215], v[92:95]
	v_mfma_f32_16x16x32_bf16 v[80:83], v[188:191], v[220:223], v[80:83]
	v_mfma_f32_16x16x32_bf16 v[76:79], v[196:199], v[220:223], v[76:79]
	v_mfma_f32_16x16x32_bf16 v[68:71], v[188:191], v[228:231], v[68:71]
	v_mfma_f32_16x16x32_bf16 v[64:67], v[196:199], v[228:231], v[64:67]
	s_setprio 0
	s_barrier
	s_add_i32 s16, s51, s36
	v_lshl_add_u64 v[176:177], s[20:21], 0, v[146:147]
	s_mov_b32 m0, s16
	ds_read_b128 v[200:203], v182 offset:16384
	ds_read_b128 v[204:207], v182 offset:17408
	ds_read_b128 v[208:211], v182 offset:18432
	ds_read_b128 v[212:215], v182 offset:19456
	ds_read_b128 v[216:219], v182 offset:20480
	ds_read_b128 v[220:223], v182 offset:21504
	ds_read_b128 v[224:227], v182 offset:22528
	ds_read_b128 v[228:231], v182 offset:23552
	global_load_lds_dwordx4 v[176:177], off
	s_add_i32 m0, s16, 0x2000
	s_add_u32 s16, s20, 0xb0000
	v_lshl_add_u64 v[232:233], s[20:21], 0, v[150:151]
	s_addc_u32 s17, s21, 0
	s_add_i32 s57, s52, s36
	global_load_lds_dwordx4 v[232:233], off
	s_mov_b32 m0, s57
	v_lshl_add_u64 v[236:237], s[22:23], 0, v[148:149]
	global_load_lds_dwordx4 v146, s[16:17]
	s_add_i32 m0, s57, 0x2000
	s_nop 0
	global_load_lds_dwordx4 v150, s[16:17]
	v_lshl_add_u64 v[234:235], s[22:23], 0, v[144:145]
	s_mov_b32 m0, s37
	s_nop 0
	global_load_lds_dwordx4 v[234:235], off
	s_mov_b32 m0, s38
	s_nop 0
	global_load_lds_dwordx4 v[236:237], off
	s_waitcnt vmcnt(8)
	s_waitcnt lgkmcnt(0)
	s_barrier
; #define PG8_STAGE(bufoff, gbase, voff) do { _Pragma("unroll") for (int _i = 0; _i < 2; ++_i) \
;         __builtin_amdgcn_global_load_lds((const unsigned*)((const char*)(gbase) + (voff)[_i]), (PG8_LAS unsigned*)(lds + (bufoff) + ldsw + _i * 8192), 16, 0, 0); } while (0)
; #define PG8_LDA(dst, b, h) do { _Pragma("unroll") for (int m = 0; m < 4; ++m) _Pragma("unroll") for (int k = 0; k < 2; ++k) dst[m][k] = *(const PG8_LAS bf16x8*)(lds + PG8_SA(b, h) + aoff + m * 2048 + k * 1024); } while (0)
; #define PG8_LDB(dst, b, h) do { _Pragma("unroll") for (int n = 0; n < 2; ++n) _Pragma("unroll") for (int k = 0; k < 2; ++k) dst[n][k] = *(const PG8_LAS bf16x8*)(lds + PG8_SB(b, h) + boff + n * 2048 + k * 1024); } while (0)
; #define PG8_MMA(ai, bj, At, Bt) do { __builtin_amdgcn_s_setprio(1); _Pragma("unroll") for (int m = 0; m < 4; ++m) _Pragma("unroll") for (int n = 0; n < 2; ++n) _Pragma("unroll") for (int k = 0; k < 2; ++k) \
;         acc[ai][bj][m][n] = __builtin_amdgcn_mfma_f32_16x16x32_bf16(Bt[n][k], At[m][k], acc[ai][bj][m][n], 0, 0, 0); __builtin_amdgcn_s_setprio(0); } while (0)
; #define PG8_WAIT_V(n) asm volatile("s_waitcnt vmcnt(" #n ")" ::: "memory")
; #define PG8_WAIT_L(n) asm volatile("s_waitcnt lgkmcnt(" #n ")" ::: "memory")
; #define PG8_BAR __builtin_amdgcn_s_barrier()
; #define PG8_SCHED __builtin_amdgcn_sched_barrier(0)
; template <class Epi, class Sched, bool ALIGN_EPI = false, bool SP2 = false>
; __device__ __forceinline__ void gemm_phase(PG8_LAS unsigned char* lds, const Gemm g, const Sched& S, const Epi& E, const int tid) {
;     ...
;             PG8_WAIT_V(8); PG8_WAIT_L(0); PG8_BAR; PG8_MMA(1, 0, At, B0); PG8_MMA(1, 1, At, B1); PG8_BAR; PG8_SCHED;
;             PG8_LDB(B0, 1, 0); PG8_LDB(B1, 1, 1); PG8_SCHED; PG8_LDA(At, 1, 0); PG8_STAGE(PG8_SA(0, 1), a2 + hstep, voffA);
;             PG8_WAIT_V(8); PG8_WAIT_L(0); PG8_BAR; PG8_MMA(0, 0, At, B0); PG8_MMA(0, 1, At, B1); PG8_BAR; PG8_SCHED;
	s_setprio 1
	s_waitcnt lgkmcnt(0)
	v_mfma_f32_16x16x32_bf16 v[60:63], v[128:131], v[200:203], v[60:63]
	v_mfma_f32_16x16x32_bf16 v[56:59], v[136:139], v[200:203], v[56:59]
	v_mfma_f32_16x16x32_bf16 v[52:55], v[128:131], v[208:211], v[52:55]
	v_mfma_f32_16x16x32_bf16 v[40:43], v[136:139], v[208:211], v[40:43]
	v_mfma_f32_16x16x32_bf16 v[36:39], v[128:131], v[216:219], v[36:39]
	v_mfma_f32_16x16x32_bf16 v[24:27], v[136:139], v[216:219], v[24:27]
	v_mfma_f32_16x16x32_bf16 v[20:23], v[128:131], v[224:227], v[20:23]
	v_mfma_f32_16x16x32_bf16 v[8:11], v[136:139], v[224:227], v[8:11]
	v_mfma_f32_16x16x32_bf16 v[60:63], v[132:135], v[204:207], v[60:63]
	v_mfma_f32_16x16x32_bf16 v[56:59], v[140:143], v[204:207], v[56:59]
	v_mfma_f32_16x16x32_bf16 v[52:55], v[132:135], v[212:215], v[52:55]
	v_mfma_f32_16x16x32_bf16 v[40:43], v[140:143], v[212:215], v[40:43]
	v_mfma_f32_16x16x32_bf16 v[36:39], v[132:135], v[220:223], v[36:39]
	v_mfma_f32_16x16x32_bf16 v[24:27], v[140:143], v[220:223], v[24:27]
	v_mfma_f32_16x16x32_bf16 v[20:23], v[132:135], v[228:231], v[20:23]
	v_mfma_f32_16x16x32_bf16 v[8:11], v[140:143], v[228:231], v[8:11]
	s_setprio 0
	s_setprio 1
	v_mfma_f32_16x16x32_bf16 v[48:51], v[184:187], v[200:203], v[48:51]
	v_mfma_f32_16x16x32_bf16 v[44:47], v[192:195], v[200:203], v[44:47]
	v_mfma_f32_16x16x32_bf16 v[32:35], v[184:187], v[208:211], v[32:35]
	v_mfma_f32_16x16x32_bf16 v[28:31], v[192:195], v[208:211], v[28:31]
	v_mfma_f32_16x16x32_bf16 v[16:19], v[184:187], v[216:219], v[16:19]
	v_mfma_f32_16x16x32_bf16 v[12:15], v[192:195], v[216:219], v[12:15]
	v_mfma_f32_16x16x32_bf16 v[4:7], v[184:187], v[224:227], v[4:7]
	v_mfma_f32_16x16x32_bf16 v[0:3], v[192:195], v[224:227], v[0:3]
	v_mfma_f32_16x16x32_bf16 v[48:51], v[188:191], v[204:207], v[48:51]
	v_mfma_f32_16x16x32_bf16 v[44:47], v[196:199], v[204:207], v[44:47]
	v_mfma_f32_16x16x32_bf16 v[32:35], v[188:191], v[212:215], v[32:35]
	v_mfma_f32_16x16x32_bf16 v[28:31], v[196:199], v[212:215], v[28:31]
	v_mfma_f32_16x16x32_bf16 v[16:19], v[188:191], v[220:223], v[16:19]
	v_mfma_f32_16x16x32_bf16 v[12:15], v[196:199], v[220:223], v[12:15]
	v_mfma_f32_16x16x32_bf16 v[4:7], v[188:191], v[228:231], v[4:7]
	v_mfma_f32_16x16x32_bf16 v[0:3], v[196:199], v[228:231], v[0:3]
	s_setprio 0
	s_barrier
	s_add_i32 s57, 0, 0x18000
	s_add_i32 s58, 0, 0x1c000
	v_add_u32_e32 v140, s57, v178
	v_add_u32_e32 v183, s58, v178
	ds_read_b128 v[128:131], v140
	ds_read_b128 v[132:135], v140 offset:1024
	ds_read_b128 v[136:139], v140 offset:2048
	ds_read_b128 v[140:143], v140 offset:3072
	ds_read_b128 v[184:187], v183
	ds_read_b128 v[188:191], v183 offset:1024
	ds_read_b128 v[192:195], v183 offset:2048
	ds_read_b128 v[196:199], v183 offset:3072
	s_add_u32 s16, s22, 0xb0000
	s_addc_u32 s17, s23, 0
	s_mov_b32 m0, s39
	ds_read_b128 v[200:203], v182 offset:32768
	ds_read_b128 v[204:207], v182 offset:33792
	ds_read_b128 v[208:211], v182 offset:34816
	ds_read_b128 v[212:215], v182 offset:35840
	ds_read_b128 v[216:219], v182 offset:36864
	ds_read_b128 v[220:223], v182 offset:37888
	ds_read_b128 v[224:227], v182 offset:38912
	ds_read_b128 v[228:231], v182 offset:39936
	global_load_lds_dwordx4 v144, s[16:17]
	v_lshl_add_u64 v[238:239], s[16:17], 0, v[148:149]
	s_mov_b32 m0, s40
	s_nop 0
	global_load_lds_dwordx4 v[238:239], off
	s_waitcnt vmcnt(8)
	s_waitcnt lgkmcnt(0)
	s_barrier
	s_setprio 1
	s_waitcnt lgkmcnt(0)
	v_mfma_f32_16x16x32_bf16 v[124:127], v[128:131], v[200:203], v[124:127]
	v_mfma_f32_16x16x32_bf16 v[120:123], v[136:139], v[200:203], v[120:123]
	v_mfma_f32_16x16x32_bf16 v[116:119], v[128:131], v[208:211], v[116:119]
	v_mfma_f32_16x16x32_bf16 v[104:107], v[136:139], v[208:211], v[104:107]
	v_mfma_f32_16x16x32_bf16 v[100:103], v[128:131], v[216:219], v[100:103]
	v_mfma_f32_16x16x32_bf16 v[88:91], v[136:139], v[216:219], v[88:91]
	v_mfma_f32_16x16x32_bf16 v[84:87], v[128:131], v[224:227], v[84:87]
	v_mfma_f32_16x16x32_bf16 v[72:75], v[136:139], v[224:227], v[72:75]
	v_mfma_f32_16x16x32_bf16 v[124:127], v[132:135], v[204:207], v[124:127]
	v_mfma_f32_16x16x32_bf16 v[120:123], v[140:143], v[204:207], v[120:123]
	v_mfma_f32_16x16x32_bf16 v[116:119], v[132:135], v[212:215], v[116:119]
	v_mfma_f32_16x16x32_bf16 v[104:107], v[140:143], v[212:215], v[104:107]
	v_mfma_f32_16x16x32_bf16 v[100:103], v[132:135], v[220:223], v[100:103]
	v_mfma_f32_16x16x32_bf16 v[88:91], v[140:143], v[220:223], v[88:91]
	v_mfma_f32_16x16x32_bf16 v[84:87], v[132:135], v[228:231], v[84:87]
	v_mfma_f32_16x16x32_bf16 v[72:75], v[140:143], v[228:231], v[72:75]
	s_setprio 0
	s_setprio 1
	v_mfma_f32_16x16x32_bf16 v[112:115], v[184:187], v[200:203], v[112:115]
	v_mfma_f32_16x16x32_bf16 v[108:111], v[192:195], v[200:203], v[108:111]
	v_mfma_f32_16x16x32_bf16 v[96:99], v[184:187], v[208:211], v[96:99]
	v_mfma_f32_16x16x32_bf16 v[92:95], v[192:195], v[208:211], v[92:95]
	v_mfma_f32_16x16x32_bf16 v[80:83], v[184:187], v[216:219], v[80:83]
	v_mfma_f32_16x16x32_bf16 v[76:79], v[192:195], v[216:219], v[76:79]
	v_mfma_f32_16x16x32_bf16 v[68:71], v[184:187], v[224:227], v[68:71]
	v_mfma_f32_16x16x32_bf16 v[64:67], v[192:195], v[224:227], v[64:67]
	v_mfma_f32_16x16x32_bf16 v[112:115], v[188:191], v[204:207], v[112:115]
	v_mfma_f32_16x16x32_bf16 v[108:111], v[196:199], v[204:207], v[108:111]
	v_mfma_f32_16x16x32_bf16 v[96:99], v[188:191], v[212:215], v[96:99]
	v_mfma_f32_16x16x32_bf16 v[92:95], v[196:199], v[212:215], v[92:95]
	v_mfma_f32_16x16x32_bf16 v[80:83], v[188:191], v[220:223], v[80:83]
	v_mfma_f32_16x16x32_bf16 v[76:79], v[196:199], v[220:223], v[76:79]
	v_mfma_f32_16x16x32_bf16 v[68:71], v[188:191], v[228:231], v[68:71]
	v_mfma_f32_16x16x32_bf16 v[64:67], v[196:199], v[228:231], v[64:67]
	s_setprio 0
	s_barrier
; #define PG8_STAGE(bufoff, gbase, voff) do { _Pragma("unroll") for (int _i = 0; _i < 2; ++_i) \
;         __builtin_amdgcn_global_load_lds((const unsigned*)((const char*)(gbase) + (voff)[_i]), (PG8_LAS unsigned*)(lds + (bufoff) + ldsw + _i * 8192), 16, 0, 0); } while (0)
; #define PG8_LDA(dst, b, h) do { _Pragma("unroll") for (int m = 0; m < 4; ++m) _Pragma("unroll") for (int k = 0; k < 2; ++k) dst[m][k] = *(const PG8_LAS bf16x8*)(lds + PG8_SA(b, h) + aoff + m * 2048 + k * 1024); } while (0)
; #define PG8_MMA(ai, bj, At, Bt) do { __builtin_amdgcn_s_setprio(1); _Pragma("unroll") for (int m = 0; m < 4; ++m) _Pragma("unroll") for (int n = 0; n < 2; ++n) _Pragma("unroll") for (int k = 0; k < 2; ++k) \
;         acc[ai][bj][m][n] = __builtin_amdgcn_mfma_f32_16x16x32_bf16(Bt[n][k], At[m][k], acc[ai][bj][m][n], 0, 0, 0); __builtin_amdgcn_s_setprio(0); } while (0)
; #define PG8_WAIT_V(n) asm volatile("s_waitcnt vmcnt(" #n ")" ::: "memory")
; #define PG8_WAIT_L(n) asm volatile("s_waitcnt lgkmcnt(" #n ")" ::: "memory")
; #define PG8_BAR __builtin_amdgcn_s_barrier()
; #define PG8_SCHED __builtin_amdgcn_sched_barrier(0)
; template <class Epi, class Sched, bool ALIGN_EPI = false, bool SP2 = false>
; __device__ __forceinline__ void gemm_phase(PG8_LAS unsigned char* lds, const Gemm g, const Sched& S, const Epi& E, const int tid) {
;     ...
;         for (int t = 0; t < nt; t += 2) {
;             const bool last = (t == nt - 2);
;             const char* a1 = cA + (size_t)(t + 1) * kstep;
;             const char* a2 = last ? nA : cA + (size_t)(t + 2) * kstep; const char* b2 = last ? nB : cB + (size_t)(t + 2) * kstep;
;     ...
;             PG8_LDA(At, 1, 1); PG8_STAGE(PG8_SB(1, 0), b3, voffB); PG8_STAGE(PG8_SB(1, 1), b3 + hstep, voffB); PG8_STAGE(PG8_SA(1, 0), a3, voffA);
;             PG8_WAIT_V(8); PG8_WAIT_L(0); PG8_BAR; PG8_MMA(1, 0, At, B0); PG8_MMA(1, 1, At, B1); PG8_BAR; PG8_SCHED;
	s_add_i32 s16, s57, s36
	v_lshl_add_u64 v[176:177], v[176:177], 0, s[8:9]
	s_mov_b32 m0, s16
	ds_read_b128 v[200:203], v182 offset:49152
	ds_read_b128 v[204:207], v182 offset:50176
	ds_read_b128 v[208:211], v182 offset:51200
	ds_read_b128 v[212:215], v182 offset:52224
	ds_read_b128 v[216:219], v182 offset:53248
	ds_read_b128 v[220:223], v182 offset:54272
	ds_read_b128 v[224:227], v182 offset:55296
	ds_read_b128 v[228:231], v182 offset:56320
	global_load_lds_dwordx4 v[176:177], off
	s_add_i32 m0, s16, 0x2000
	s_add_u32 s16, s20, 0xb0080
	v_lshl_add_u64 v[176:177], v[232:233], 0, s[8:9]
	s_addc_u32 s17, s21, 0
	s_add_i32 s20, s58, s36
	global_load_lds_dwordx4 v[176:177], off
	s_mov_b32 m0, s20
	s_nop 0
	global_load_lds_dwordx4 v146, s[16:17]
	s_add_i32 m0, s20, 0x2000
	s_nop 0
	global_load_lds_dwordx4 v150, s[16:17]
	v_lshl_add_u64 v[176:177], v[234:235], 0, s[8:9]
	s_mov_b32 m0, s48
	s_nop 0
	global_load_lds_dwordx4 v[176:177], off
	v_lshl_add_u64 v[176:177], v[236:237], 0, s[8:9]
	s_mov_b32 m0, s49
	s_nop 0
	global_load_lds_dwordx4 v[176:177], off
	s_waitcnt vmcnt(8)
	s_waitcnt lgkmcnt(0)
	s_barrier
	s_setprio 1
	s_waitcnt lgkmcnt(0)
	v_mfma_f32_16x16x32_bf16 v[60:63], v[128:131], v[200:203], v[60:63]
	v_mfma_f32_16x16x32_bf16 v[56:59], v[136:139], v[200:203], v[56:59]
	v_mfma_f32_16x16x32_bf16 v[52:55], v[128:131], v[208:211], v[52:55]
	v_mfma_f32_16x16x32_bf16 v[40:43], v[136:139], v[208:211], v[40:43]
	v_mfma_f32_16x16x32_bf16 v[36:39], v[128:131], v[216:219], v[36:39]
	v_mfma_f32_16x16x32_bf16 v[24:27], v[136:139], v[216:219], v[24:27]
	v_mfma_f32_16x16x32_bf16 v[20:23], v[128:131], v[224:227], v[20:23]
	v_mfma_f32_16x16x32_bf16 v[8:11], v[136:139], v[224:227], v[8:11]
	v_mfma_f32_16x16x32_bf16 v[60:63], v[132:135], v[204:207], v[60:63]
	v_mfma_f32_16x16x32_bf16 v[56:59], v[140:143], v[204:207], v[56:59]
	v_mfma_f32_16x16x32_bf16 v[52:55], v[132:135], v[212:215], v[52:55]
	v_mfma_f32_16x16x32_bf16 v[40:43], v[140:143], v[212:215], v[40:43]
	v_mfma_f32_16x16x32_bf16 v[36:39], v[132:135], v[220:223], v[36:39]
	v_mfma_f32_16x16x32_bf16 v[24:27], v[140:143], v[220:223], v[24:27]
	v_mfma_f32_16x16x32_bf16 v[20:23], v[132:135], v[228:231], v[20:23]
	v_mfma_f32_16x16x32_bf16 v[8:11], v[140:143], v[228:231], v[8:11]
	s_setprio 0
	s_setprio 1
	v_mfma_f32_16x16x32_bf16 v[48:51], v[184:187], v[200:203], v[48:51]
	v_mfma_f32_16x16x32_bf16 v[44:47], v[192:195], v[200:203], v[44:47]
	v_mfma_f32_16x16x32_bf16 v[32:35], v[184:187], v[208:211], v[32:35]
	v_mfma_f32_16x16x32_bf16 v[28:31], v[192:195], v[208:211], v[28:31]
	v_mfma_f32_16x16x32_bf16 v[16:19], v[184:187], v[216:219], v[16:19]
	v_mfma_f32_16x16x32_bf16 v[12:15], v[192:195], v[216:219], v[12:15]
	v_mfma_f32_16x16x32_bf16 v[4:7], v[184:187], v[224:227], v[4:7]
	v_mfma_f32_16x16x32_bf16 v[0:3], v[192:195], v[224:227], v[0:3]
	v_mfma_f32_16x16x32_bf16 v[48:51], v[188:191], v[204:207], v[48:51]
	v_mfma_f32_16x16x32_bf16 v[44:47], v[196:199], v[204:207], v[44:47]
	v_mfma_f32_16x16x32_bf16 v[32:35], v[188:191], v[212:215], v[32:35]
	v_mfma_f32_16x16x32_bf16 v[28:31], v[196:199], v[212:215], v[28:31]
	v_mfma_f32_16x16x32_bf16 v[16:19], v[188:191], v[220:223], v[16:19]
	v_mfma_f32_16x16x32_bf16 v[12:15], v[196:199], v[220:223], v[12:15]
	v_mfma_f32_16x16x32_bf16 v[4:7], v[188:191], v[228:231], v[4:7]
	v_mfma_f32_16x16x32_bf16 v[0:3], v[196:199], v[228:231], v[0:3]
	s_setprio 0
	s_barrier
	s_add_i32 s56, s56, 2
	s_add_u32 s25, s25, 0x100
	s_addc_u32 s33, s33, 0
	s_cmp_gt_u32 s56, 41
	s_mov_b64 s[16:17], s[18:19]
	s_cbranch_scc0 .LBB0_1783
	s_and_b64 vcc, exec, s[10:11]
	s_cbranch_vccz .LBB0_1786
	s_barrier
